# noprio + 62 m0 s_nop removed in GEMM load segments by swapping with the address v_lshl_add_u64 (loader issue slots)
# speedup vs baseline: 1.0136x; 1.0074x over previous
; #define PG8_STAGE(bufoff, gbase, voff) do { _Pragma("unroll") for (int _i = 0; _i < 2; ++_i) \
;         __builtin_amdgcn_global_load_lds((const unsigned*)((const char*)(gbase) + (voff)[_i]), (LAS unsigned*)(lds + (bufoff) + ldsw + _i * 8192), 16, 0, 0); } while (0)
; #define PG8_LDA(dst, b, h) do { _Pragma("unroll") for (int m = 0; m < 4; ++m) _Pragma("unroll") for (int k = 0; k < 2; ++k) dst[m][k] = *(const LAS bf16x8*)(lds + PG8_SA(b, h) + aoff + m * 2048 + k * 1024); } while (0)
; #define PG8_LDB(dst, b, h) do { _Pragma("unroll") for (int n = 0; n < 2; ++n) _Pragma("unroll") for (int k = 0; k < 2; ++k) dst[n][k] = *(const LAS bf16x8*)(lds + PG8_SB(b, h) + boff + n * 2048 + k * 1024); } while (0)
; #define PG8_MMA(ai, bj, At, Bt) do { __builtin_amdgcn_s_setprio(1); _Pragma("unroll") for (int m = 0; m < 4; ++m) _Pragma("unroll") for (int n = 0; n < 2; ++n) _Pragma("unroll") for (int k = 0; k < 2; ++k) \
;         acc[ai][bj][m][n] = __builtin_amdgcn_mfma_f32_16x16x32_bf16(Bt[n][k], At[m][k], acc[ai][bj][m][n], 0, 0, 0); __builtin_amdgcn_s_setprio(0); } while (0)
; #define PG8_WAIT_V(n) asm volatile("s_waitcnt vmcnt(" #n ")" ::: "memory")
; #define PG8_WAIT_L(n) asm volatile("s_waitcnt lgkmcnt(" #n ")" ::: "memory")
; #define PG8_BAR __builtin_amdgcn_s_barrier()
; #define PG8_SCHED __builtin_amdgcn_sched_barrier(0)
; template <class Epi, class Sched, bool ALIGN_EPI = true>
; __device__ __forceinline__ void gemm_phase(LAS unsigned char* lds, const Gemm g, const Sched& S, const Epi& E) {
;     ...
;         for (int t = 0; t < nt; t += 2) {
;             const bool last = (t == nt - 2);
;             const char* a1 = cA + (size_t)(t + 1) * kstep;
;             const char* a2 = last ? nA : cA + (size_t)(t + 2) * kstep; const char* b2 = last ? nB : cB + (size_t)(t + 2) * kstep;
;             const char* a3 = a2 + kstep; const char* b3 = b2 + kstep;
;             PG8_LDB(B0, 0, 0); PG8_LDB(B1, 0, 1); PG8_SCHED; PG8_LDA(At, 0, 0); PG8_STAGE(PG8_SA(1, 1), a1 + hstep, voffA);
;             PG8_WAIT_V(8); PG8_WAIT_L(0); PG8_BAR; PG8_MMA(0, 0, At, B0); PG8_MMA(0, 1, At, B1); PG8_BAR; PG8_SCHED;
;             PG8_LDA(At, 0, 1); PG8_STAGE(PG8_SB(0, 0), b2, voffB); PG8_STAGE(PG8_SB(0, 1), b2 + hstep, voffB); PG8_STAGE(PG8_SA(0, 0), a2, voffA);
;             PG8_WAIT_V(8); PG8_WAIT_L(0); PG8_BAR; PG8_MMA(1, 0, At, B0); PG8_MMA(1, 1, At, B1); PG8_BAR; PG8_SCHED;
.LBB0_195:
	v_add_u32_e32 v136, s78, v169
	ds_read_b128 v[172:175], v136
	ds_read_b128 v[180:183], v136 offset:1024
	ds_read_b128 v[184:187], v136 offset:2048
	ds_read_b128 v[188:191], v136 offset:3072
	v_add_u32_e32 v136, s79, v169
	ds_read_b128 v[192:195], v136
	ds_read_b128 v[196:199], v136 offset:1024
	ds_read_b128 v[204:207], v136 offset:2048
	ds_read_b128 v[208:211], v136 offset:3072
	s_add_u32 s36, s34, 0xfff80080
	s_addc_u32 s37, s35, -1
	s_cmp_eq_u32 s89, 28
	s_cselect_b32 s39, s84, s37
	s_cselect_b32 s38, s85, s36
	s_cselect_b32 s37, s9, s88
	s_cselect_b32 s36, s86, s87
	v_lshl_add_u64 v[164:165], s[34:35], 0, v[160:161]
	s_add_i32 m0, s44, 0xc000
	ds_read_b128 v[212:215], v171
	ds_read_b128 v[216:219], v171 offset:1024
	ds_read_b128 v[220:223], v171 offset:2048
	ds_read_b128 v[224:227], v171 offset:3072
	ds_read_b128 v[228:231], v171 offset:4096
	ds_read_b128 v[232:235], v171 offset:5120
	ds_read_b128 v[236:239], v171 offset:6144
	ds_read_b128 v[240:243], v171 offset:7168
	global_load_lds_dwordx4 v[164:165], off
	s_add_i32 m0, s44, 0xe000
	v_lshl_add_u64 v[164:165], s[34:35], 0, v[162:163]
	global_load_lds_dwordx4 v[164:165], off
	s_waitcnt vmcnt(8)
	s_waitcnt lgkmcnt(0)
	s_barrier
	s_waitcnt lgkmcnt(0)
	v_mfma_f32_16x16x32_bf16 v[124:127], v[172:175], v[212:215], v[124:127]
	v_mfma_f32_16x16x32_bf16 v[120:123], v[184:187], v[212:215], v[120:123]
	v_mfma_f32_16x16x32_bf16 v[108:111], v[172:175], v[220:223], v[108:111]
	v_mfma_f32_16x16x32_bf16 v[104:107], v[184:187], v[220:223], v[104:107]
	v_mfma_f32_16x16x32_bf16 v[92:95], v[172:175], v[228:231], v[92:95]
	v_mfma_f32_16x16x32_bf16 v[88:91], v[184:187], v[228:231], v[88:91]
	v_mfma_f32_16x16x32_bf16 v[76:79], v[172:175], v[236:239], v[76:79]
	v_mfma_f32_16x16x32_bf16 v[72:75], v[184:187], v[236:239], v[72:75]
	v_mfma_f32_16x16x32_bf16 v[124:127], v[180:183], v[216:219], v[124:127]
	v_mfma_f32_16x16x32_bf16 v[120:123], v[188:191], v[216:219], v[120:123]
	v_mfma_f32_16x16x32_bf16 v[108:111], v[180:183], v[224:227], v[108:111]
	v_mfma_f32_16x16x32_bf16 v[104:107], v[188:191], v[224:227], v[104:107]
	v_mfma_f32_16x16x32_bf16 v[92:95], v[180:183], v[232:235], v[92:95]
	v_mfma_f32_16x16x32_bf16 v[88:91], v[188:191], v[232:235], v[88:91]
	v_mfma_f32_16x16x32_bf16 v[76:79], v[180:183], v[240:243], v[76:79]
	v_mfma_f32_16x16x32_bf16 v[72:75], v[188:191], v[240:243], v[72:75]
	v_mfma_f32_16x16x32_bf16 v[116:119], v[192:195], v[212:215], v[116:119]
	v_mfma_f32_16x16x32_bf16 v[112:115], v[204:207], v[212:215], v[112:115]
	v_mfma_f32_16x16x32_bf16 v[100:103], v[192:195], v[220:223], v[100:103]
	v_mfma_f32_16x16x32_bf16 v[96:99], v[204:207], v[220:223], v[96:99]
	v_mfma_f32_16x16x32_bf16 v[84:87], v[192:195], v[228:231], v[84:87]
	v_mfma_f32_16x16x32_bf16 v[80:83], v[204:207], v[228:231], v[80:83]
	v_mfma_f32_16x16x32_bf16 v[68:71], v[192:195], v[236:239], v[68:71]
	v_mfma_f32_16x16x32_bf16 v[64:67], v[204:207], v[236:239], v[64:67]
	v_mfma_f32_16x16x32_bf16 v[116:119], v[196:199], v[216:219], v[116:119]
	v_mfma_f32_16x16x32_bf16 v[112:115], v[208:211], v[216:219], v[112:115]
	v_mfma_f32_16x16x32_bf16 v[100:103], v[196:199], v[224:227], v[100:103]
	v_mfma_f32_16x16x32_bf16 v[96:99], v[208:211], v[224:227], v[96:99]
	v_mfma_f32_16x16x32_bf16 v[84:87], v[196:199], v[232:235], v[84:87]
	v_mfma_f32_16x16x32_bf16 v[80:83], v[208:211], v[232:235], v[80:83]
	v_mfma_f32_16x16x32_bf16 v[68:71], v[196:199], v[240:243], v[68:71]
	v_mfma_f32_16x16x32_bf16 v[64:67], v[208:211], v[240:243], v[64:67]
	s_barrier
	s_add_i32 s46, s78, s42
	v_lshl_add_u64 v[164:165], s[36:37], 0, v[130:131]
	s_mov_b32 m0, s46
	ds_read_b128 v[212:215], v171 offset:16384
	ds_read_b128 v[216:219], v171 offset:17408
	ds_read_b128 v[220:223], v171 offset:18432
	ds_read_b128 v[224:227], v171 offset:19456
	ds_read_b128 v[228:231], v171 offset:20480
	ds_read_b128 v[232:235], v171 offset:21504
	ds_read_b128 v[236:239], v171 offset:22528
	ds_read_b128 v[240:243], v171 offset:23552
	global_load_lds_dwordx4 v[164:165], off
	s_add_i32 m0, s46, 0x2000
	s_add_u32 s90, s36, 0x80000
	v_lshl_add_u64 v[176:177], s[36:37], 0, v[134:135]
	s_addc_u32 s91, s37, 0
	s_add_i32 s46, s79, s42
	global_load_lds_dwordx4 v[176:177], off
	v_lshl_add_u64 v[200:201], s[90:91], 0, v[130:131]
	s_mov_b32 m0, s46
	v_lshl_add_u64 v[244:245], s[38:39], 0, v[132:133]
	global_load_lds_dwordx4 v[200:201], off
	s_add_i32 m0, s46, 0x2000
	v_lshl_add_u64 v[200:201], s[90:91], 0, v[134:135]
	global_load_lds_dwordx4 v[200:201], off
	s_mov_b32 m0, s44
	v_lshl_add_u64 v[200:201], s[38:39], 0, v[128:129]
	global_load_lds_dwordx4 v[200:201], off
	s_mov_b32 m0, s50
	s_nop 0
	global_load_lds_dwordx4 v[244:245], off
	s_waitcnt vmcnt(8)
	s_waitcnt lgkmcnt(0)
	s_barrier
; #define PG8_STAGE(bufoff, gbase, voff) do { _Pragma("unroll") for (int _i = 0; _i < 2; ++_i) \
;         __builtin_amdgcn_global_load_lds((const unsigned*)((const char*)(gbase) + (voff)[_i]), (LAS unsigned*)(lds + (bufoff) + ldsw + _i * 8192), 16, 0, 0); } while (0)
; #define PG8_LDA(dst, b, h) do { _Pragma("unroll") for (int m = 0; m < 4; ++m) _Pragma("unroll") for (int k = 0; k < 2; ++k) dst[m][k] = *(const LAS bf16x8*)(lds + PG8_SA(b, h) + aoff + m * 2048 + k * 1024); } while (0)
; #define PG8_LDB(dst, b, h) do { _Pragma("unroll") for (int n = 0; n < 2; ++n) _Pragma("unroll") for (int k = 0; k < 2; ++k) dst[n][k] = *(const LAS bf16x8*)(lds + PG8_SB(b, h) + boff + n * 2048 + k * 1024); } while (0)
; #define PG8_MMA(ai, bj, At, Bt) do { __builtin_amdgcn_s_setprio(1); _Pragma("unroll") for (int m = 0; m < 4; ++m) _Pragma("unroll") for (int n = 0; n < 2; ++n) _Pragma("unroll") for (int k = 0; k < 2; ++k) \
;         acc[ai][bj][m][n] = __builtin_amdgcn_mfma_f32_16x16x32_bf16(Bt[n][k], At[m][k], acc[ai][bj][m][n], 0, 0, 0); __builtin_amdgcn_s_setprio(0); } while (0)
; #define PG8_WAIT_V(n) asm volatile("s_waitcnt vmcnt(" #n ")" ::: "memory")
; #define PG8_WAIT_L(n) asm volatile("s_waitcnt lgkmcnt(" #n ")" ::: "memory")
; #define PG8_BAR __builtin_amdgcn_s_barrier()
; #define PG8_SCHED __builtin_amdgcn_sched_barrier(0)
; template <class Epi, class Sched, bool ALIGN_EPI = true>
; __device__ __forceinline__ void gemm_phase(LAS unsigned char* lds, const Gemm g, const Sched& S, const Epi& E) {
;     ...
;             PG8_WAIT_V(8); PG8_WAIT_L(0); PG8_BAR; PG8_MMA(1, 0, At, B0); PG8_MMA(1, 1, At, B1); PG8_BAR; PG8_SCHED;
;             PG8_LDB(B0, 1, 0); PG8_LDB(B1, 1, 1); PG8_SCHED; PG8_LDA(At, 1, 0); PG8_STAGE(PG8_SA(0, 1), a2 + hstep, voffA);
;             PG8_WAIT_V(8); PG8_WAIT_L(0); PG8_BAR; PG8_MMA(0, 0, At, B0); PG8_MMA(0, 1, At, B1); PG8_BAR; PG8_SCHED;
	s_waitcnt lgkmcnt(0)
	v_mfma_f32_16x16x32_bf16 v[60:63], v[172:175], v[212:215], v[60:63]
	v_mfma_f32_16x16x32_bf16 v[56:59], v[184:187], v[212:215], v[56:59]
	v_mfma_f32_16x16x32_bf16 v[44:47], v[172:175], v[220:223], v[44:47]
	v_mfma_f32_16x16x32_bf16 v[40:43], v[184:187], v[220:223], v[40:43]
	v_mfma_f32_16x16x32_bf16 v[28:31], v[172:175], v[228:231], v[28:31]
	v_mfma_f32_16x16x32_bf16 v[24:27], v[184:187], v[228:231], v[24:27]
	v_mfma_f32_16x16x32_bf16 v[12:15], v[172:175], v[236:239], v[12:15]
	v_mfma_f32_16x16x32_bf16 v[8:11], v[184:187], v[236:239], v[8:11]
	v_mfma_f32_16x16x32_bf16 v[60:63], v[180:183], v[216:219], v[60:63]
	v_mfma_f32_16x16x32_bf16 v[56:59], v[188:191], v[216:219], v[56:59]
	v_mfma_f32_16x16x32_bf16 v[44:47], v[180:183], v[224:227], v[44:47]
	v_mfma_f32_16x16x32_bf16 v[40:43], v[188:191], v[224:227], v[40:43]
	v_mfma_f32_16x16x32_bf16 v[28:31], v[180:183], v[232:235], v[28:31]
	v_mfma_f32_16x16x32_bf16 v[24:27], v[188:191], v[232:235], v[24:27]
	v_mfma_f32_16x16x32_bf16 v[12:15], v[180:183], v[240:243], v[12:15]
	v_mfma_f32_16x16x32_bf16 v[8:11], v[188:191], v[240:243], v[8:11]
	v_mfma_f32_16x16x32_bf16 v[52:55], v[192:195], v[212:215], v[52:55]
	v_mfma_f32_16x16x32_bf16 v[48:51], v[204:207], v[212:215], v[48:51]
	v_mfma_f32_16x16x32_bf16 v[36:39], v[192:195], v[220:223], v[36:39]
	v_mfma_f32_16x16x32_bf16 v[32:35], v[204:207], v[220:223], v[32:35]
	v_mfma_f32_16x16x32_bf16 v[20:23], v[192:195], v[228:231], v[20:23]
	v_mfma_f32_16x16x32_bf16 v[16:19], v[204:207], v[228:231], v[16:19]
	v_mfma_f32_16x16x32_bf16 v[4:7], v[192:195], v[236:239], v[4:7]
	v_mfma_f32_16x16x32_bf16 v[0:3], v[204:207], v[236:239], v[0:3]
	v_mfma_f32_16x16x32_bf16 v[52:55], v[196:199], v[216:219], v[52:55]
	v_mfma_f32_16x16x32_bf16 v[48:51], v[208:211], v[216:219], v[48:51]
	v_mfma_f32_16x16x32_bf16 v[36:39], v[196:199], v[224:227], v[36:39]
	v_mfma_f32_16x16x32_bf16 v[32:35], v[208:211], v[224:227], v[32:35]
	v_mfma_f32_16x16x32_bf16 v[20:23], v[196:199], v[232:235], v[20:23]
	v_mfma_f32_16x16x32_bf16 v[16:19], v[208:211], v[232:235], v[16:19]
	v_mfma_f32_16x16x32_bf16 v[4:7], v[196:199], v[240:243], v[4:7]
	v_mfma_f32_16x16x32_bf16 v[0:3], v[208:211], v[240:243], v[0:3]
	s_barrier
	s_add_i32 s46, 0, 0x18000
	v_add_u32_e32 v136, s46, v169
	s_add_i32 s47, 0, 0x1c000
	ds_read_b128 v[172:175], v136
	ds_read_b128 v[180:183], v136 offset:1024
	ds_read_b128 v[184:187], v136 offset:2048
	ds_read_b128 v[188:191], v136 offset:3072
	v_add_u32_e32 v136, s47, v169
	ds_read_b128 v[192:195], v136
	ds_read_b128 v[196:199], v136 offset:1024
	ds_read_b128 v[204:207], v136 offset:2048
	ds_read_b128 v[208:211], v136 offset:3072
	s_add_u32 s38, s38, 0x80000
	s_addc_u32 s39, s39, 0
	s_mov_b32 m0, s52
	v_lshl_add_u64 v[246:247], s[38:39], 0, v[128:129]
	ds_read_b128 v[212:215], v171 offset:32768
	ds_read_b128 v[216:219], v171 offset:33792
	ds_read_b128 v[220:223], v171 offset:34816
	ds_read_b128 v[224:227], v171 offset:35840
	ds_read_b128 v[228:231], v171 offset:36864
	ds_read_b128 v[232:235], v171 offset:37888
	ds_read_b128 v[236:239], v171 offset:38912
	ds_read_b128 v[240:243], v171 offset:39936
	global_load_lds_dwordx4 v[246:247], off
	s_mov_b32 m0, s53
	v_lshl_add_u64 v[246:247], s[38:39], 0, v[132:133]
	global_load_lds_dwordx4 v[246:247], off
	s_waitcnt vmcnt(8)
	s_waitcnt lgkmcnt(0)
	s_barrier
	s_waitcnt lgkmcnt(0)
	v_mfma_f32_16x16x32_bf16 v[124:127], v[172:175], v[212:215], v[124:127]
	v_mfma_f32_16x16x32_bf16 v[120:123], v[184:187], v[212:215], v[120:123]
	v_mfma_f32_16x16x32_bf16 v[108:111], v[172:175], v[220:223], v[108:111]
	v_mfma_f32_16x16x32_bf16 v[104:107], v[184:187], v[220:223], v[104:107]
	v_mfma_f32_16x16x32_bf16 v[92:95], v[172:175], v[228:231], v[92:95]
	v_mfma_f32_16x16x32_bf16 v[88:91], v[184:187], v[228:231], v[88:91]
	v_mfma_f32_16x16x32_bf16 v[76:79], v[172:175], v[236:239], v[76:79]
	v_mfma_f32_16x16x32_bf16 v[72:75], v[184:187], v[236:239], v[72:75]
	v_mfma_f32_16x16x32_bf16 v[124:127], v[180:183], v[216:219], v[124:127]
	v_mfma_f32_16x16x32_bf16 v[120:123], v[188:191], v[216:219], v[120:123]
	v_mfma_f32_16x16x32_bf16 v[108:111], v[180:183], v[224:227], v[108:111]
	v_mfma_f32_16x16x32_bf16 v[104:107], v[188:191], v[224:227], v[104:107]
	v_mfma_f32_16x16x32_bf16 v[92:95], v[180:183], v[232:235], v[92:95]
	v_mfma_f32_16x16x32_bf16 v[88:91], v[188:191], v[232:235], v[88:91]
	v_mfma_f32_16x16x32_bf16 v[76:79], v[180:183], v[240:243], v[76:79]
	v_mfma_f32_16x16x32_bf16 v[72:75], v[188:191], v[240:243], v[72:75]
	v_mfma_f32_16x16x32_bf16 v[116:119], v[192:195], v[212:215], v[116:119]
	v_mfma_f32_16x16x32_bf16 v[112:115], v[204:207], v[212:215], v[112:115]
	v_mfma_f32_16x16x32_bf16 v[100:103], v[192:195], v[220:223], v[100:103]
	v_mfma_f32_16x16x32_bf16 v[96:99], v[204:207], v[220:223], v[96:99]
	v_mfma_f32_16x16x32_bf16 v[84:87], v[192:195], v[228:231], v[84:87]
	v_mfma_f32_16x16x32_bf16 v[80:83], v[204:207], v[228:231], v[80:83]
	v_mfma_f32_16x16x32_bf16 v[68:71], v[192:195], v[236:239], v[68:71]
	v_mfma_f32_16x16x32_bf16 v[64:67], v[204:207], v[236:239], v[64:67]
	v_mfma_f32_16x16x32_bf16 v[116:119], v[196:199], v[216:219], v[116:119]
	v_mfma_f32_16x16x32_bf16 v[112:115], v[208:211], v[216:219], v[112:115]
	v_mfma_f32_16x16x32_bf16 v[100:103], v[196:199], v[224:227], v[100:103]
	v_mfma_f32_16x16x32_bf16 v[96:99], v[208:211], v[224:227], v[96:99]
	v_mfma_f32_16x16x32_bf16 v[84:87], v[196:199], v[232:235], v[84:87]
	v_mfma_f32_16x16x32_bf16 v[80:83], v[208:211], v[232:235], v[80:83]
	v_mfma_f32_16x16x32_bf16 v[68:71], v[196:199], v[240:243], v[68:71]
	v_mfma_f32_16x16x32_bf16 v[64:67], v[208:211], v[240:243], v[64:67]
	s_barrier
; #define PG8_STAGE(bufoff, gbase, voff) do { _Pragma("unroll") for (int _i = 0; _i < 2; ++_i) \
;         __builtin_amdgcn_global_load_lds((const unsigned*)((const char*)(gbase) + (voff)[_i]), (LAS unsigned*)(lds + (bufoff) + ldsw + _i * 8192), 16, 0, 0); } while (0)
; #define PG8_LDA(dst, b, h) do { _Pragma("unroll") for (int m = 0; m < 4; ++m) _Pragma("unroll") for (int k = 0; k < 2; ++k) dst[m][k] = *(const LAS bf16x8*)(lds + PG8_SA(b, h) + aoff + m * 2048 + k * 1024); } while (0)
; #define PG8_MMA(ai, bj, At, Bt) do { __builtin_amdgcn_s_setprio(1); _Pragma("unroll") for (int m = 0; m < 4; ++m) _Pragma("unroll") for (int n = 0; n < 2; ++n) _Pragma("unroll") for (int k = 0; k < 2; ++k) \
;         acc[ai][bj][m][n] = __builtin_amdgcn_mfma_f32_16x16x32_bf16(Bt[n][k], At[m][k], acc[ai][bj][m][n], 0, 0, 0); __builtin_amdgcn_s_setprio(0); } while (0)
; #define PG8_WAIT_V(n) asm volatile("s_waitcnt vmcnt(" #n ")" ::: "memory")
; #define PG8_WAIT_L(n) asm volatile("s_waitcnt lgkmcnt(" #n ")" ::: "memory")
; #define PG8_BAR __builtin_amdgcn_s_barrier()
; #define PG8_SCHED __builtin_amdgcn_sched_barrier(0)
; template <class Epi, class Sched, bool ALIGN_EPI = true>
; __device__ __forceinline__ void gemm_phase(LAS unsigned char* lds, const Gemm g, const Sched& S, const Epi& E) {
;     ...
;             PG8_LDA(At, 1, 1); PG8_STAGE(PG8_SB(1, 0), b3, voffB); PG8_STAGE(PG8_SB(1, 1), b3 + hstep, voffB); PG8_STAGE(PG8_SA(1, 0), a3, voffA);
;             PG8_WAIT_V(8); PG8_WAIT_L(0); PG8_BAR; PG8_MMA(1, 0, At, B0); PG8_MMA(1, 1, At, B1); PG8_BAR; PG8_SCHED;
;         }
;         if constexpr (ALIGN_EPI) { if (wr == 0) PG8_BAR; }
;     __device__ __forceinline__ void operator()(const Acc& acc, const Unit& u, int wr, int wc, int fr, int fq) const {
;         switch (u.pm >> 2) {
;             case 0: body<0>(acc, u, wr, wc, fr, fq); break;
	s_add_i32 s38, s46, s42
	v_lshl_add_u64 v[164:165], v[164:165], 0, s[22:23]
	s_mov_b32 m0, s38
	ds_read_b128 v[212:215], v171 offset:49152
	ds_read_b128 v[216:219], v171 offset:50176
	ds_read_b128 v[220:223], v171 offset:51200
	ds_read_b128 v[224:227], v171 offset:52224
	ds_read_b128 v[228:231], v171 offset:53248
	ds_read_b128 v[232:235], v171 offset:54272
	ds_read_b128 v[236:239], v171 offset:55296
	ds_read_b128 v[240:243], v171 offset:56320
	global_load_lds_dwordx4 v[164:165], off
	s_add_i32 m0, s38, 0x2000
	s_add_u32 s36, s36, 0x80080
	v_lshl_add_u64 v[164:165], v[176:177], 0, s[22:23]
	s_addc_u32 s37, s37, 0
	s_add_i32 s38, s47, s42
	global_load_lds_dwordx4 v[164:165], off
	s_mov_b32 m0, s38
	v_lshl_add_u64 v[164:165], s[36:37], 0, v[130:131]
	global_load_lds_dwordx4 v[164:165], off
	s_add_i32 m0, s38, 0x2000
	v_lshl_add_u64 v[164:165], s[36:37], 0, v[134:135]
	global_load_lds_dwordx4 v[164:165], off
	s_mov_b32 m0, s54
	v_lshl_add_u64 v[164:165], v[200:201], 0, s[22:23]
	global_load_lds_dwordx4 v[164:165], off
	s_mov_b32 m0, s55
	v_lshl_add_u64 v[164:165], v[244:245], 0, s[22:23]
	global_load_lds_dwordx4 v[164:165], off
	s_waitcnt vmcnt(8)
	s_waitcnt lgkmcnt(0)
	s_barrier
	s_waitcnt lgkmcnt(0)
	v_mfma_f32_16x16x32_bf16 v[60:63], v[172:175], v[212:215], v[60:63]
	v_mfma_f32_16x16x32_bf16 v[56:59], v[184:187], v[212:215], v[56:59]
	v_mfma_f32_16x16x32_bf16 v[44:47], v[172:175], v[220:223], v[44:47]
	v_mfma_f32_16x16x32_bf16 v[40:43], v[184:187], v[220:223], v[40:43]
	v_mfma_f32_16x16x32_bf16 v[28:31], v[172:175], v[228:231], v[28:31]
	v_mfma_f32_16x16x32_bf16 v[24:27], v[184:187], v[228:231], v[24:27]
	v_mfma_f32_16x16x32_bf16 v[12:15], v[172:175], v[236:239], v[12:15]
	v_mfma_f32_16x16x32_bf16 v[8:11], v[184:187], v[236:239], v[8:11]
	v_mfma_f32_16x16x32_bf16 v[60:63], v[180:183], v[216:219], v[60:63]
	v_mfma_f32_16x16x32_bf16 v[56:59], v[188:191], v[216:219], v[56:59]
	v_mfma_f32_16x16x32_bf16 v[44:47], v[180:183], v[224:227], v[44:47]
	v_mfma_f32_16x16x32_bf16 v[40:43], v[188:191], v[224:227], v[40:43]
	v_mfma_f32_16x16x32_bf16 v[28:31], v[180:183], v[232:235], v[28:31]
	v_mfma_f32_16x16x32_bf16 v[24:27], v[188:191], v[232:235], v[24:27]
	v_mfma_f32_16x16x32_bf16 v[12:15], v[180:183], v[240:243], v[12:15]
	v_mfma_f32_16x16x32_bf16 v[8:11], v[188:191], v[240:243], v[8:11]
	v_mfma_f32_16x16x32_bf16 v[52:55], v[192:195], v[212:215], v[52:55]
	v_mfma_f32_16x16x32_bf16 v[48:51], v[204:207], v[212:215], v[48:51]
	v_mfma_f32_16x16x32_bf16 v[36:39], v[192:195], v[220:223], v[36:39]
	v_mfma_f32_16x16x32_bf16 v[32:35], v[204:207], v[220:223], v[32:35]
	v_mfma_f32_16x16x32_bf16 v[20:23], v[192:195], v[228:231], v[20:23]
	v_mfma_f32_16x16x32_bf16 v[16:19], v[204:207], v[228:231], v[16:19]
	v_mfma_f32_16x16x32_bf16 v[4:7], v[192:195], v[236:239], v[4:7]
	v_mfma_f32_16x16x32_bf16 v[0:3], v[204:207], v[236:239], v[0:3]
	v_mfma_f32_16x16x32_bf16 v[52:55], v[196:199], v[216:219], v[52:55]
	v_mfma_f32_16x16x32_bf16 v[48:51], v[208:211], v[216:219], v[48:51]
	v_mfma_f32_16x16x32_bf16 v[36:39], v[196:199], v[224:227], v[36:39]
	v_mfma_f32_16x16x32_bf16 v[32:35], v[208:211], v[224:227], v[32:35]
	v_mfma_f32_16x16x32_bf16 v[20:23], v[196:199], v[232:235], v[20:23]
	v_mfma_f32_16x16x32_bf16 v[16:19], v[208:211], v[232:235], v[16:19]
	v_mfma_f32_16x16x32_bf16 v[4:7], v[196:199], v[240:243], v[4:7]
	v_mfma_f32_16x16x32_bf16 v[0:3], v[208:211], v[240:243], v[0:3]
	s_barrier
	s_add_i32 s89, s89, 2
	s_add_u32 s34, s34, 0x100
	s_addc_u32 s35, s35, 0
	s_add_u32 s87, s87, 0x100
	s_addc_u32 s88, s88, 0
	s_cmp_gt_u32 s89, 29
	s_cbranch_scc0 .LBB0_195
	s_and_b64 vcc, exec, s[24:25]
	s_cbranch_vccnz .LBB0_202
	s_lshr_b32 s9, s81, 2
	s_cmp_lt_i32 s9, 1
	s_mov_b64 s[34:35], -1
	s_cbranch_scc0 .LBB0_203

; #define PG8_STAGE(bufoff, gbase, voff) do { _Pragma("unroll") for (int _i = 0; _i < 2; ++_i) \
;         __builtin_amdgcn_global_load_lds((const unsigned*)((const char*)(gbase) + (voff)[_i]), (LAS unsigned*)(lds + (bufoff) + ldsw + _i * 8192), 16, 0, 0); } while (0)
; #define PG8_LDA(dst, b, h) do { _Pragma("unroll") for (int m = 0; m < 4; ++m) _Pragma("unroll") for (int k = 0; k < 2; ++k) dst[m][k] = *(const LAS bf16x8*)(lds + PG8_SA(b, h) + aoff + m * 2048 + k * 1024); } while (0)
; #define PG8_LDB(dst, b, h) do { _Pragma("unroll") for (int n = 0; n < 2; ++n) _Pragma("unroll") for (int k = 0; k < 2; ++k) dst[n][k] = *(const LAS bf16x8*)(lds + PG8_SB(b, h) + boff + n * 2048 + k * 1024); } while (0)
; #define PG8_MMA(ai, bj, At, Bt) do { __builtin_amdgcn_s_setprio(1); _Pragma("unroll") for (int m = 0; m < 4; ++m) _Pragma("unroll") for (int n = 0; n < 2; ++n) _Pragma("unroll") for (int k = 0; k < 2; ++k) \
;         acc[ai][bj][m][n] = __builtin_amdgcn_mfma_f32_16x16x32_bf16(Bt[n][k], At[m][k], acc[ai][bj][m][n], 0, 0, 0); __builtin_amdgcn_s_setprio(0); } while (0)
; #define PG8_WAIT_V(n) asm volatile("s_waitcnt vmcnt(" #n ")" ::: "memory")
; #define PG8_WAIT_L(n) asm volatile("s_waitcnt lgkmcnt(" #n ")" ::: "memory")
; #define PG8_BAR __builtin_amdgcn_s_barrier()
; #define PG8_SCHED __builtin_amdgcn_sched_barrier(0)
; template <class Epi, class Sched, bool ALIGN_EPI = true>
; __device__ __forceinline__ void gemm_phase(LAS unsigned char* lds, const Gemm g, const Sched& S, const Epi& E) {
;     ...
;         for (int t = 0; t < nt; t += 2) {
;             const bool last = (t == nt - 2);
;             const char* a1 = cA + (size_t)(t + 1) * kstep;
;             const char* a2 = last ? nA : cA + (size_t)(t + 2) * kstep; const char* b2 = last ? nB : cB + (size_t)(t + 2) * kstep;
;             const char* a3 = a2 + kstep; const char* b3 = b2 + kstep;
;             PG8_LDB(B0, 0, 0); PG8_LDB(B1, 0, 1); PG8_SCHED; PG8_LDA(At, 0, 0); PG8_STAGE(PG8_SA(1, 1), a1 + hstep, voffA);
;             PG8_WAIT_V(8); PG8_WAIT_L(0); PG8_BAR; PG8_MMA(0, 0, At, B0); PG8_MMA(0, 1, At, B1); PG8_BAR; PG8_SCHED;
;             PG8_LDA(At, 0, 1); PG8_STAGE(PG8_SB(0, 0), b2, voffB); PG8_STAGE(PG8_SB(0, 1), b2 + hstep, voffB); PG8_STAGE(PG8_SA(0, 0), a2, voffA);
;             PG8_WAIT_V(8); PG8_WAIT_L(0); PG8_BAR; PG8_MMA(1, 0, At, B0); PG8_MMA(1, 1, At, B1); PG8_BAR; PG8_SCHED;
.LBB0_223:
	ds_read_b128 v[128:131], v203
	s_waitcnt lgkmcnt(0)
	ds_read_b128 v[132:135], v203 offset:1024
	ds_read_b128 v[136:139], v203 offset:2048
	ds_read_b128 v[140:143], v203 offset:3072
	ds_read_b128 v[176:179], v204
	ds_read_b128 v[180:183], v204 offset:1024
	ds_read_b128 v[184:187], v204 offset:2048
	ds_read_b128 v[188:191], v204 offset:3072
	s_add_u32 s46, s76, 0xfff80080
	s_addc_u32 s47, s77, -1
	s_cmp_eq_u32 vcc_hi, 28
	s_cselect_b32 s81, s9, s47
	s_cselect_b32 s80, s30, s46
	s_cselect_b32 s79, s11, vcc_lo
	s_cselect_b32 s78, s96, s97
	v_lshl_add_u64 v[200:201], s[76:77], 0, v[164:165]
	s_add_i32 m0, s55, 0xc000
	ds_read_b128 v[192:195], v205
	ds_read_b128 v[196:199], v205 offset:1024
	ds_read_b128 v[208:211], v205 offset:2048
	ds_read_b128 v[212:215], v205 offset:3072
	ds_read_b128 v[216:219], v205 offset:4096
	ds_read_b128 v[220:223], v205 offset:5120
	ds_read_b128 v[224:227], v205 offset:6144
	ds_read_b128 v[228:231], v205 offset:7168
	global_load_lds_dwordx4 v[200:201], off
	s_add_i32 m0, s55, 0xe000
	v_lshl_add_u64 v[200:201], s[76:77], 0, v[166:167]
	global_load_lds_dwordx4 v[200:201], off
	s_waitcnt vmcnt(8)
	s_waitcnt lgkmcnt(0)
	s_barrier
	s_waitcnt lgkmcnt(0)
	v_mfma_f32_16x16x32_bf16 v[124:127], v[128:131], v[192:195], v[124:127]
	v_mfma_f32_16x16x32_bf16 v[120:123], v[136:139], v[192:195], v[120:123]
	v_mfma_f32_16x16x32_bf16 v[108:111], v[128:131], v[208:211], v[108:111]
	v_mfma_f32_16x16x32_bf16 v[104:107], v[136:139], v[208:211], v[104:107]
	v_mfma_f32_16x16x32_bf16 v[92:95], v[128:131], v[216:219], v[92:95]
	v_mfma_f32_16x16x32_bf16 v[88:91], v[136:139], v[216:219], v[88:91]
	v_mfma_f32_16x16x32_bf16 v[76:79], v[128:131], v[224:227], v[76:79]
	v_mfma_f32_16x16x32_bf16 v[72:75], v[136:139], v[224:227], v[72:75]
	v_mfma_f32_16x16x32_bf16 v[124:127], v[132:135], v[196:199], v[124:127]
	v_mfma_f32_16x16x32_bf16 v[120:123], v[140:143], v[196:199], v[120:123]
	v_mfma_f32_16x16x32_bf16 v[108:111], v[132:135], v[212:215], v[108:111]
	v_mfma_f32_16x16x32_bf16 v[104:107], v[140:143], v[212:215], v[104:107]
	v_mfma_f32_16x16x32_bf16 v[92:95], v[132:135], v[220:223], v[92:95]
	v_mfma_f32_16x16x32_bf16 v[88:91], v[140:143], v[220:223], v[88:91]
	v_mfma_f32_16x16x32_bf16 v[76:79], v[132:135], v[228:231], v[76:79]
	v_mfma_f32_16x16x32_bf16 v[72:75], v[140:143], v[228:231], v[72:75]
	v_mfma_f32_16x16x32_bf16 v[116:119], v[176:179], v[192:195], v[116:119]
	v_mfma_f32_16x16x32_bf16 v[112:115], v[184:187], v[192:195], v[112:115]
	v_mfma_f32_16x16x32_bf16 v[100:103], v[176:179], v[208:211], v[100:103]
	v_mfma_f32_16x16x32_bf16 v[96:99], v[184:187], v[208:211], v[96:99]
	v_mfma_f32_16x16x32_bf16 v[84:87], v[176:179], v[216:219], v[84:87]
	v_mfma_f32_16x16x32_bf16 v[80:83], v[184:187], v[216:219], v[80:83]
	v_mfma_f32_16x16x32_bf16 v[68:71], v[176:179], v[224:227], v[68:71]
	v_mfma_f32_16x16x32_bf16 v[64:67], v[184:187], v[224:227], v[64:67]
	v_mfma_f32_16x16x32_bf16 v[116:119], v[180:183], v[196:199], v[116:119]
	v_mfma_f32_16x16x32_bf16 v[112:115], v[188:191], v[196:199], v[112:115]
	v_mfma_f32_16x16x32_bf16 v[100:103], v[180:183], v[212:215], v[100:103]
	v_mfma_f32_16x16x32_bf16 v[96:99], v[188:191], v[212:215], v[96:99]
	v_mfma_f32_16x16x32_bf16 v[84:87], v[180:183], v[220:223], v[84:87]
	v_mfma_f32_16x16x32_bf16 v[80:83], v[188:191], v[220:223], v[80:83]
	v_mfma_f32_16x16x32_bf16 v[68:71], v[180:183], v[228:231], v[68:71]
	v_mfma_f32_16x16x32_bf16 v[64:67], v[188:191], v[228:231], v[64:67]
	s_barrier
	s_add_i32 s46, s90, s53
	v_lshl_add_u64 v[200:201], s[78:79], 0, v[146:147]
	s_mov_b32 m0, s46
	ds_read_b128 v[192:195], v205 offset:16384
	ds_read_b128 v[196:199], v205 offset:17408
	ds_read_b128 v[208:211], v205 offset:18432
	ds_read_b128 v[212:215], v205 offset:19456
	ds_read_b128 v[216:219], v205 offset:20480
	ds_read_b128 v[220:223], v205 offset:21504
	ds_read_b128 v[224:227], v205 offset:22528
	ds_read_b128 v[228:231], v205 offset:23552
	global_load_lds_dwordx4 v[200:201], off
	s_add_i32 m0, s46, 0x2000
	s_add_u32 s46, s78, 0x80000
	v_lshl_add_u64 v[232:233], s[78:79], 0, v[150:151]
	s_addc_u32 s47, s79, 0
	s_add_i32 s82, s91, s53
	global_load_lds_dwordx4 v[232:233], off
	v_lshl_add_u64 v[234:235], s[46:47], 0, v[146:147]
	s_mov_b32 m0, s82
	v_lshl_add_u64 v[236:237], s[80:81], 0, v[148:149]
	global_load_lds_dwordx4 v[234:235], off
	s_add_i32 m0, s82, 0x2000
	v_lshl_add_u64 v[234:235], s[46:47], 0, v[150:151]
	global_load_lds_dwordx4 v[234:235], off
	s_mov_b32 m0, s55
	v_lshl_add_u64 v[234:235], s[80:81], 0, v[144:145]
	global_load_lds_dwordx4 v[234:235], off
	s_mov_b32 m0, s57
	s_nop 0
	global_load_lds_dwordx4 v[236:237], off
	s_waitcnt vmcnt(8)
	s_waitcnt lgkmcnt(0)
	s_barrier
; #define PG8_STAGE(bufoff, gbase, voff) do { _Pragma("unroll") for (int _i = 0; _i < 2; ++_i) \
;         __builtin_amdgcn_global_load_lds((const unsigned*)((const char*)(gbase) + (voff)[_i]), (LAS unsigned*)(lds + (bufoff) + ldsw + _i * 8192), 16, 0, 0); } while (0)
; #define PG8_LDA(dst, b, h) do { _Pragma("unroll") for (int m = 0; m < 4; ++m) _Pragma("unroll") for (int k = 0; k < 2; ++k) dst[m][k] = *(const LAS bf16x8*)(lds + PG8_SA(b, h) + aoff + m * 2048 + k * 1024); } while (0)
; #define PG8_LDB(dst, b, h) do { _Pragma("unroll") for (int n = 0; n < 2; ++n) _Pragma("unroll") for (int k = 0; k < 2; ++k) dst[n][k] = *(const LAS bf16x8*)(lds + PG8_SB(b, h) + boff + n * 2048 + k * 1024); } while (0)
; #define PG8_MMA(ai, bj, At, Bt) do { __builtin_amdgcn_s_setprio(1); _Pragma("unroll") for (int m = 0; m < 4; ++m) _Pragma("unroll") for (int n = 0; n < 2; ++n) _Pragma("unroll") for (int k = 0; k < 2; ++k) \
;         acc[ai][bj][m][n] = __builtin_amdgcn_mfma_f32_16x16x32_bf16(Bt[n][k], At[m][k], acc[ai][bj][m][n], 0, 0, 0); __builtin_amdgcn_s_setprio(0); } while (0)
; #define PG8_WAIT_V(n) asm volatile("s_waitcnt vmcnt(" #n ")" ::: "memory")
; #define PG8_WAIT_L(n) asm volatile("s_waitcnt lgkmcnt(" #n ")" ::: "memory")
; #define PG8_BAR __builtin_amdgcn_s_barrier()
; #define PG8_SCHED __builtin_amdgcn_sched_barrier(0)
; template <class Epi, class Sched, bool ALIGN_EPI = true>
; __device__ __forceinline__ void gemm_phase(LAS unsigned char* lds, const Gemm g, const Sched& S, const Epi& E) {
;     ...
;             PG8_WAIT_V(8); PG8_WAIT_L(0); PG8_BAR; PG8_MMA(1, 0, At, B0); PG8_MMA(1, 1, At, B1); PG8_BAR; PG8_SCHED;
;             PG8_LDB(B0, 1, 0); PG8_LDB(B1, 1, 1); PG8_SCHED; PG8_LDA(At, 1, 0); PG8_STAGE(PG8_SA(0, 1), a2 + hstep, voffA);
;             PG8_WAIT_V(8); PG8_WAIT_L(0); PG8_BAR; PG8_MMA(0, 0, At, B0); PG8_MMA(0, 1, At, B1); PG8_BAR; PG8_SCHED;
	s_waitcnt lgkmcnt(0)
	v_mfma_f32_16x16x32_bf16 v[60:63], v[128:131], v[192:195], v[60:63]
	v_mfma_f32_16x16x32_bf16 v[56:59], v[136:139], v[192:195], v[56:59]
	v_mfma_f32_16x16x32_bf16 v[44:47], v[128:131], v[208:211], v[44:47]
	v_mfma_f32_16x16x32_bf16 v[40:43], v[136:139], v[208:211], v[40:43]
	v_mfma_f32_16x16x32_bf16 v[28:31], v[128:131], v[216:219], v[28:31]
	v_mfma_f32_16x16x32_bf16 v[24:27], v[136:139], v[216:219], v[24:27]
	v_mfma_f32_16x16x32_bf16 v[12:15], v[128:131], v[224:227], v[12:15]
	v_mfma_f32_16x16x32_bf16 v[8:11], v[136:139], v[224:227], v[8:11]
	v_mfma_f32_16x16x32_bf16 v[60:63], v[132:135], v[196:199], v[60:63]
	v_mfma_f32_16x16x32_bf16 v[56:59], v[140:143], v[196:199], v[56:59]
	v_mfma_f32_16x16x32_bf16 v[44:47], v[132:135], v[212:215], v[44:47]
	v_mfma_f32_16x16x32_bf16 v[40:43], v[140:143], v[212:215], v[40:43]
	v_mfma_f32_16x16x32_bf16 v[28:31], v[132:135], v[220:223], v[28:31]
	v_mfma_f32_16x16x32_bf16 v[24:27], v[140:143], v[220:223], v[24:27]
	v_mfma_f32_16x16x32_bf16 v[12:15], v[132:135], v[228:231], v[12:15]
	v_mfma_f32_16x16x32_bf16 v[8:11], v[140:143], v[228:231], v[8:11]
	v_mfma_f32_16x16x32_bf16 v[52:55], v[176:179], v[192:195], v[52:55]
	v_mfma_f32_16x16x32_bf16 v[48:51], v[184:187], v[192:195], v[48:51]
	v_mfma_f32_16x16x32_bf16 v[36:39], v[176:179], v[208:211], v[36:39]
	v_mfma_f32_16x16x32_bf16 v[32:35], v[184:187], v[208:211], v[32:35]
	v_mfma_f32_16x16x32_bf16 v[20:23], v[176:179], v[216:219], v[20:23]
	v_mfma_f32_16x16x32_bf16 v[16:19], v[184:187], v[216:219], v[16:19]
	v_mfma_f32_16x16x32_bf16 v[4:7], v[176:179], v[224:227], v[4:7]
	v_mfma_f32_16x16x32_bf16 v[0:3], v[184:187], v[224:227], v[0:3]
	v_mfma_f32_16x16x32_bf16 v[52:55], v[180:183], v[196:199], v[52:55]
	v_mfma_f32_16x16x32_bf16 v[48:51], v[188:191], v[196:199], v[48:51]
	v_mfma_f32_16x16x32_bf16 v[36:39], v[180:183], v[212:215], v[36:39]
	v_mfma_f32_16x16x32_bf16 v[32:35], v[188:191], v[212:215], v[32:35]
	v_mfma_f32_16x16x32_bf16 v[20:23], v[180:183], v[220:223], v[20:23]
	v_mfma_f32_16x16x32_bf16 v[16:19], v[188:191], v[220:223], v[16:19]
	v_mfma_f32_16x16x32_bf16 v[4:7], v[180:183], v[228:231], v[4:7]
	v_mfma_f32_16x16x32_bf16 v[0:3], v[188:191], v[228:231], v[0:3]
	s_barrier
	s_add_i32 s82, 0, 0x18000
	s_add_i32 s92, 0, 0x1c000
	v_add_u32_e32 v140, s82, v161
	v_add_u32_e32 v152, s92, v161
	ds_read_b128 v[128:131], v140
	ds_read_b128 v[132:135], v140 offset:1024
	ds_read_b128 v[136:139], v140 offset:2048
	ds_read_b128 v[140:143], v140 offset:3072
	ds_read_b128 v[176:179], v152
	ds_read_b128 v[180:183], v152 offset:1024
	ds_read_b128 v[184:187], v152 offset:2048
	ds_read_b128 v[188:191], v152 offset:3072
	s_add_u32 s46, s80, 0x80000
	s_addc_u32 s47, s81, 0
	s_mov_b32 m0, s83
	v_lshl_add_u64 v[238:239], s[46:47], 0, v[144:145]
	ds_read_b128 v[192:195], v205 offset:32768
	ds_read_b128 v[196:199], v205 offset:33792
	ds_read_b128 v[208:211], v205 offset:34816
	ds_read_b128 v[212:215], v205 offset:35840
	ds_read_b128 v[216:219], v205 offset:36864
	ds_read_b128 v[220:223], v205 offset:37888
	ds_read_b128 v[224:227], v205 offset:38912
	ds_read_b128 v[228:231], v205 offset:39936
	global_load_lds_dwordx4 v[238:239], off
	s_mov_b32 m0, s84
	v_lshl_add_u64 v[238:239], s[46:47], 0, v[148:149]
	global_load_lds_dwordx4 v[238:239], off
	s_waitcnt vmcnt(8)
	s_waitcnt lgkmcnt(0)
	s_barrier
	s_waitcnt lgkmcnt(0)
	v_mfma_f32_16x16x32_bf16 v[124:127], v[128:131], v[192:195], v[124:127]
	v_mfma_f32_16x16x32_bf16 v[120:123], v[136:139], v[192:195], v[120:123]
	v_mfma_f32_16x16x32_bf16 v[108:111], v[128:131], v[208:211], v[108:111]
	v_mfma_f32_16x16x32_bf16 v[104:107], v[136:139], v[208:211], v[104:107]
	v_mfma_f32_16x16x32_bf16 v[92:95], v[128:131], v[216:219], v[92:95]
	v_mfma_f32_16x16x32_bf16 v[88:91], v[136:139], v[216:219], v[88:91]
	v_mfma_f32_16x16x32_bf16 v[76:79], v[128:131], v[224:227], v[76:79]
	v_mfma_f32_16x16x32_bf16 v[72:75], v[136:139], v[224:227], v[72:75]
	v_mfma_f32_16x16x32_bf16 v[124:127], v[132:135], v[196:199], v[124:127]
	v_mfma_f32_16x16x32_bf16 v[120:123], v[140:143], v[196:199], v[120:123]
	v_mfma_f32_16x16x32_bf16 v[108:111], v[132:135], v[212:215], v[108:111]
	v_mfma_f32_16x16x32_bf16 v[104:107], v[140:143], v[212:215], v[104:107]
	v_mfma_f32_16x16x32_bf16 v[92:95], v[132:135], v[220:223], v[92:95]
	v_mfma_f32_16x16x32_bf16 v[88:91], v[140:143], v[220:223], v[88:91]
	v_mfma_f32_16x16x32_bf16 v[76:79], v[132:135], v[228:231], v[76:79]
	v_mfma_f32_16x16x32_bf16 v[72:75], v[140:143], v[228:231], v[72:75]
	v_mfma_f32_16x16x32_bf16 v[116:119], v[176:179], v[192:195], v[116:119]
	v_mfma_f32_16x16x32_bf16 v[112:115], v[184:187], v[192:195], v[112:115]
	v_mfma_f32_16x16x32_bf16 v[100:103], v[176:179], v[208:211], v[100:103]
	v_mfma_f32_16x16x32_bf16 v[96:99], v[184:187], v[208:211], v[96:99]
	v_mfma_f32_16x16x32_bf16 v[84:87], v[176:179], v[216:219], v[84:87]
	v_mfma_f32_16x16x32_bf16 v[80:83], v[184:187], v[216:219], v[80:83]
	v_mfma_f32_16x16x32_bf16 v[68:71], v[176:179], v[224:227], v[68:71]
	v_mfma_f32_16x16x32_bf16 v[64:67], v[184:187], v[224:227], v[64:67]
	v_mfma_f32_16x16x32_bf16 v[116:119], v[180:183], v[196:199], v[116:119]
	v_mfma_f32_16x16x32_bf16 v[112:115], v[188:191], v[196:199], v[112:115]
	v_mfma_f32_16x16x32_bf16 v[100:103], v[180:183], v[212:215], v[100:103]
	v_mfma_f32_16x16x32_bf16 v[96:99], v[188:191], v[212:215], v[96:99]
	v_mfma_f32_16x16x32_bf16 v[84:87], v[180:183], v[220:223], v[84:87]
	v_mfma_f32_16x16x32_bf16 v[80:83], v[188:191], v[220:223], v[80:83]
	v_mfma_f32_16x16x32_bf16 v[68:71], v[180:183], v[228:231], v[68:71]
	v_mfma_f32_16x16x32_bf16 v[64:67], v[188:191], v[228:231], v[64:67]
	s_barrier
; #define PG8_STAGE(bufoff, gbase, voff) do { _Pragma("unroll") for (int _i = 0; _i < 2; ++_i) \
;         __builtin_amdgcn_global_load_lds((const unsigned*)((const char*)(gbase) + (voff)[_i]), (LAS unsigned*)(lds + (bufoff) + ldsw + _i * 8192), 16, 0, 0); } while (0)
; #define PG8_LDA(dst, b, h) do { _Pragma("unroll") for (int m = 0; m < 4; ++m) _Pragma("unroll") for (int k = 0; k < 2; ++k) dst[m][k] = *(const LAS bf16x8*)(lds + PG8_SA(b, h) + aoff + m * 2048 + k * 1024); } while (0)
; #define PG8_MMA(ai, bj, At, Bt) do { __builtin_amdgcn_s_setprio(1); _Pragma("unroll") for (int m = 0; m < 4; ++m) _Pragma("unroll") for (int n = 0; n < 2; ++n) _Pragma("unroll") for (int k = 0; k < 2; ++k) \
;         acc[ai][bj][m][n] = __builtin_amdgcn_mfma_f32_16x16x32_bf16(Bt[n][k], At[m][k], acc[ai][bj][m][n], 0, 0, 0); __builtin_amdgcn_s_setprio(0); } while (0)
; #define PG8_WAIT_V(n) asm volatile("s_waitcnt vmcnt(" #n ")" ::: "memory")
; #define PG8_WAIT_L(n) asm volatile("s_waitcnt lgkmcnt(" #n ")" ::: "memory")
; #define PG8_BAR __builtin_amdgcn_s_barrier()
; #define PG8_SCHED __builtin_amdgcn_sched_barrier(0)
; template <class Epi, class Sched, bool ALIGN_EPI = true>
; __device__ __forceinline__ void gemm_phase(LAS unsigned char* lds, const Gemm g, const Sched& S, const Epi& E) {
;     ...
;             PG8_LDA(At, 1, 1); PG8_STAGE(PG8_SB(1, 0), b3, voffB); PG8_STAGE(PG8_SB(1, 1), b3 + hstep, voffB); PG8_STAGE(PG8_SA(1, 0), a3, voffA);
;             PG8_WAIT_V(8); PG8_WAIT_L(0); PG8_BAR; PG8_MMA(1, 0, At, B0); PG8_MMA(1, 1, At, B1); PG8_BAR; PG8_SCHED;
;         }
;         if constexpr (ALIGN_EPI) { if (wr == 0) PG8_BAR; }
	s_add_i32 s46, s82, s53
	v_lshl_add_u64 v[200:201], v[200:201], 0, s[28:29]
	s_mov_b32 m0, s46
	ds_read_b128 v[192:195], v205 offset:49152
	ds_read_b128 v[196:199], v205 offset:50176
	ds_read_b128 v[208:211], v205 offset:51200
	ds_read_b128 v[212:215], v205 offset:52224
	ds_read_b128 v[216:219], v205 offset:53248
	ds_read_b128 v[220:223], v205 offset:54272
	ds_read_b128 v[224:227], v205 offset:55296
	ds_read_b128 v[228:231], v205 offset:56320
	global_load_lds_dwordx4 v[200:201], off
	s_add_i32 m0, s46, 0x2000
	s_add_u32 s46, s78, 0x80080
	v_lshl_add_u64 v[200:201], v[232:233], 0, s[28:29]
	s_addc_u32 s47, s79, 0
	s_add_i32 s78, s92, s53
	global_load_lds_dwordx4 v[200:201], off
	s_mov_b32 m0, s78
	v_lshl_add_u64 v[200:201], s[46:47], 0, v[146:147]
	global_load_lds_dwordx4 v[200:201], off
	s_add_i32 m0, s78, 0x2000
	v_lshl_add_u64 v[200:201], s[46:47], 0, v[150:151]
	global_load_lds_dwordx4 v[200:201], off
	s_mov_b32 m0, s87
	v_lshl_add_u64 v[200:201], v[234:235], 0, s[28:29]
	global_load_lds_dwordx4 v[200:201], off
	s_mov_b32 m0, s88
	v_lshl_add_u64 v[200:201], v[236:237], 0, s[28:29]
	global_load_lds_dwordx4 v[200:201], off
	s_waitcnt vmcnt(8)
	s_waitcnt lgkmcnt(0)
	s_barrier
	s_waitcnt lgkmcnt(0)
	v_mfma_f32_16x16x32_bf16 v[60:63], v[128:131], v[192:195], v[60:63]
	v_mfma_f32_16x16x32_bf16 v[56:59], v[136:139], v[192:195], v[56:59]
	v_mfma_f32_16x16x32_bf16 v[44:47], v[128:131], v[208:211], v[44:47]
	v_mfma_f32_16x16x32_bf16 v[40:43], v[136:139], v[208:211], v[40:43]
	v_mfma_f32_16x16x32_bf16 v[28:31], v[128:131], v[216:219], v[28:31]
	v_mfma_f32_16x16x32_bf16 v[24:27], v[136:139], v[216:219], v[24:27]
	v_mfma_f32_16x16x32_bf16 v[12:15], v[128:131], v[224:227], v[12:15]
	v_mfma_f32_16x16x32_bf16 v[8:11], v[136:139], v[224:227], v[8:11]
	v_mfma_f32_16x16x32_bf16 v[60:63], v[132:135], v[196:199], v[60:63]
	v_mfma_f32_16x16x32_bf16 v[56:59], v[140:143], v[196:199], v[56:59]
	v_mfma_f32_16x16x32_bf16 v[44:47], v[132:135], v[212:215], v[44:47]
	v_mfma_f32_16x16x32_bf16 v[40:43], v[140:143], v[212:215], v[40:43]
	v_mfma_f32_16x16x32_bf16 v[28:31], v[132:135], v[220:223], v[28:31]
	v_mfma_f32_16x16x32_bf16 v[24:27], v[140:143], v[220:223], v[24:27]
	v_mfma_f32_16x16x32_bf16 v[12:15], v[132:135], v[228:231], v[12:15]
	v_mfma_f32_16x16x32_bf16 v[8:11], v[140:143], v[228:231], v[8:11]
	v_mfma_f32_16x16x32_bf16 v[52:55], v[176:179], v[192:195], v[52:55]
	v_mfma_f32_16x16x32_bf16 v[48:51], v[184:187], v[192:195], v[48:51]
	v_mfma_f32_16x16x32_bf16 v[36:39], v[176:179], v[208:211], v[36:39]
	v_mfma_f32_16x16x32_bf16 v[32:35], v[184:187], v[208:211], v[32:35]
	v_mfma_f32_16x16x32_bf16 v[20:23], v[176:179], v[216:219], v[20:23]
	v_mfma_f32_16x16x32_bf16 v[16:19], v[184:187], v[216:219], v[16:19]
	v_mfma_f32_16x16x32_bf16 v[4:7], v[176:179], v[224:227], v[4:7]
	v_mfma_f32_16x16x32_bf16 v[0:3], v[184:187], v[224:227], v[0:3]
	v_mfma_f32_16x16x32_bf16 v[52:55], v[180:183], v[196:199], v[52:55]
	v_mfma_f32_16x16x32_bf16 v[48:51], v[188:191], v[196:199], v[48:51]
	v_mfma_f32_16x16x32_bf16 v[36:39], v[180:183], v[212:215], v[36:39]
	v_mfma_f32_16x16x32_bf16 v[32:35], v[188:191], v[212:215], v[32:35]
	v_mfma_f32_16x16x32_bf16 v[20:23], v[180:183], v[220:223], v[20:23]
	v_mfma_f32_16x16x32_bf16 v[16:19], v[188:191], v[220:223], v[16:19]
	v_mfma_f32_16x16x32_bf16 v[4:7], v[180:183], v[228:231], v[4:7]
	v_mfma_f32_16x16x32_bf16 v[0:3], v[188:191], v[228:231], v[0:3]
	s_barrier
	s_add_i32 vcc_hi, vcc_hi, 2
	s_add_u32 s76, s76, 0x100
	s_addc_u32 s77, s77, 0
	s_add_u32 s97, s97, 0x100
	s_addc_u32 vcc_lo, vcc_lo, 0
	s_cmp_gt_u32 vcc_hi, 29
	s_cbranch_scc0 .LBB0_223
	s_and_b64 vcc, exec, s[34:35]
	s_cbranch_vccz .LBB0_226
	s_barrier

; #define PG8_STAGE(bufoff, gbase, voff) do { _Pragma("unroll") for (int _i = 0; _i < 2; ++_i) \
;         __builtin_amdgcn_global_load_lds((const unsigned*)((const char*)(gbase) + (voff)[_i]), (LAS unsigned*)(lds + (bufoff) + ldsw + _i * 8192), 16, 0, 0); } while (0)
; #define PG8_LDA(dst, b, h) do { _Pragma("unroll") for (int m = 0; m < 4; ++m) _Pragma("unroll") for (int k = 0; k < 2; ++k) dst[m][k] = *(const LAS bf16x8*)(lds + PG8_SA(b, h) + aoff + m * 2048 + k * 1024); } while (0)
; #define PG8_LDB(dst, b, h) do { _Pragma("unroll") for (int n = 0; n < 2; ++n) _Pragma("unroll") for (int k = 0; k < 2; ++k) dst[n][k] = *(const LAS bf16x8*)(lds + PG8_SB(b, h) + boff + n * 2048 + k * 1024); } while (0)
; #define PG8_MMA(ai, bj, At, Bt) do { __builtin_amdgcn_s_setprio(1); _Pragma("unroll") for (int m = 0; m < 4; ++m) _Pragma("unroll") for (int n = 0; n < 2; ++n) _Pragma("unroll") for (int k = 0; k < 2; ++k) \
;         acc[ai][bj][m][n] = __builtin_amdgcn_mfma_f32_16x16x32_bf16(Bt[n][k], At[m][k], acc[ai][bj][m][n], 0, 0, 0); __builtin_amdgcn_s_setprio(0); } while (0)
; #define PG8_WAIT_V(n) asm volatile("s_waitcnt vmcnt(" #n ")" ::: "memory")
; #define PG8_WAIT_L(n) asm volatile("s_waitcnt lgkmcnt(" #n ")" ::: "memory")
; #define PG8_BAR __builtin_amdgcn_s_barrier()
; #define PG8_SCHED __builtin_amdgcn_sched_barrier(0)
; template <class Epi, class Sched, bool ALIGN_EPI = true>
; __device__ __forceinline__ void gemm_phase(LAS unsigned char* lds, const Gemm g, const Sched& S, const Epi& E) {
;     ...
;         for (int t = 0; t < nt; t += 2) {
;             const bool last = (t == nt - 2);
;             const char* a1 = cA + (size_t)(t + 1) * kstep;
;             const char* a2 = last ? nA : cA + (size_t)(t + 2) * kstep; const char* b2 = last ? nB : cB + (size_t)(t + 2) * kstep;
;             const char* a3 = a2 + kstep; const char* b3 = b2 + kstep;
;             PG8_LDB(B0, 0, 0); PG8_LDB(B1, 0, 1); PG8_SCHED; PG8_LDA(At, 0, 0); PG8_STAGE(PG8_SA(1, 1), a1 + hstep, voffA);
;             PG8_WAIT_V(8); PG8_WAIT_L(0); PG8_BAR; PG8_MMA(0, 0, At, B0); PG8_MMA(0, 1, At, B1); PG8_BAR; PG8_SCHED;
;             PG8_LDA(At, 0, 1); PG8_STAGE(PG8_SB(0, 0), b2, voffB); PG8_STAGE(PG8_SB(0, 1), b2 + hstep, voffB); PG8_STAGE(PG8_SA(0, 0), a2, voffA);
;             PG8_WAIT_V(8); PG8_WAIT_L(0); PG8_BAR; PG8_MMA(1, 0, At, B0); PG8_MMA(1, 1, At, B1); PG8_BAR; PG8_SCHED;
.LBB0_560:
	ds_read_b128 v[128:131], v206
	ds_read_b128 v[132:135], v206 offset:1024
	ds_read_b128 v[136:139], v206 offset:2048
	ds_read_b128 v[140:143], v206 offset:3072
	ds_read_b128 v[144:147], v207
	ds_read_b128 v[148:151], v207 offset:1024
	ds_read_b128 v[152:155], v207 offset:2048
	ds_read_b128 v[156:159], v207 offset:3072
	s_add_u32 s28, s26, 0xfff80080
	s_addc_u32 s29, s27, -1
	s_cmp_eq_u32 s58, 28
	s_cselect_b32 s31, s53, s29
	s_cselect_b32 s30, s54, s28
	s_cselect_b32 s29, s9, s57
	s_cselect_b32 s28, s55, s56
	v_lshl_add_u64 v[214:215], s[26:27], 0, v[184:185]
	s_add_i32 m0, s38, 0xc000
	ds_read_b128 v[160:163], v208
	ds_read_b128 v[164:167], v208 offset:1024
	ds_read_b128 v[168:171], v208 offset:2048
	ds_read_b128 v[172:175], v208 offset:3072
	ds_read_b128 v[188:191], v208 offset:4096
	ds_read_b128 v[192:195], v208 offset:5120
	ds_read_b128 v[196:199], v208 offset:6144
	ds_read_b128 v[210:213], v208 offset:7168
	global_load_lds_dwordx4 v[214:215], off
	s_add_i32 m0, s38, 0xe000
	v_lshl_add_u64 v[214:215], s[26:27], 0, v[186:187]
	global_load_lds_dwordx4 v[214:215], off
	s_waitcnt vmcnt(8)
	s_waitcnt lgkmcnt(0)
	s_barrier
	s_waitcnt lgkmcnt(0)
	v_mfma_f32_16x16x32_bf16 v[124:127], v[128:131], v[160:163], v[124:127]
	v_mfma_f32_16x16x32_bf16 v[120:123], v[136:139], v[160:163], v[120:123]
	v_mfma_f32_16x16x32_bf16 v[108:111], v[128:131], v[168:171], v[108:111]
	v_mfma_f32_16x16x32_bf16 v[104:107], v[136:139], v[168:171], v[104:107]
	v_mfma_f32_16x16x32_bf16 v[92:95], v[128:131], v[188:191], v[92:95]
	v_mfma_f32_16x16x32_bf16 v[88:91], v[136:139], v[188:191], v[88:91]
	v_mfma_f32_16x16x32_bf16 v[76:79], v[128:131], v[196:199], v[76:79]
	v_mfma_f32_16x16x32_bf16 v[72:75], v[136:139], v[196:199], v[72:75]
	v_mfma_f32_16x16x32_bf16 v[124:127], v[132:135], v[164:167], v[124:127]
	v_mfma_f32_16x16x32_bf16 v[120:123], v[140:143], v[164:167], v[120:123]
	v_mfma_f32_16x16x32_bf16 v[108:111], v[132:135], v[172:175], v[108:111]
	v_mfma_f32_16x16x32_bf16 v[104:107], v[140:143], v[172:175], v[104:107]
	v_mfma_f32_16x16x32_bf16 v[92:95], v[132:135], v[192:195], v[92:95]
	v_mfma_f32_16x16x32_bf16 v[88:91], v[140:143], v[192:195], v[88:91]
	v_mfma_f32_16x16x32_bf16 v[76:79], v[132:135], v[210:213], v[76:79]
	v_mfma_f32_16x16x32_bf16 v[72:75], v[140:143], v[210:213], v[72:75]
	v_mfma_f32_16x16x32_bf16 v[116:119], v[144:147], v[160:163], v[116:119]
	v_mfma_f32_16x16x32_bf16 v[112:115], v[152:155], v[160:163], v[112:115]
	v_mfma_f32_16x16x32_bf16 v[100:103], v[144:147], v[168:171], v[100:103]
	v_mfma_f32_16x16x32_bf16 v[96:99], v[152:155], v[168:171], v[96:99]
	v_mfma_f32_16x16x32_bf16 v[84:87], v[144:147], v[188:191], v[84:87]
	v_mfma_f32_16x16x32_bf16 v[80:83], v[152:155], v[188:191], v[80:83]
	v_mfma_f32_16x16x32_bf16 v[68:71], v[144:147], v[196:199], v[68:71]
	v_mfma_f32_16x16x32_bf16 v[64:67], v[152:155], v[196:199], v[64:67]
	v_mfma_f32_16x16x32_bf16 v[116:119], v[148:151], v[164:167], v[116:119]
	v_mfma_f32_16x16x32_bf16 v[112:115], v[156:159], v[164:167], v[112:115]
	v_mfma_f32_16x16x32_bf16 v[100:103], v[148:151], v[172:175], v[100:103]
	v_mfma_f32_16x16x32_bf16 v[96:99], v[156:159], v[172:175], v[96:99]
	v_mfma_f32_16x16x32_bf16 v[84:87], v[148:151], v[192:195], v[84:87]
	v_mfma_f32_16x16x32_bf16 v[80:83], v[156:159], v[192:195], v[80:83]
	v_mfma_f32_16x16x32_bf16 v[68:71], v[148:151], v[210:213], v[68:71]
	v_mfma_f32_16x16x32_bf16 v[64:67], v[156:159], v[210:213], v[64:67]
	s_barrier
	s_add_i32 s46, s44, s37
	v_lshl_add_u64 v[214:215], s[28:29], 0, v[178:179]
	s_mov_b32 m0, s46
	ds_read_b128 v[160:163], v208 offset:16384
	ds_read_b128 v[164:167], v208 offset:17408
	ds_read_b128 v[168:171], v208 offset:18432
	ds_read_b128 v[172:175], v208 offset:19456
	ds_read_b128 v[188:191], v208 offset:20480
	ds_read_b128 v[192:195], v208 offset:21504
	ds_read_b128 v[196:199], v208 offset:22528
	ds_read_b128 v[210:213], v208 offset:23552
	global_load_lds_dwordx4 v[214:215], off
	s_add_i32 m0, s46, 0x2000
	s_add_u32 s46, s28, 0x80000
	v_lshl_add_u64 v[216:217], s[28:29], 0, v[182:183]
	s_addc_u32 s47, s29, 0
	s_add_i32 s59, s45, s37
	global_load_lds_dwordx4 v[216:217], off
	v_lshl_add_u64 v[218:219], s[46:47], 0, v[178:179]
	s_mov_b32 m0, s59
	v_lshl_add_u64 v[220:221], s[30:31], 0, v[180:181]
	global_load_lds_dwordx4 v[218:219], off
	s_add_i32 m0, s59, 0x2000
	v_lshl_add_u64 v[218:219], s[46:47], 0, v[182:183]
	global_load_lds_dwordx4 v[218:219], off
	s_mov_b32 m0, s38
	v_lshl_add_u64 v[218:219], s[30:31], 0, v[176:177]
	global_load_lds_dwordx4 v[218:219], off
	s_mov_b32 m0, s39
	s_nop 0
	global_load_lds_dwordx4 v[220:221], off
	s_waitcnt vmcnt(8)
	s_waitcnt lgkmcnt(0)
	s_barrier
; #define PG8_STAGE(bufoff, gbase, voff) do { _Pragma("unroll") for (int _i = 0; _i < 2; ++_i) \
;         __builtin_amdgcn_global_load_lds((const unsigned*)((const char*)(gbase) + (voff)[_i]), (LAS unsigned*)(lds + (bufoff) + ldsw + _i * 8192), 16, 0, 0); } while (0)
; #define PG8_LDA(dst, b, h) do { _Pragma("unroll") for (int m = 0; m < 4; ++m) _Pragma("unroll") for (int k = 0; k < 2; ++k) dst[m][k] = *(const LAS bf16x8*)(lds + PG8_SA(b, h) + aoff + m * 2048 + k * 1024); } while (0)
; #define PG8_LDB(dst, b, h) do { _Pragma("unroll") for (int n = 0; n < 2; ++n) _Pragma("unroll") for (int k = 0; k < 2; ++k) dst[n][k] = *(const LAS bf16x8*)(lds + PG8_SB(b, h) + boff + n * 2048 + k * 1024); } while (0)
; #define PG8_MMA(ai, bj, At, Bt) do { __builtin_amdgcn_s_setprio(1); _Pragma("unroll") for (int m = 0; m < 4; ++m) _Pragma("unroll") for (int n = 0; n < 2; ++n) _Pragma("unroll") for (int k = 0; k < 2; ++k) \
;         acc[ai][bj][m][n] = __builtin_amdgcn_mfma_f32_16x16x32_bf16(Bt[n][k], At[m][k], acc[ai][bj][m][n], 0, 0, 0); __builtin_amdgcn_s_setprio(0); } while (0)
; #define PG8_WAIT_V(n) asm volatile("s_waitcnt vmcnt(" #n ")" ::: "memory")
; #define PG8_WAIT_L(n) asm volatile("s_waitcnt lgkmcnt(" #n ")" ::: "memory")
; #define PG8_BAR __builtin_amdgcn_s_barrier()
; #define PG8_SCHED __builtin_amdgcn_sched_barrier(0)
; template <class Epi, class Sched, bool ALIGN_EPI = true>
; __device__ __forceinline__ void gemm_phase(LAS unsigned char* lds, const Gemm g, const Sched& S, const Epi& E) {
;     ...
;             PG8_WAIT_V(8); PG8_WAIT_L(0); PG8_BAR; PG8_MMA(1, 0, At, B0); PG8_MMA(1, 1, At, B1); PG8_BAR; PG8_SCHED;
;             PG8_LDB(B0, 1, 0); PG8_LDB(B1, 1, 1); PG8_SCHED; PG8_LDA(At, 1, 0); PG8_STAGE(PG8_SA(0, 1), a2 + hstep, voffA);
;             PG8_WAIT_V(8); PG8_WAIT_L(0); PG8_BAR; PG8_MMA(0, 0, At, B0); PG8_MMA(0, 1, At, B1); PG8_BAR; PG8_SCHED;
	s_waitcnt lgkmcnt(0)
	v_mfma_f32_16x16x32_bf16 v[60:63], v[128:131], v[160:163], v[60:63]
	v_mfma_f32_16x16x32_bf16 v[56:59], v[136:139], v[160:163], v[56:59]
	v_mfma_f32_16x16x32_bf16 v[44:47], v[128:131], v[168:171], v[44:47]
	v_mfma_f32_16x16x32_bf16 v[40:43], v[136:139], v[168:171], v[40:43]
	v_mfma_f32_16x16x32_bf16 v[28:31], v[128:131], v[188:191], v[28:31]
	v_mfma_f32_16x16x32_bf16 v[24:27], v[136:139], v[188:191], v[24:27]
	v_mfma_f32_16x16x32_bf16 v[12:15], v[128:131], v[196:199], v[12:15]
	v_mfma_f32_16x16x32_bf16 v[8:11], v[136:139], v[196:199], v[8:11]
	v_mfma_f32_16x16x32_bf16 v[60:63], v[132:135], v[164:167], v[60:63]
	v_mfma_f32_16x16x32_bf16 v[56:59], v[140:143], v[164:167], v[56:59]
	v_mfma_f32_16x16x32_bf16 v[44:47], v[132:135], v[172:175], v[44:47]
	v_mfma_f32_16x16x32_bf16 v[40:43], v[140:143], v[172:175], v[40:43]
	v_mfma_f32_16x16x32_bf16 v[28:31], v[132:135], v[192:195], v[28:31]
	v_mfma_f32_16x16x32_bf16 v[24:27], v[140:143], v[192:195], v[24:27]
	v_mfma_f32_16x16x32_bf16 v[12:15], v[132:135], v[210:213], v[12:15]
	v_mfma_f32_16x16x32_bf16 v[8:11], v[140:143], v[210:213], v[8:11]
	v_mfma_f32_16x16x32_bf16 v[52:55], v[144:147], v[160:163], v[52:55]
	v_mfma_f32_16x16x32_bf16 v[48:51], v[152:155], v[160:163], v[48:51]
	v_mfma_f32_16x16x32_bf16 v[36:39], v[144:147], v[168:171], v[36:39]
	v_mfma_f32_16x16x32_bf16 v[32:35], v[152:155], v[168:171], v[32:35]
	v_mfma_f32_16x16x32_bf16 v[20:23], v[144:147], v[188:191], v[20:23]
	v_mfma_f32_16x16x32_bf16 v[16:19], v[152:155], v[188:191], v[16:19]
	v_mfma_f32_16x16x32_bf16 v[4:7], v[144:147], v[196:199], v[4:7]
	v_mfma_f32_16x16x32_bf16 v[0:3], v[152:155], v[196:199], v[0:3]
	v_mfma_f32_16x16x32_bf16 v[52:55], v[148:151], v[164:167], v[52:55]
	v_mfma_f32_16x16x32_bf16 v[48:51], v[156:159], v[164:167], v[48:51]
	v_mfma_f32_16x16x32_bf16 v[36:39], v[148:151], v[172:175], v[36:39]
	v_mfma_f32_16x16x32_bf16 v[32:35], v[156:159], v[172:175], v[32:35]
	v_mfma_f32_16x16x32_bf16 v[20:23], v[148:151], v[192:195], v[20:23]
	v_mfma_f32_16x16x32_bf16 v[16:19], v[156:159], v[192:195], v[16:19]
	v_mfma_f32_16x16x32_bf16 v[4:7], v[148:151], v[210:213], v[4:7]
	v_mfma_f32_16x16x32_bf16 v[0:3], v[156:159], v[210:213], v[0:3]
	s_barrier
	s_add_i32 s46, 0, 0x18000
	s_add_i32 s47, 0, 0x1c000
	v_add_u32_e32 v140, s46, v204
	v_add_u32_e32 v156, s47, v204
	ds_read_b128 v[128:131], v140
	ds_read_b128 v[132:135], v140 offset:1024
	ds_read_b128 v[136:139], v140 offset:2048
	ds_read_b128 v[140:143], v140 offset:3072
	ds_read_b128 v[144:147], v156
	ds_read_b128 v[148:151], v156 offset:1024
	ds_read_b128 v[152:155], v156 offset:2048
	ds_read_b128 v[156:159], v156 offset:3072
	s_add_u32 s30, s30, 0x80000
	s_addc_u32 s31, s31, 0
	s_mov_b32 m0, s40
	v_lshl_add_u64 v[222:223], s[30:31], 0, v[176:177]
	ds_read_b128 v[160:163], v208 offset:32768
	ds_read_b128 v[164:167], v208 offset:33792
	ds_read_b128 v[168:171], v208 offset:34816
	ds_read_b128 v[172:175], v208 offset:35840
	ds_read_b128 v[188:191], v208 offset:36864
	ds_read_b128 v[192:195], v208 offset:37888
	ds_read_b128 v[196:199], v208 offset:38912
	ds_read_b128 v[210:213], v208 offset:39936
	global_load_lds_dwordx4 v[222:223], off
	s_mov_b32 m0, s41
	v_lshl_add_u64 v[222:223], s[30:31], 0, v[180:181]
	global_load_lds_dwordx4 v[222:223], off
	s_waitcnt vmcnt(8)
	s_waitcnt lgkmcnt(0)
	s_barrier
	s_waitcnt lgkmcnt(0)
	v_mfma_f32_16x16x32_bf16 v[124:127], v[128:131], v[160:163], v[124:127]
	v_mfma_f32_16x16x32_bf16 v[120:123], v[136:139], v[160:163], v[120:123]
	v_mfma_f32_16x16x32_bf16 v[108:111], v[128:131], v[168:171], v[108:111]
	v_mfma_f32_16x16x32_bf16 v[104:107], v[136:139], v[168:171], v[104:107]
	v_mfma_f32_16x16x32_bf16 v[92:95], v[128:131], v[188:191], v[92:95]
	v_mfma_f32_16x16x32_bf16 v[88:91], v[136:139], v[188:191], v[88:91]
	v_mfma_f32_16x16x32_bf16 v[76:79], v[128:131], v[196:199], v[76:79]
	v_mfma_f32_16x16x32_bf16 v[72:75], v[136:139], v[196:199], v[72:75]
	v_mfma_f32_16x16x32_bf16 v[124:127], v[132:135], v[164:167], v[124:127]
	v_mfma_f32_16x16x32_bf16 v[120:123], v[140:143], v[164:167], v[120:123]
	v_mfma_f32_16x16x32_bf16 v[108:111], v[132:135], v[172:175], v[108:111]
	v_mfma_f32_16x16x32_bf16 v[104:107], v[140:143], v[172:175], v[104:107]
	v_mfma_f32_16x16x32_bf16 v[92:95], v[132:135], v[192:195], v[92:95]
	v_mfma_f32_16x16x32_bf16 v[88:91], v[140:143], v[192:195], v[88:91]
	v_mfma_f32_16x16x32_bf16 v[76:79], v[132:135], v[210:213], v[76:79]
	v_mfma_f32_16x16x32_bf16 v[72:75], v[140:143], v[210:213], v[72:75]
	v_mfma_f32_16x16x32_bf16 v[116:119], v[144:147], v[160:163], v[116:119]
	v_mfma_f32_16x16x32_bf16 v[112:115], v[152:155], v[160:163], v[112:115]
	v_mfma_f32_16x16x32_bf16 v[100:103], v[144:147], v[168:171], v[100:103]
	v_mfma_f32_16x16x32_bf16 v[96:99], v[152:155], v[168:171], v[96:99]
	v_mfma_f32_16x16x32_bf16 v[84:87], v[144:147], v[188:191], v[84:87]
	v_mfma_f32_16x16x32_bf16 v[80:83], v[152:155], v[188:191], v[80:83]
	v_mfma_f32_16x16x32_bf16 v[68:71], v[144:147], v[196:199], v[68:71]
	v_mfma_f32_16x16x32_bf16 v[64:67], v[152:155], v[196:199], v[64:67]
	v_mfma_f32_16x16x32_bf16 v[116:119], v[148:151], v[164:167], v[116:119]
	v_mfma_f32_16x16x32_bf16 v[112:115], v[156:159], v[164:167], v[112:115]
	v_mfma_f32_16x16x32_bf16 v[100:103], v[148:151], v[172:175], v[100:103]
	v_mfma_f32_16x16x32_bf16 v[96:99], v[156:159], v[172:175], v[96:99]
	v_mfma_f32_16x16x32_bf16 v[84:87], v[148:151], v[192:195], v[84:87]
	v_mfma_f32_16x16x32_bf16 v[80:83], v[156:159], v[192:195], v[80:83]
	v_mfma_f32_16x16x32_bf16 v[68:71], v[148:151], v[210:213], v[68:71]
	v_mfma_f32_16x16x32_bf16 v[64:67], v[156:159], v[210:213], v[64:67]
	s_barrier
; #define PG8_STAGE(bufoff, gbase, voff) do { _Pragma("unroll") for (int _i = 0; _i < 2; ++_i) \
;         __builtin_amdgcn_global_load_lds((const unsigned*)((const char*)(gbase) + (voff)[_i]), (LAS unsigned*)(lds + (bufoff) + ldsw + _i * 8192), 16, 0, 0); } while (0)
; #define PG8_LDA(dst, b, h) do { _Pragma("unroll") for (int m = 0; m < 4; ++m) _Pragma("unroll") for (int k = 0; k < 2; ++k) dst[m][k] = *(const LAS bf16x8*)(lds + PG8_SA(b, h) + aoff + m * 2048 + k * 1024); } while (0)
; #define PG8_MMA(ai, bj, At, Bt) do { __builtin_amdgcn_s_setprio(1); _Pragma("unroll") for (int m = 0; m < 4; ++m) _Pragma("unroll") for (int n = 0; n < 2; ++n) _Pragma("unroll") for (int k = 0; k < 2; ++k) \
;         acc[ai][bj][m][n] = __builtin_amdgcn_mfma_f32_16x16x32_bf16(Bt[n][k], At[m][k], acc[ai][bj][m][n], 0, 0, 0); __builtin_amdgcn_s_setprio(0); } while (0)
; #define PG8_WAIT_V(n) asm volatile("s_waitcnt vmcnt(" #n ")" ::: "memory")
; #define PG8_WAIT_L(n) asm volatile("s_waitcnt lgkmcnt(" #n ")" ::: "memory")
; #define PG8_BAR __builtin_amdgcn_s_barrier()
; #define PG8_SCHED __builtin_amdgcn_sched_barrier(0)
; template <class Epi, class Sched, bool ALIGN_EPI = true>
; __device__ __forceinline__ void gemm_phase(LAS unsigned char* lds, const Gemm g, const Sched& S, const Epi& E) {
;     ...
;             PG8_LDA(At, 1, 1); PG8_STAGE(PG8_SB(1, 0), b3, voffB); PG8_STAGE(PG8_SB(1, 1), b3 + hstep, voffB); PG8_STAGE(PG8_SA(1, 0), a3, voffA);
;             PG8_WAIT_V(8); PG8_WAIT_L(0); PG8_BAR; PG8_MMA(1, 0, At, B0); PG8_MMA(1, 1, At, B1); PG8_BAR; PG8_SCHED;
;         }
;         if constexpr (ALIGN_EPI) { if (wr == 0) PG8_BAR; }
	s_add_i32 s30, s46, s37
	v_lshl_add_u64 v[214:215], v[214:215], 0, s[20:21]
	s_mov_b32 m0, s30
	ds_read_b128 v[160:163], v208 offset:49152
	ds_read_b128 v[164:167], v208 offset:50176
	ds_read_b128 v[168:171], v208 offset:51200
	ds_read_b128 v[172:175], v208 offset:52224
	ds_read_b128 v[188:191], v208 offset:53248
	ds_read_b128 v[192:195], v208 offset:54272
	ds_read_b128 v[196:199], v208 offset:55296
	ds_read_b128 v[210:213], v208 offset:56320
	global_load_lds_dwordx4 v[214:215], off
	s_add_i32 m0, s30, 0x2000
	s_add_u32 s28, s28, 0x80080
	v_lshl_add_u64 v[214:215], v[216:217], 0, s[20:21]
	s_addc_u32 s29, s29, 0
	s_add_i32 s30, s47, s37
	global_load_lds_dwordx4 v[214:215], off
	s_mov_b32 m0, s30
	v_lshl_add_u64 v[214:215], s[28:29], 0, v[178:179]
	global_load_lds_dwordx4 v[214:215], off
	s_add_i32 m0, s30, 0x2000
	v_lshl_add_u64 v[214:215], s[28:29], 0, v[182:183]
	global_load_lds_dwordx4 v[214:215], off
	s_mov_b32 m0, s42
	v_lshl_add_u64 v[214:215], v[218:219], 0, s[20:21]
	global_load_lds_dwordx4 v[214:215], off
	s_mov_b32 m0, s43
	v_lshl_add_u64 v[214:215], v[220:221], 0, s[20:21]
	global_load_lds_dwordx4 v[214:215], off
	s_waitcnt vmcnt(8)
	s_waitcnt lgkmcnt(0)
	s_barrier
	s_waitcnt lgkmcnt(0)
	v_mfma_f32_16x16x32_bf16 v[60:63], v[128:131], v[160:163], v[60:63]
	v_mfma_f32_16x16x32_bf16 v[56:59], v[136:139], v[160:163], v[56:59]
	v_mfma_f32_16x16x32_bf16 v[44:47], v[128:131], v[168:171], v[44:47]
	v_mfma_f32_16x16x32_bf16 v[40:43], v[136:139], v[168:171], v[40:43]
	v_mfma_f32_16x16x32_bf16 v[28:31], v[128:131], v[188:191], v[28:31]
	v_mfma_f32_16x16x32_bf16 v[24:27], v[136:139], v[188:191], v[24:27]
	v_mfma_f32_16x16x32_bf16 v[12:15], v[128:131], v[196:199], v[12:15]
	v_mfma_f32_16x16x32_bf16 v[8:11], v[136:139], v[196:199], v[8:11]
	v_mfma_f32_16x16x32_bf16 v[60:63], v[132:135], v[164:167], v[60:63]
	v_mfma_f32_16x16x32_bf16 v[56:59], v[140:143], v[164:167], v[56:59]
	v_mfma_f32_16x16x32_bf16 v[44:47], v[132:135], v[172:175], v[44:47]
	v_mfma_f32_16x16x32_bf16 v[40:43], v[140:143], v[172:175], v[40:43]
	v_mfma_f32_16x16x32_bf16 v[28:31], v[132:135], v[192:195], v[28:31]
	v_mfma_f32_16x16x32_bf16 v[24:27], v[140:143], v[192:195], v[24:27]
	v_mfma_f32_16x16x32_bf16 v[12:15], v[132:135], v[210:213], v[12:15]
	v_mfma_f32_16x16x32_bf16 v[8:11], v[140:143], v[210:213], v[8:11]
	v_mfma_f32_16x16x32_bf16 v[52:55], v[144:147], v[160:163], v[52:55]
	v_mfma_f32_16x16x32_bf16 v[48:51], v[152:155], v[160:163], v[48:51]
	v_mfma_f32_16x16x32_bf16 v[36:39], v[144:147], v[168:171], v[36:39]
	v_mfma_f32_16x16x32_bf16 v[32:35], v[152:155], v[168:171], v[32:35]
	v_mfma_f32_16x16x32_bf16 v[20:23], v[144:147], v[188:191], v[20:23]
	v_mfma_f32_16x16x32_bf16 v[16:19], v[152:155], v[188:191], v[16:19]
	v_mfma_f32_16x16x32_bf16 v[4:7], v[144:147], v[196:199], v[4:7]
	v_mfma_f32_16x16x32_bf16 v[0:3], v[152:155], v[196:199], v[0:3]
	v_mfma_f32_16x16x32_bf16 v[52:55], v[148:151], v[164:167], v[52:55]
	v_mfma_f32_16x16x32_bf16 v[48:51], v[156:159], v[164:167], v[48:51]
	v_mfma_f32_16x16x32_bf16 v[36:39], v[148:151], v[172:175], v[36:39]
	v_mfma_f32_16x16x32_bf16 v[32:35], v[156:159], v[172:175], v[32:35]
	v_mfma_f32_16x16x32_bf16 v[20:23], v[148:151], v[192:195], v[20:23]
	v_mfma_f32_16x16x32_bf16 v[16:19], v[156:159], v[192:195], v[16:19]
	v_mfma_f32_16x16x32_bf16 v[4:7], v[148:151], v[210:213], v[4:7]
	v_mfma_f32_16x16x32_bf16 v[0:3], v[156:159], v[210:213], v[0:3]
	s_barrier
	s_add_i32 s58, s58, 2
	s_add_u32 s26, s26, 0x100
	s_addc_u32 s27, s27, 0
	s_add_u32 s56, s56, 0x100
	s_addc_u32 s57, s57, 0
	s_cmp_gt_u32 s58, 29
	s_cbranch_scc0 .LBB0_560
	s_and_b64 vcc, exec, s[22:23]
	s_cbranch_vccz .LBB0_563
	s_barrier

; #define PG8_STAGE(bufoff, gbase, voff) do { _Pragma("unroll") for (int _i = 0; _i < 2; ++_i) \
;         __builtin_amdgcn_global_load_lds((const unsigned*)((const char*)(gbase) + (voff)[_i]), (LAS unsigned*)(lds + (bufoff) + ldsw + _i * 8192), 16, 0, 0); } while (0)
; #define PG8_LDA(dst, b, h) do { _Pragma("unroll") for (int m = 0; m < 4; ++m) _Pragma("unroll") for (int k = 0; k < 2; ++k) dst[m][k] = *(const LAS bf16x8*)(lds + PG8_SA(b, h) + aoff + m * 2048 + k * 1024); } while (0)
; #define PG8_LDB(dst, b, h) do { _Pragma("unroll") for (int n = 0; n < 2; ++n) _Pragma("unroll") for (int k = 0; k < 2; ++k) dst[n][k] = *(const LAS bf16x8*)(lds + PG8_SB(b, h) + boff + n * 2048 + k * 1024); } while (0)
; #define PG8_MMA(ai, bj, At, Bt) do { __builtin_amdgcn_s_setprio(1); _Pragma("unroll") for (int m = 0; m < 4; ++m) _Pragma("unroll") for (int n = 0; n < 2; ++n) _Pragma("unroll") for (int k = 0; k < 2; ++k) \
;         acc[ai][bj][m][n] = __builtin_amdgcn_mfma_f32_16x16x32_bf16(Bt[n][k], At[m][k], acc[ai][bj][m][n], 0, 0, 0); __builtin_amdgcn_s_setprio(0); } while (0)
; #define PG8_WAIT_V(n) asm volatile("s_waitcnt vmcnt(" #n ")" ::: "memory")
; #define PG8_WAIT_L(n) asm volatile("s_waitcnt lgkmcnt(" #n ")" ::: "memory")
; #define PG8_BAR __builtin_amdgcn_s_barrier()
; #define PG8_SCHED __builtin_amdgcn_sched_barrier(0)
; template <class Epi, class Sched, bool ALIGN_EPI = true>
; __device__ __forceinline__ void gemm_phase(LAS unsigned char* lds, const Gemm g, const Sched& S, const Epi& E) {
;     ...
;         for (int t = 0; t < nt; t += 2) {
;             const bool last = (t == nt - 2);
;             const char* a1 = cA + (size_t)(t + 1) * kstep;
;             const char* a2 = last ? nA : cA + (size_t)(t + 2) * kstep; const char* b2 = last ? nB : cB + (size_t)(t + 2) * kstep;
;             const char* a3 = a2 + kstep; const char* b3 = b2 + kstep;
;             PG8_LDB(B0, 0, 0); PG8_LDB(B1, 0, 1); PG8_SCHED; PG8_LDA(At, 0, 0); PG8_STAGE(PG8_SA(1, 1), a1 + hstep, voffA);
;             PG8_WAIT_V(8); PG8_WAIT_L(0); PG8_BAR; PG8_MMA(0, 0, At, B0); PG8_MMA(0, 1, At, B1); PG8_BAR; PG8_SCHED;
;             PG8_LDA(At, 0, 1); PG8_STAGE(PG8_SB(0, 0), b2, voffB); PG8_STAGE(PG8_SB(0, 1), b2 + hstep, voffB); PG8_STAGE(PG8_SA(0, 0), a2, voffA);
;             PG8_WAIT_V(8); PG8_WAIT_L(0); PG8_BAR; PG8_MMA(1, 0, At, B0); PG8_MMA(1, 1, At, B1); PG8_BAR; PG8_SCHED;
.LBB0_647:
	ds_read_b128 v[152:155], v147
	ds_read_b128 v[156:159], v147 offset:1024
	ds_read_b128 v[160:163], v147 offset:2048
	ds_read_b128 v[164:167], v147 offset:3072
	ds_read_b128 v[168:171], v148
	ds_read_b128 v[172:175], v148 offset:1024
	ds_read_b128 v[176:179], v148 offset:2048
	ds_read_b128 v[180:183], v148 offset:3072
	s_add_u32 s26, s24, 0xfff80080
	s_addc_u32 s27, s25, -1
	s_cmp_eq_u32 s56, 28
	s_cselect_b32 s29, s51, s27
	s_cselect_b32 s28, s52, s26
	s_cselect_b32 s27, s7, s55
	s_cselect_b32 s26, s53, s54
	v_lshl_add_u64 v[140:141], s[24:25], 0, v[136:137]
	s_add_i32 m0, s37, 0xc000
	ds_read_b128 v[184:187], v149
	ds_read_b128 v[188:191], v149 offset:1024
	ds_read_b128 v[192:195], v149 offset:2048
	ds_read_b128 v[196:199], v149 offset:3072
	ds_read_b128 v[204:207], v149 offset:4096
	ds_read_b128 v[208:211], v149 offset:5120
	ds_read_b128 v[212:215], v149 offset:6144
	ds_read_b128 v[216:219], v149 offset:7168
	global_load_lds_dwordx4 v[140:141], off
	s_add_i32 m0, s37, 0xe000
	v_lshl_add_u64 v[140:141], s[24:25], 0, v[138:139]
	global_load_lds_dwordx4 v[140:141], off
	s_waitcnt vmcnt(8)
	s_waitcnt lgkmcnt(0)
	s_barrier
	s_waitcnt lgkmcnt(0)
	v_mfma_f32_16x16x32_bf16 v[112:115], v[152:155], v[184:187], v[112:115]
	v_mfma_f32_16x16x32_bf16 v[108:111], v[160:163], v[184:187], v[108:111]
	v_mfma_f32_16x16x32_bf16 v[100:103], v[152:155], v[192:195], v[100:103]
	v_mfma_f32_16x16x32_bf16 v[96:99], v[160:163], v[192:195], v[96:99]
	v_mfma_f32_16x16x32_bf16 v[92:95], v[152:155], v[204:207], v[92:95]
	v_mfma_f32_16x16x32_bf16 v[84:87], v[160:163], v[204:207], v[84:87]
	v_mfma_f32_16x16x32_bf16 v[76:79], v[152:155], v[212:215], v[76:79]
	v_mfma_f32_16x16x32_bf16 v[68:71], v[160:163], v[212:215], v[68:71]
	v_mfma_f32_16x16x32_bf16 v[112:115], v[156:159], v[188:191], v[112:115]
	v_mfma_f32_16x16x32_bf16 v[108:111], v[164:167], v[188:191], v[108:111]
	v_mfma_f32_16x16x32_bf16 v[100:103], v[156:159], v[196:199], v[100:103]
	v_mfma_f32_16x16x32_bf16 v[96:99], v[164:167], v[196:199], v[96:99]
	v_mfma_f32_16x16x32_bf16 v[92:95], v[156:159], v[208:211], v[92:95]
	v_mfma_f32_16x16x32_bf16 v[84:87], v[164:167], v[208:211], v[84:87]
	v_mfma_f32_16x16x32_bf16 v[76:79], v[156:159], v[216:219], v[76:79]
	v_mfma_f32_16x16x32_bf16 v[68:71], v[164:167], v[216:219], v[68:71]
	v_mfma_f32_16x16x32_bf16 v[124:127], v[168:171], v[184:187], v[124:127]
	v_mfma_f32_16x16x32_bf16 v[120:123], v[176:179], v[184:187], v[120:123]
	v_mfma_f32_16x16x32_bf16 v[116:119], v[168:171], v[192:195], v[116:119]
	v_mfma_f32_16x16x32_bf16 v[104:107], v[176:179], v[192:195], v[104:107]
	v_mfma_f32_16x16x32_bf16 v[88:91], v[168:171], v[204:207], v[88:91]
	v_mfma_f32_16x16x32_bf16 v[80:83], v[176:179], v[204:207], v[80:83]
	v_mfma_f32_16x16x32_bf16 v[72:75], v[168:171], v[212:215], v[72:75]
	v_mfma_f32_16x16x32_bf16 v[64:67], v[176:179], v[212:215], v[64:67]
	v_mfma_f32_16x16x32_bf16 v[124:127], v[172:175], v[188:191], v[124:127]
	v_mfma_f32_16x16x32_bf16 v[120:123], v[180:183], v[188:191], v[120:123]
	v_mfma_f32_16x16x32_bf16 v[116:119], v[172:175], v[196:199], v[116:119]
	v_mfma_f32_16x16x32_bf16 v[104:107], v[180:183], v[196:199], v[104:107]
	v_mfma_f32_16x16x32_bf16 v[88:91], v[172:175], v[208:211], v[88:91]
	v_mfma_f32_16x16x32_bf16 v[80:83], v[180:183], v[208:211], v[80:83]
	v_mfma_f32_16x16x32_bf16 v[72:75], v[172:175], v[216:219], v[72:75]
	v_mfma_f32_16x16x32_bf16 v[64:67], v[180:183], v[216:219], v[64:67]
	s_barrier
	s_add_i32 s46, s43, s36
	v_lshl_add_u64 v[140:141], s[26:27], 0, v[130:131]
	s_mov_b32 m0, s46
	ds_read_b128 v[184:187], v149 offset:16384
	ds_read_b128 v[188:191], v149 offset:17408
	ds_read_b128 v[192:195], v149 offset:18432
	ds_read_b128 v[196:199], v149 offset:19456
	ds_read_b128 v[204:207], v149 offset:20480
	ds_read_b128 v[208:211], v149 offset:21504
	ds_read_b128 v[212:215], v149 offset:22528
	ds_read_b128 v[216:219], v149 offset:23552
	global_load_lds_dwordx4 v[140:141], off
	s_add_i32 m0, s46, 0x2000
	s_add_u32 s46, s26, 0x80000
	v_lshl_add_u64 v[200:201], s[26:27], 0, v[134:135]
	s_addc_u32 s47, s27, 0
	s_add_i32 s57, s44, s36
	global_load_lds_dwordx4 v[200:201], off
	v_lshl_add_u64 v[220:221], s[46:47], 0, v[130:131]
	s_mov_b32 m0, s57
	v_lshl_add_u64 v[222:223], s[28:29], 0, v[132:133]
	global_load_lds_dwordx4 v[220:221], off
	s_add_i32 m0, s57, 0x2000
	v_lshl_add_u64 v[220:221], s[46:47], 0, v[134:135]
	global_load_lds_dwordx4 v[220:221], off
	s_mov_b32 m0, s37
	v_lshl_add_u64 v[220:221], s[28:29], 0, v[128:129]
	global_load_lds_dwordx4 v[220:221], off
	s_mov_b32 m0, s38
	s_nop 0
	global_load_lds_dwordx4 v[222:223], off
	s_waitcnt vmcnt(8)
	s_waitcnt lgkmcnt(0)
	s_barrier
; #define PG8_STAGE(bufoff, gbase, voff) do { _Pragma("unroll") for (int _i = 0; _i < 2; ++_i) \
;         __builtin_amdgcn_global_load_lds((const unsigned*)((const char*)(gbase) + (voff)[_i]), (LAS unsigned*)(lds + (bufoff) + ldsw + _i * 8192), 16, 0, 0); } while (0)
; #define PG8_LDA(dst, b, h) do { _Pragma("unroll") for (int m = 0; m < 4; ++m) _Pragma("unroll") for (int k = 0; k < 2; ++k) dst[m][k] = *(const LAS bf16x8*)(lds + PG8_SA(b, h) + aoff + m * 2048 + k * 1024); } while (0)
; #define PG8_LDB(dst, b, h) do { _Pragma("unroll") for (int n = 0; n < 2; ++n) _Pragma("unroll") for (int k = 0; k < 2; ++k) dst[n][k] = *(const LAS bf16x8*)(lds + PG8_SB(b, h) + boff + n * 2048 + k * 1024); } while (0)
; #define PG8_MMA(ai, bj, At, Bt) do { __builtin_amdgcn_s_setprio(1); _Pragma("unroll") for (int m = 0; m < 4; ++m) _Pragma("unroll") for (int n = 0; n < 2; ++n) _Pragma("unroll") for (int k = 0; k < 2; ++k) \
;         acc[ai][bj][m][n] = __builtin_amdgcn_mfma_f32_16x16x32_bf16(Bt[n][k], At[m][k], acc[ai][bj][m][n], 0, 0, 0); __builtin_amdgcn_s_setprio(0); } while (0)
; #define PG8_WAIT_V(n) asm volatile("s_waitcnt vmcnt(" #n ")" ::: "memory")
; #define PG8_WAIT_L(n) asm volatile("s_waitcnt lgkmcnt(" #n ")" ::: "memory")
; #define PG8_BAR __builtin_amdgcn_s_barrier()
; #define PG8_SCHED __builtin_amdgcn_sched_barrier(0)
; template <class Epi, class Sched, bool ALIGN_EPI = true>
; __device__ __forceinline__ void gemm_phase(LAS unsigned char* lds, const Gemm g, const Sched& S, const Epi& E) {
;     ...
;             PG8_WAIT_V(8); PG8_WAIT_L(0); PG8_BAR; PG8_MMA(1, 0, At, B0); PG8_MMA(1, 1, At, B1); PG8_BAR; PG8_SCHED;
;             PG8_LDB(B0, 1, 0); PG8_LDB(B1, 1, 1); PG8_SCHED; PG8_LDA(At, 1, 0); PG8_STAGE(PG8_SA(0, 1), a2 + hstep, voffA);
;             PG8_WAIT_V(8); PG8_WAIT_L(0); PG8_BAR; PG8_MMA(0, 0, At, B0); PG8_MMA(0, 1, At, B1); PG8_BAR; PG8_SCHED;
	s_waitcnt lgkmcnt(0)
	v_mfma_f32_16x16x32_bf16 v[60:63], v[152:155], v[184:187], v[60:63]
	v_mfma_f32_16x16x32_bf16 v[52:55], v[160:163], v[184:187], v[52:55]
	v_mfma_f32_16x16x32_bf16 v[44:47], v[152:155], v[192:195], v[44:47]
	v_mfma_f32_16x16x32_bf16 v[36:39], v[160:163], v[192:195], v[36:39]
	v_mfma_f32_16x16x32_bf16 v[28:31], v[152:155], v[204:207], v[28:31]
	v_mfma_f32_16x16x32_bf16 v[20:23], v[160:163], v[204:207], v[20:23]
	v_mfma_f32_16x16x32_bf16 v[12:15], v[152:155], v[212:215], v[12:15]
	v_mfma_f32_16x16x32_bf16 v[4:7], v[160:163], v[212:215], v[4:7]
	v_mfma_f32_16x16x32_bf16 v[60:63], v[156:159], v[188:191], v[60:63]
	v_mfma_f32_16x16x32_bf16 v[52:55], v[164:167], v[188:191], v[52:55]
	v_mfma_f32_16x16x32_bf16 v[44:47], v[156:159], v[196:199], v[44:47]
	v_mfma_f32_16x16x32_bf16 v[36:39], v[164:167], v[196:199], v[36:39]
	v_mfma_f32_16x16x32_bf16 v[28:31], v[156:159], v[208:211], v[28:31]
	v_mfma_f32_16x16x32_bf16 v[20:23], v[164:167], v[208:211], v[20:23]
	v_mfma_f32_16x16x32_bf16 v[12:15], v[156:159], v[216:219], v[12:15]
	v_mfma_f32_16x16x32_bf16 v[4:7], v[164:167], v[216:219], v[4:7]
	v_mfma_f32_16x16x32_bf16 v[56:59], v[168:171], v[184:187], v[56:59]
	v_mfma_f32_16x16x32_bf16 v[48:51], v[176:179], v[184:187], v[48:51]
	v_mfma_f32_16x16x32_bf16 v[40:43], v[168:171], v[192:195], v[40:43]
	v_mfma_f32_16x16x32_bf16 v[32:35], v[176:179], v[192:195], v[32:35]
	v_mfma_f32_16x16x32_bf16 v[24:27], v[168:171], v[204:207], v[24:27]
	v_mfma_f32_16x16x32_bf16 v[16:19], v[176:179], v[204:207], v[16:19]
	v_mfma_f32_16x16x32_bf16 v[8:11], v[168:171], v[212:215], v[8:11]
	v_mfma_f32_16x16x32_bf16 v[0:3], v[176:179], v[212:215], v[0:3]
	v_mfma_f32_16x16x32_bf16 v[56:59], v[172:175], v[188:191], v[56:59]
	v_mfma_f32_16x16x32_bf16 v[48:51], v[180:183], v[188:191], v[48:51]
	v_mfma_f32_16x16x32_bf16 v[40:43], v[172:175], v[196:199], v[40:43]
	v_mfma_f32_16x16x32_bf16 v[32:35], v[180:183], v[196:199], v[32:35]
	v_mfma_f32_16x16x32_bf16 v[24:27], v[172:175], v[208:211], v[24:27]
	v_mfma_f32_16x16x32_bf16 v[16:19], v[180:183], v[208:211], v[16:19]
	v_mfma_f32_16x16x32_bf16 v[8:11], v[172:175], v[216:219], v[8:11]
	v_mfma_f32_16x16x32_bf16 v[0:3], v[180:183], v[216:219], v[0:3]
	s_barrier
	s_add_i32 s46, 0, 0x18000
	v_add_u32_e32 v151, s46, v145
	s_add_i32 s47, 0, 0x1c000
	ds_read_b128 v[152:155], v151
	ds_read_b128 v[156:159], v151 offset:1024
	ds_read_b128 v[160:163], v151 offset:2048
	ds_read_b128 v[164:167], v151 offset:3072
	v_add_u32_e32 v151, s47, v145
	ds_read_b128 v[168:171], v151
	ds_read_b128 v[172:175], v151 offset:1024
	ds_read_b128 v[176:179], v151 offset:2048
	ds_read_b128 v[180:183], v151 offset:3072
	s_add_u32 s28, s28, 0x80000
	s_addc_u32 s29, s29, 0
	s_mov_b32 m0, s39
	v_lshl_add_u64 v[224:225], s[28:29], 0, v[128:129]
	ds_read_b128 v[184:187], v149 offset:32768
	ds_read_b128 v[188:191], v149 offset:33792
	ds_read_b128 v[192:195], v149 offset:34816
	ds_read_b128 v[196:199], v149 offset:35840
	ds_read_b128 v[204:207], v149 offset:36864
	ds_read_b128 v[208:211], v149 offset:37888
	ds_read_b128 v[212:215], v149 offset:38912
	ds_read_b128 v[216:219], v149 offset:39936
	global_load_lds_dwordx4 v[224:225], off
	s_mov_b32 m0, s40
	v_lshl_add_u64 v[224:225], s[28:29], 0, v[132:133]
	global_load_lds_dwordx4 v[224:225], off
	s_waitcnt vmcnt(8)
	s_waitcnt lgkmcnt(0)
	s_barrier
	s_waitcnt lgkmcnt(0)
	v_mfma_f32_16x16x32_bf16 v[112:115], v[152:155], v[184:187], v[112:115]
	v_mfma_f32_16x16x32_bf16 v[108:111], v[160:163], v[184:187], v[108:111]
	v_mfma_f32_16x16x32_bf16 v[100:103], v[152:155], v[192:195], v[100:103]
	v_mfma_f32_16x16x32_bf16 v[96:99], v[160:163], v[192:195], v[96:99]
	v_mfma_f32_16x16x32_bf16 v[92:95], v[152:155], v[204:207], v[92:95]
	v_mfma_f32_16x16x32_bf16 v[84:87], v[160:163], v[204:207], v[84:87]
	v_mfma_f32_16x16x32_bf16 v[76:79], v[152:155], v[212:215], v[76:79]
	v_mfma_f32_16x16x32_bf16 v[68:71], v[160:163], v[212:215], v[68:71]
	v_mfma_f32_16x16x32_bf16 v[112:115], v[156:159], v[188:191], v[112:115]
	v_mfma_f32_16x16x32_bf16 v[108:111], v[164:167], v[188:191], v[108:111]
	v_mfma_f32_16x16x32_bf16 v[100:103], v[156:159], v[196:199], v[100:103]
	v_mfma_f32_16x16x32_bf16 v[96:99], v[164:167], v[196:199], v[96:99]
	v_mfma_f32_16x16x32_bf16 v[92:95], v[156:159], v[208:211], v[92:95]
	v_mfma_f32_16x16x32_bf16 v[84:87], v[164:167], v[208:211], v[84:87]
	v_mfma_f32_16x16x32_bf16 v[76:79], v[156:159], v[216:219], v[76:79]
	v_mfma_f32_16x16x32_bf16 v[68:71], v[164:167], v[216:219], v[68:71]
	v_mfma_f32_16x16x32_bf16 v[124:127], v[168:171], v[184:187], v[124:127]
	v_mfma_f32_16x16x32_bf16 v[120:123], v[176:179], v[184:187], v[120:123]
	v_mfma_f32_16x16x32_bf16 v[116:119], v[168:171], v[192:195], v[116:119]
	v_mfma_f32_16x16x32_bf16 v[104:107], v[176:179], v[192:195], v[104:107]
	v_mfma_f32_16x16x32_bf16 v[88:91], v[168:171], v[204:207], v[88:91]
	v_mfma_f32_16x16x32_bf16 v[80:83], v[176:179], v[204:207], v[80:83]
	v_mfma_f32_16x16x32_bf16 v[72:75], v[168:171], v[212:215], v[72:75]
	v_mfma_f32_16x16x32_bf16 v[64:67], v[176:179], v[212:215], v[64:67]
	v_mfma_f32_16x16x32_bf16 v[124:127], v[172:175], v[188:191], v[124:127]
	v_mfma_f32_16x16x32_bf16 v[120:123], v[180:183], v[188:191], v[120:123]
	v_mfma_f32_16x16x32_bf16 v[116:119], v[172:175], v[196:199], v[116:119]
	v_mfma_f32_16x16x32_bf16 v[104:107], v[180:183], v[196:199], v[104:107]
	v_mfma_f32_16x16x32_bf16 v[88:91], v[172:175], v[208:211], v[88:91]
	v_mfma_f32_16x16x32_bf16 v[80:83], v[180:183], v[208:211], v[80:83]
	v_mfma_f32_16x16x32_bf16 v[72:75], v[172:175], v[216:219], v[72:75]
	v_mfma_f32_16x16x32_bf16 v[64:67], v[180:183], v[216:219], v[64:67]
	s_barrier
; #define PG8_STAGE(bufoff, gbase, voff) do { _Pragma("unroll") for (int _i = 0; _i < 2; ++_i) \
;         __builtin_amdgcn_global_load_lds((const unsigned*)((const char*)(gbase) + (voff)[_i]), (LAS unsigned*)(lds + (bufoff) + ldsw + _i * 8192), 16, 0, 0); } while (0)
; #define PG8_LDA(dst, b, h) do { _Pragma("unroll") for (int m = 0; m < 4; ++m) _Pragma("unroll") for (int k = 0; k < 2; ++k) dst[m][k] = *(const LAS bf16x8*)(lds + PG8_SA(b, h) + aoff + m * 2048 + k * 1024); } while (0)
; #define PG8_MMA(ai, bj, At, Bt) do { __builtin_amdgcn_s_setprio(1); _Pragma("unroll") for (int m = 0; m < 4; ++m) _Pragma("unroll") for (int n = 0; n < 2; ++n) _Pragma("unroll") for (int k = 0; k < 2; ++k) \
;         acc[ai][bj][m][n] = __builtin_amdgcn_mfma_f32_16x16x32_bf16(Bt[n][k], At[m][k], acc[ai][bj][m][n], 0, 0, 0); __builtin_amdgcn_s_setprio(0); } while (0)
; #define PG8_WAIT_V(n) asm volatile("s_waitcnt vmcnt(" #n ")" ::: "memory")
; #define PG8_WAIT_L(n) asm volatile("s_waitcnt lgkmcnt(" #n ")" ::: "memory")
; #define PG8_BAR __builtin_amdgcn_s_barrier()
; #define PG8_SCHED __builtin_amdgcn_sched_barrier(0)
; template <class Epi, class Sched, bool ALIGN_EPI = true>
; __device__ __forceinline__ void gemm_phase(LAS unsigned char* lds, const Gemm g, const Sched& S, const Epi& E) {
;     ...
;             PG8_LDA(At, 1, 1); PG8_STAGE(PG8_SB(1, 0), b3, voffB); PG8_STAGE(PG8_SB(1, 1), b3 + hstep, voffB); PG8_STAGE(PG8_SA(1, 0), a3, voffA);
;             PG8_WAIT_V(8); PG8_WAIT_L(0); PG8_BAR; PG8_MMA(1, 0, At, B0); PG8_MMA(1, 1, At, B1); PG8_BAR; PG8_SCHED;
;         }
;         if constexpr (ALIGN_EPI) { if (wr == 0) PG8_BAR; }
	s_add_i32 s28, s46, s36
	v_lshl_add_u64 v[140:141], v[140:141], 0, s[18:19]
	s_mov_b32 m0, s28
	ds_read_b128 v[184:187], v149 offset:49152
	ds_read_b128 v[188:191], v149 offset:50176
	ds_read_b128 v[192:195], v149 offset:51200
	ds_read_b128 v[196:199], v149 offset:52224
	ds_read_b128 v[204:207], v149 offset:53248
	ds_read_b128 v[208:211], v149 offset:54272
	ds_read_b128 v[212:215], v149 offset:55296
	ds_read_b128 v[216:219], v149 offset:56320
	global_load_lds_dwordx4 v[140:141], off
	s_add_i32 m0, s28, 0x2000
	s_add_u32 s26, s26, 0x80080
	v_lshl_add_u64 v[140:141], v[200:201], 0, s[18:19]
	s_addc_u32 s27, s27, 0
	s_add_i32 s28, s47, s36
	global_load_lds_dwordx4 v[140:141], off
	s_mov_b32 m0, s28
	v_lshl_add_u64 v[140:141], s[26:27], 0, v[130:131]
	global_load_lds_dwordx4 v[140:141], off
	s_add_i32 m0, s28, 0x2000
	v_lshl_add_u64 v[140:141], s[26:27], 0, v[134:135]
	global_load_lds_dwordx4 v[140:141], off
	s_mov_b32 m0, s41
	v_lshl_add_u64 v[140:141], v[220:221], 0, s[18:19]
	global_load_lds_dwordx4 v[140:141], off
	s_mov_b32 m0, s42
	v_lshl_add_u64 v[140:141], v[222:223], 0, s[18:19]
	global_load_lds_dwordx4 v[140:141], off
	s_waitcnt vmcnt(8)
	s_waitcnt lgkmcnt(0)
	s_barrier
	s_waitcnt lgkmcnt(0)
	v_mfma_f32_16x16x32_bf16 v[60:63], v[152:155], v[184:187], v[60:63]
	v_mfma_f32_16x16x32_bf16 v[52:55], v[160:163], v[184:187], v[52:55]
	v_mfma_f32_16x16x32_bf16 v[44:47], v[152:155], v[192:195], v[44:47]
	v_mfma_f32_16x16x32_bf16 v[36:39], v[160:163], v[192:195], v[36:39]
	v_mfma_f32_16x16x32_bf16 v[28:31], v[152:155], v[204:207], v[28:31]
	v_mfma_f32_16x16x32_bf16 v[20:23], v[160:163], v[204:207], v[20:23]
	v_mfma_f32_16x16x32_bf16 v[12:15], v[152:155], v[212:215], v[12:15]
	v_mfma_f32_16x16x32_bf16 v[4:7], v[160:163], v[212:215], v[4:7]
	v_mfma_f32_16x16x32_bf16 v[60:63], v[156:159], v[188:191], v[60:63]
	v_mfma_f32_16x16x32_bf16 v[52:55], v[164:167], v[188:191], v[52:55]
	v_mfma_f32_16x16x32_bf16 v[44:47], v[156:159], v[196:199], v[44:47]
	v_mfma_f32_16x16x32_bf16 v[36:39], v[164:167], v[196:199], v[36:39]
	v_mfma_f32_16x16x32_bf16 v[28:31], v[156:159], v[208:211], v[28:31]
	v_mfma_f32_16x16x32_bf16 v[20:23], v[164:167], v[208:211], v[20:23]
	v_mfma_f32_16x16x32_bf16 v[12:15], v[156:159], v[216:219], v[12:15]
	v_mfma_f32_16x16x32_bf16 v[4:7], v[164:167], v[216:219], v[4:7]
	v_mfma_f32_16x16x32_bf16 v[56:59], v[168:171], v[184:187], v[56:59]
	v_mfma_f32_16x16x32_bf16 v[48:51], v[176:179], v[184:187], v[48:51]
	v_mfma_f32_16x16x32_bf16 v[40:43], v[168:171], v[192:195], v[40:43]
	v_mfma_f32_16x16x32_bf16 v[32:35], v[176:179], v[192:195], v[32:35]
	v_mfma_f32_16x16x32_bf16 v[24:27], v[168:171], v[204:207], v[24:27]
	v_mfma_f32_16x16x32_bf16 v[16:19], v[176:179], v[204:207], v[16:19]
	v_mfma_f32_16x16x32_bf16 v[8:11], v[168:171], v[212:215], v[8:11]
	v_mfma_f32_16x16x32_bf16 v[0:3], v[176:179], v[212:215], v[0:3]
	v_mfma_f32_16x16x32_bf16 v[56:59], v[172:175], v[188:191], v[56:59]
	v_mfma_f32_16x16x32_bf16 v[48:51], v[180:183], v[188:191], v[48:51]
	v_mfma_f32_16x16x32_bf16 v[40:43], v[172:175], v[196:199], v[40:43]
	v_mfma_f32_16x16x32_bf16 v[32:35], v[180:183], v[196:199], v[32:35]
	v_mfma_f32_16x16x32_bf16 v[24:27], v[172:175], v[208:211], v[24:27]
	v_mfma_f32_16x16x32_bf16 v[16:19], v[180:183], v[208:211], v[16:19]
	v_mfma_f32_16x16x32_bf16 v[8:11], v[172:175], v[216:219], v[8:11]
	v_mfma_f32_16x16x32_bf16 v[0:3], v[180:183], v[216:219], v[0:3]
	s_barrier
	s_add_i32 s56, s56, 2
	s_add_u32 s24, s24, 0x100
	s_addc_u32 s25, s25, 0
	s_add_u32 s54, s54, 0x100
	s_addc_u32 s55, s55, 0
	s_cmp_gt_u32 s56, 29
	s_cbranch_scc0 .LBB0_647
	s_and_b64 vcc, exec, s[20:21]
	s_cbranch_vccz .LBB0_650
	s_barrier

; #define PG8_STAGE(bufoff, gbase, voff) do { _Pragma("unroll") for (int _i = 0; _i < 2; ++_i) \
;         __builtin_amdgcn_global_load_lds((const unsigned*)((const char*)(gbase) + (voff)[_i]), (LAS unsigned*)(lds + (bufoff) + ldsw + _i * 8192), 16, 0, 0); } while (0)
; #define PG8_LDA(dst, b, h) do { _Pragma("unroll") for (int m = 0; m < 4; ++m) _Pragma("unroll") for (int k = 0; k < 2; ++k) dst[m][k] = *(const LAS bf16x8*)(lds + PG8_SA(b, h) + aoff + m * 2048 + k * 1024); } while (0)
; #define PG8_LDB(dst, b, h) do { _Pragma("unroll") for (int n = 0; n < 2; ++n) _Pragma("unroll") for (int k = 0; k < 2; ++k) dst[n][k] = *(const LAS bf16x8*)(lds + PG8_SB(b, h) + boff + n * 2048 + k * 1024); } while (0)
; #define PG8_MMA(ai, bj, At, Bt) do { __builtin_amdgcn_s_setprio(1); _Pragma("unroll") for (int m = 0; m < 4; ++m) _Pragma("unroll") for (int n = 0; n < 2; ++n) _Pragma("unroll") for (int k = 0; k < 2; ++k) \
;         acc[ai][bj][m][n] = __builtin_amdgcn_mfma_f32_16x16x32_bf16(Bt[n][k], At[m][k], acc[ai][bj][m][n], 0, 0, 0); __builtin_amdgcn_s_setprio(0); } while (0)
; #define PG8_BAR __builtin_amdgcn_s_barrier()
; template <class Epi, class Sched, bool ALIGN_EPI = true>
; __device__ __forceinline__ void gemm_phase(LAS unsigned char* lds, const Gemm g, const Sched& S, const Epi& E) {
;     ...
;         const bool has_next = PG8_NEXT(ui + 1, nxt);
;         const char* nA = has_next ? (const char*)g.A + (size_t)nxt.pm * tstep : cA; const char* nB = has_next ? (const char*)g.Bt + (size_t)nxt.pn * tstep : cB;
;         for (int t = 0; t < nt; t += 2) {
;             const bool last = (t == nt - 2);
;             const char* a1 = cA + (size_t)(t + 1) * kstep;
;             const char* a2 = last ? nA : cA + (size_t)(t + 2) * kstep; const char* b2 = last ? nB : cB + (size_t)(t + 2) * kstep;
;             const char* a3 = a2 + kstep; const char* b3 = b2 + kstep;
;             PG8_LDB(B0, 0, 0); PG8_LDB(B1, 0, 1); PG8_SCHED; PG8_LDA(At, 0, 0); PG8_STAGE(PG8_SA(1, 1), a1 + hstep, voffA);
;             PG8_WAIT_V(8); PG8_WAIT_L(0); PG8_BAR; PG8_MMA(0, 0, At, B0); PG8_MMA(0, 1, At, B1); PG8_BAR; PG8_SCHED;
;             PG8_LDA(At, 0, 1); PG8_STAGE(PG8_SB(0, 0), b2, voffB); PG8_STAGE(PG8_SB(0, 1), b2 + hstep, voffB); PG8_STAGE(PG8_SA(0, 0), a2, voffA);
;             PG8_WAIT_V(8); PG8_WAIT_L(0); PG8_BAR; PG8_MMA(1, 0, At, B0); PG8_MMA(1, 1, At, B1); PG8_BAR; PG8_SCHED;
.LBB0_667:
	v_readlane_b32 s14, v137, s56
	ds_read_b128 v[0:3], v140
	ds_read_b128 v[4:7], v140 offset:1024
	ds_read_b128 v[8:11], v140 offset:2048
	ds_read_b128 v[12:15], v140 offset:3072
	ds_read_b128 v[16:19], v141
	ds_read_b128 v[20:23], v141 offset:1024
	ds_read_b128 v[24:27], v141 offset:2048
	ds_read_b128 v[28:31], v141 offset:3072
	s_cmp_gt_i32 s14, -1
	s_mov_b64 s[48:49], s[6:7]
	s_cselect_b64 s[38:39], -1, 0
	s_lshl_b64 s[6:7], s[14:15], 17
	s_add_u32 s36, s3, s6
	s_addc_u32 s37, s50, s7
	v_readlane_b32 s34, v136, s56
	s_and_b64 s[6:7], s[38:39], exec
	s_cselect_b32 s45, s37, s43
	s_cselect_b32 s44, s36, s42
	s_ashr_i32 s35, s34, 31
	s_lshl_b64 s[6:7], s[34:35], 17
	s_add_u32 s6, s51, s6
	s_addc_u32 s7, s52, s7
	s_and_b64 s[40:41], s[38:39], exec
	s_cselect_b32 s41, s7, s49
	s_cselect_b32 s40, s6, s48
	s_add_u32 s46, s42, 0x10080
	s_addc_u32 s47, s43, 0
	s_mov_b32 m0, s59
	v_lshl_add_u64 v[64:65], s[46:47], 0, v[128:129]
	ds_read_b128 v[32:35], v142
	ds_read_b128 v[36:39], v142 offset:1024
	ds_read_b128 v[40:43], v142 offset:2048
	ds_read_b128 v[44:47], v142 offset:3072
	ds_read_b128 v[48:51], v142 offset:4096
	ds_read_b128 v[52:55], v142 offset:5120
	ds_read_b128 v[56:59], v142 offset:6144
	ds_read_b128 v[60:63], v142 offset:7168
	global_load_lds_dwordx4 v[64:65], off
	s_mov_b32 m0, s60
	v_lshl_add_u64 v[64:65], s[46:47], 0, v[132:133]
	global_load_lds_dwordx4 v[64:65], off
	s_waitcnt vmcnt(8)
	s_waitcnt lgkmcnt(0)
	s_barrier
	s_waitcnt lgkmcnt(0)
	v_mfma_f32_16x16x32_bf16 v[64:67], v[0:3], v[32:35], 0
	v_mfma_f32_16x16x32_bf16 v[68:71], v[8:11], v[32:35], 0
	v_mfma_f32_16x16x32_bf16 v[72:75], v[0:3], v[40:43], 0
	v_mfma_f32_16x16x32_bf16 v[76:79], v[8:11], v[40:43], 0
	v_mfma_f32_16x16x32_bf16 v[80:83], v[0:3], v[48:51], 0
	v_mfma_f32_16x16x32_bf16 v[84:87], v[8:11], v[48:51], 0
	v_mfma_f32_16x16x32_bf16 v[88:91], v[0:3], v[56:59], 0
	v_mfma_f32_16x16x32_bf16 v[92:95], v[8:11], v[56:59], 0
	v_mfma_f32_16x16x32_bf16 v[64:67], v[4:7], v[36:39], v[64:67]
	v_mfma_f32_16x16x32_bf16 v[68:71], v[12:15], v[36:39], v[68:71]
	v_mfma_f32_16x16x32_bf16 v[72:75], v[4:7], v[44:47], v[72:75]
	v_mfma_f32_16x16x32_bf16 v[76:79], v[12:15], v[44:47], v[76:79]
	v_mfma_f32_16x16x32_bf16 v[80:83], v[4:7], v[52:55], v[80:83]
	v_mfma_f32_16x16x32_bf16 v[84:87], v[12:15], v[52:55], v[84:87]
	v_mfma_f32_16x16x32_bf16 v[88:91], v[4:7], v[60:63], v[88:91]
	v_mfma_f32_16x16x32_bf16 v[92:95], v[12:15], v[60:63], v[92:95]
	v_mfma_f32_16x16x32_bf16 v[96:99], v[16:19], v[32:35], 0
	v_mfma_f32_16x16x32_bf16 v[32:35], v[24:27], v[32:35], 0
	v_mfma_f32_16x16x32_bf16 v[96:99], v[20:23], v[36:39], v[96:99]
	v_mfma_f32_16x16x32_bf16 v[32:35], v[28:31], v[36:39], v[32:35]
	v_mfma_f32_16x16x32_bf16 v[36:39], v[16:19], v[40:43], 0
	v_mfma_f32_16x16x32_bf16 v[40:43], v[24:27], v[40:43], 0
	v_mfma_f32_16x16x32_bf16 v[36:39], v[20:23], v[44:47], v[36:39]
	v_mfma_f32_16x16x32_bf16 v[40:43], v[28:31], v[44:47], v[40:43]
	v_mfma_f32_16x16x32_bf16 v[44:47], v[16:19], v[48:51], 0
	v_mfma_f32_16x16x32_bf16 v[48:51], v[24:27], v[48:51], 0
	v_mfma_f32_16x16x32_bf16 v[44:47], v[20:23], v[52:55], v[44:47]
	v_mfma_f32_16x16x32_bf16 v[48:51], v[28:31], v[52:55], v[48:51]
	v_mfma_f32_16x16x32_bf16 v[52:55], v[16:19], v[56:59], 0
	v_mfma_f32_16x16x32_bf16 v[56:59], v[24:27], v[56:59], 0
	v_mfma_f32_16x16x32_bf16 v[52:55], v[20:23], v[60:63], v[52:55]
	v_mfma_f32_16x16x32_bf16 v[56:59], v[28:31], v[60:63], v[56:59]
	s_barrier
	v_lshl_add_u64 v[212:213], s[48:49], 0, v[130:131]
	s_mov_b32 m0, s61
	v_lshl_add_u64 v[146:147], v[212:213], 0, s[16:17]
	v_lshl_add_u64 v[214:215], s[48:49], 0, v[134:135]
	s_add_u32 s46, s48, 0x10100
	ds_read_b128 v[60:63], v142 offset:16384
	ds_read_b128 v[100:103], v142 offset:17408
	ds_read_b128 v[104:107], v142 offset:18432
	ds_read_b128 v[108:111], v142 offset:19456
	ds_read_b128 v[112:115], v142 offset:20480
	ds_read_b128 v[116:119], v142 offset:21504
	ds_read_b128 v[120:123], v142 offset:22528
	ds_read_b128 v[124:127], v142 offset:23552
	global_load_lds_dwordx4 v[146:147], off
	v_lshl_add_u64 v[146:147], v[214:215], 0, s[16:17]
	s_mov_b32 m0, s62
	s_addc_u32 s47, s49, 0
	global_load_lds_dwordx4 v[146:147], off
	v_lshl_add_u64 v[146:147], s[46:47], 0, v[130:131]
	s_mov_b32 m0, s63
	v_lshl_add_u64 v[216:217], s[42:43], 0, v[128:129]
	global_load_lds_dwordx4 v[146:147], off
	v_lshl_add_u64 v[146:147], s[46:47], 0, v[134:135]
	s_mov_b32 m0, s76
	v_lshl_add_u64 v[218:219], s[42:43], 0, v[132:133]
	global_load_lds_dwordx4 v[146:147], off
	s_mov_b32 m0, s23
	v_lshl_add_u64 v[146:147], v[216:217], 0, s[16:17]
	global_load_lds_dwordx4 v[146:147], off
	s_mov_b32 m0, s53
	v_lshl_add_u64 v[146:147], v[218:219], 0, s[16:17]
	global_load_lds_dwordx4 v[146:147], off
	s_waitcnt vmcnt(8)
	s_waitcnt lgkmcnt(0)
	s_barrier
; #define PG8_STAGE(bufoff, gbase, voff) do { _Pragma("unroll") for (int _i = 0; _i < 2; ++_i) \
;         __builtin_amdgcn_global_load_lds((const unsigned*)((const char*)(gbase) + (voff)[_i]), (LAS unsigned*)(lds + (bufoff) + ldsw + _i * 8192), 16, 0, 0); } while (0)
; #define PG8_LDA(dst, b, h) do { _Pragma("unroll") for (int m = 0; m < 4; ++m) _Pragma("unroll") for (int k = 0; k < 2; ++k) dst[m][k] = *(const LAS bf16x8*)(lds + PG8_SA(b, h) + aoff + m * 2048 + k * 1024); } while (0)
; #define PG8_LDB(dst, b, h) do { _Pragma("unroll") for (int n = 0; n < 2; ++n) _Pragma("unroll") for (int k = 0; k < 2; ++k) dst[n][k] = *(const LAS bf16x8*)(lds + PG8_SB(b, h) + boff + n * 2048 + k * 1024); } while (0)
; #define PG8_MMA(ai, bj, At, Bt) do { __builtin_amdgcn_s_setprio(1); _Pragma("unroll") for (int m = 0; m < 4; ++m) _Pragma("unroll") for (int n = 0; n < 2; ++n) _Pragma("unroll") for (int k = 0; k < 2; ++k) \
;         acc[ai][bj][m][n] = __builtin_amdgcn_mfma_f32_16x16x32_bf16(Bt[n][k], At[m][k], acc[ai][bj][m][n], 0, 0, 0); __builtin_amdgcn_s_setprio(0); } while (0)
; #define PG8_WAIT_V(n) asm volatile("s_waitcnt vmcnt(" #n ")" ::: "memory")
; #define PG8_WAIT_L(n) asm volatile("s_waitcnt lgkmcnt(" #n ")" ::: "memory")
; #define PG8_BAR __builtin_amdgcn_s_barrier()
; #define PG8_SCHED __builtin_amdgcn_sched_barrier(0)
; template <class Epi, class Sched, bool ALIGN_EPI = true>
; __device__ __forceinline__ void gemm_phase(LAS unsigned char* lds, const Gemm g, const Sched& S, const Epi& E) {
;     ...
;             PG8_WAIT_V(8); PG8_WAIT_L(0); PG8_BAR; PG8_MMA(1, 0, At, B0); PG8_MMA(1, 1, At, B1); PG8_BAR; PG8_SCHED;
;             PG8_LDB(B0, 1, 0); PG8_LDB(B1, 1, 1); PG8_SCHED; PG8_LDA(At, 1, 0); PG8_STAGE(PG8_SA(0, 1), a2 + hstep, voffA);
;             PG8_WAIT_V(8); PG8_WAIT_L(0); PG8_BAR; PG8_MMA(0, 0, At, B0); PG8_MMA(0, 1, At, B1); PG8_BAR; PG8_SCHED;
	s_waitcnt lgkmcnt(0)
	v_mfma_f32_16x16x32_bf16 v[146:149], v[0:3], v[60:63], 0
	v_mfma_f32_16x16x32_bf16 v[154:157], v[0:3], v[104:107], 0
	v_mfma_f32_16x16x32_bf16 v[162:165], v[0:3], v[112:115], 0
	v_mfma_f32_16x16x32_bf16 v[0:3], v[0:3], v[120:123], 0
	v_mfma_f32_16x16x32_bf16 v[146:149], v[4:7], v[100:103], v[146:149]
	v_mfma_f32_16x16x32_bf16 v[154:157], v[4:7], v[108:111], v[154:157]
	v_mfma_f32_16x16x32_bf16 v[162:165], v[4:7], v[116:119], v[162:165]
	v_mfma_f32_16x16x32_bf16 v[0:3], v[4:7], v[124:127], v[0:3]
	v_mfma_f32_16x16x32_bf16 v[4:7], v[8:11], v[120:123], 0
	v_mfma_f32_16x16x32_bf16 v[150:153], v[8:11], v[60:63], 0
	v_mfma_f32_16x16x32_bf16 v[158:161], v[8:11], v[104:107], 0
	v_mfma_f32_16x16x32_bf16 v[166:169], v[8:11], v[112:115], 0
	v_mfma_f32_16x16x32_bf16 v[4:7], v[12:15], v[124:127], v[4:7]
	v_mfma_f32_16x16x32_bf16 v[150:153], v[12:15], v[100:103], v[150:153]
	v_mfma_f32_16x16x32_bf16 v[158:161], v[12:15], v[108:111], v[158:161]
	v_mfma_f32_16x16x32_bf16 v[166:169], v[12:15], v[116:119], v[166:169]
	v_mfma_f32_16x16x32_bf16 v[8:11], v[16:19], v[60:63], 0
	v_mfma_f32_16x16x32_bf16 v[12:15], v[24:27], v[60:63], 0
	v_mfma_f32_16x16x32_bf16 v[8:11], v[20:23], v[100:103], v[8:11]
	v_mfma_f32_16x16x32_bf16 v[12:15], v[28:31], v[100:103], v[12:15]
	v_mfma_f32_16x16x32_bf16 v[60:63], v[16:19], v[104:107], 0
	v_mfma_f32_16x16x32_bf16 v[100:103], v[24:27], v[104:107], 0
	v_mfma_f32_16x16x32_bf16 v[104:107], v[16:19], v[112:115], 0
	v_mfma_f32_16x16x32_bf16 v[16:19], v[16:19], v[120:123], 0
	v_mfma_f32_16x16x32_bf16 v[60:63], v[20:23], v[108:111], v[60:63]
	v_mfma_f32_16x16x32_bf16 v[100:103], v[28:31], v[108:111], v[100:103]
	v_mfma_f32_16x16x32_bf16 v[104:107], v[20:23], v[116:119], v[104:107]
	v_mfma_f32_16x16x32_bf16 v[108:111], v[24:27], v[112:115], 0
	v_mfma_f32_16x16x32_bf16 v[16:19], v[20:23], v[124:127], v[16:19]
	v_mfma_f32_16x16x32_bf16 v[20:23], v[24:27], v[120:123], 0
	v_mfma_f32_16x16x32_bf16 v[108:111], v[28:31], v[116:119], v[108:111]
	v_mfma_f32_16x16x32_bf16 v[20:23], v[28:31], v[124:127], v[20:23]
	s_barrier
	ds_read_b128 v[24:27], v143
	ds_read_b128 v[28:31], v143 offset:1024
	ds_read_b128 v[112:115], v143 offset:2048
	ds_read_b128 v[116:119], v143 offset:3072
	ds_read_b128 v[120:123], v144
	ds_read_b128 v[124:127], v144 offset:1024
	ds_read_b128 v[170:173], v144 offset:2048
	ds_read_b128 v[174:177], v144 offset:3072
	s_add_u32 s46, s42, 0x10100
	s_addc_u32 s47, s43, 0
	s_mov_b32 m0, s54
	v_lshl_add_u64 v[220:221], s[46:47], 0, v[128:129]
	ds_read_b128 v[178:181], v142 offset:32768
	ds_read_b128 v[182:185], v142 offset:33792
	ds_read_b128 v[186:189], v142 offset:34816
	ds_read_b128 v[190:193], v142 offset:35840
	ds_read_b128 v[194:197], v142 offset:36864
	ds_read_b128 v[198:201], v142 offset:37888
	ds_read_b128 v[204:207], v142 offset:38912
	ds_read_b128 v[208:211], v142 offset:39936
	global_load_lds_dwordx4 v[220:221], off
	s_mov_b32 m0, s55
	v_lshl_add_u64 v[220:221], s[46:47], 0, v[132:133]
	global_load_lds_dwordx4 v[220:221], off
	s_waitcnt vmcnt(8)
	s_waitcnt lgkmcnt(0)
	s_barrier
	s_waitcnt lgkmcnt(0)
	v_mfma_f32_16x16x32_bf16 v[64:67], v[24:27], v[178:181], v[64:67]
	v_mfma_f32_16x16x32_bf16 v[68:71], v[112:115], v[178:181], v[68:71]
	v_mfma_f32_16x16x32_bf16 v[72:75], v[24:27], v[186:189], v[72:75]
	v_mfma_f32_16x16x32_bf16 v[76:79], v[112:115], v[186:189], v[76:79]
	v_mfma_f32_16x16x32_bf16 v[80:83], v[24:27], v[194:197], v[80:83]
	v_mfma_f32_16x16x32_bf16 v[84:87], v[112:115], v[194:197], v[84:87]
	v_mfma_f32_16x16x32_bf16 v[88:91], v[24:27], v[204:207], v[88:91]
	v_mfma_f32_16x16x32_bf16 v[92:95], v[112:115], v[204:207], v[92:95]
	v_mfma_f32_16x16x32_bf16 v[64:67], v[28:31], v[182:185], v[64:67]
	v_mfma_f32_16x16x32_bf16 v[68:71], v[116:119], v[182:185], v[68:71]
	v_mfma_f32_16x16x32_bf16 v[72:75], v[28:31], v[190:193], v[72:75]
	v_mfma_f32_16x16x32_bf16 v[76:79], v[116:119], v[190:193], v[76:79]
	v_mfma_f32_16x16x32_bf16 v[80:83], v[28:31], v[198:201], v[80:83]
	v_mfma_f32_16x16x32_bf16 v[84:87], v[116:119], v[198:201], v[84:87]
	v_mfma_f32_16x16x32_bf16 v[88:91], v[28:31], v[208:211], v[88:91]
	v_mfma_f32_16x16x32_bf16 v[92:95], v[116:119], v[208:211], v[92:95]
	v_mfma_f32_16x16x32_bf16 v[96:99], v[120:123], v[178:181], v[96:99]
	v_mfma_f32_16x16x32_bf16 v[32:35], v[170:173], v[178:181], v[32:35]
	v_mfma_f32_16x16x32_bf16 v[36:39], v[120:123], v[186:189], v[36:39]
	v_mfma_f32_16x16x32_bf16 v[40:43], v[170:173], v[186:189], v[40:43]
	v_mfma_f32_16x16x32_bf16 v[44:47], v[120:123], v[194:197], v[44:47]
	v_mfma_f32_16x16x32_bf16 v[48:51], v[170:173], v[194:197], v[48:51]
	v_mfma_f32_16x16x32_bf16 v[52:55], v[120:123], v[204:207], v[52:55]
	v_mfma_f32_16x16x32_bf16 v[56:59], v[170:173], v[204:207], v[56:59]
	v_mfma_f32_16x16x32_bf16 v[96:99], v[124:127], v[182:185], v[96:99]
	v_mfma_f32_16x16x32_bf16 v[32:35], v[174:177], v[182:185], v[32:35]
	v_mfma_f32_16x16x32_bf16 v[36:39], v[124:127], v[190:193], v[36:39]
	v_mfma_f32_16x16x32_bf16 v[40:43], v[174:177], v[190:193], v[40:43]
	v_mfma_f32_16x16x32_bf16 v[44:47], v[124:127], v[198:201], v[44:47]
	v_mfma_f32_16x16x32_bf16 v[48:51], v[174:177], v[198:201], v[48:51]
	v_mfma_f32_16x16x32_bf16 v[52:55], v[124:127], v[208:211], v[52:55]
	v_mfma_f32_16x16x32_bf16 v[56:59], v[174:177], v[208:211], v[56:59]
	s_barrier
; #define PG8_STAGE(bufoff, gbase, voff) do { _Pragma("unroll") for (int _i = 0; _i < 2; ++_i) \
;         __builtin_amdgcn_global_load_lds((const unsigned*)((const char*)(gbase) + (voff)[_i]), (LAS unsigned*)(lds + (bufoff) + ldsw + _i * 8192), 16, 0, 0); } while (0)
; #define PG8_LDA(dst, b, h) do { _Pragma("unroll") for (int m = 0; m < 4; ++m) _Pragma("unroll") for (int k = 0; k < 2; ++k) dst[m][k] = *(const LAS bf16x8*)(lds + PG8_SA(b, h) + aoff + m * 2048 + k * 1024); } while (0)
; #define PG8_LDB(dst, b, h) do { _Pragma("unroll") for (int n = 0; n < 2; ++n) _Pragma("unroll") for (int k = 0; k < 2; ++k) dst[n][k] = *(const LAS bf16x8*)(lds + PG8_SB(b, h) + boff + n * 2048 + k * 1024); } while (0)
; #define PG8_MMA(ai, bj, At, Bt) do { __builtin_amdgcn_s_setprio(1); _Pragma("unroll") for (int m = 0; m < 4; ++m) _Pragma("unroll") for (int n = 0; n < 2; ++n) _Pragma("unroll") for (int k = 0; k < 2; ++k) \
;         acc[ai][bj][m][n] = __builtin_amdgcn_mfma_f32_16x16x32_bf16(Bt[n][k], At[m][k], acc[ai][bj][m][n], 0, 0, 0); __builtin_amdgcn_s_setprio(0); } while (0)
; #define PG8_WAIT_V(n) asm volatile("s_waitcnt vmcnt(" #n ")" ::: "memory")
; template <class Epi, class Sched, bool ALIGN_EPI = true>
; __device__ __forceinline__ void gemm_phase(LAS unsigned char* lds, const Gemm g, const Sched& S, const Epi& E) {
;     ...
;             PG8_LDB(B0, 0, 0); PG8_LDB(B1, 0, 1); PG8_SCHED; PG8_LDA(At, 0, 0); PG8_STAGE(PG8_SA(1, 1), a1 + hstep, voffA);
;             PG8_WAIT_V(8); PG8_WAIT_L(0); PG8_BAR; PG8_MMA(0, 0, At, B0); PG8_MMA(0, 1, At, B1); PG8_BAR; PG8_SCHED;
;             PG8_LDA(At, 0, 1); PG8_STAGE(PG8_SB(0, 0), b2, voffB); PG8_STAGE(PG8_SB(0, 1), b2 + hstep, voffB); PG8_STAGE(PG8_SA(0, 0), a2, voffA);
;             PG8_WAIT_V(8); PG8_WAIT_L(0); PG8_BAR; PG8_MMA(1, 0, At, B0); PG8_MMA(1, 1, At, B1); PG8_BAR; PG8_SCHED;
;             PG8_LDB(B0, 1, 0); PG8_LDB(B1, 1, 1); PG8_SCHED; PG8_LDA(At, 1, 0); PG8_STAGE(PG8_SA(0, 1), a2 + hstep, voffA);
;             PG8_WAIT_V(8); PG8_WAIT_L(0); PG8_BAR; PG8_MMA(0, 0, At, B0); PG8_MMA(0, 1, At, B1); PG8_BAR; PG8_SCHED;
;             PG8_LDA(At, 1, 1); PG8_STAGE(PG8_SB(1, 0), b3, voffB); PG8_STAGE(PG8_SB(1, 1), b3 + hstep, voffB); PG8_STAGE(PG8_SA(1, 0), a3, voffA);
;             PG8_WAIT_V(8); PG8_WAIT_L(0); PG8_BAR; PG8_MMA(1, 0, At, B0); PG8_MMA(1, 1, At, B1); PG8_BAR; PG8_SCHED;
	s_mov_b32 m0, s77
	v_lshl_add_u64 v[212:213], v[212:213], 0, s[18:19]
	s_add_u32 s46, s48, 0x10180
	ds_read_b128 v[178:181], v142 offset:49152
	ds_read_b128 v[182:185], v142 offset:50176
	ds_read_b128 v[186:189], v142 offset:51200
	ds_read_b128 v[190:193], v142 offset:52224
	ds_read_b128 v[194:197], v142 offset:53248
	ds_read_b128 v[198:201], v142 offset:54272
	ds_read_b128 v[204:207], v142 offset:55296
	ds_read_b128 v[208:211], v142 offset:56320
	global_load_lds_dwordx4 v[212:213], off
	v_lshl_add_u64 v[212:213], v[214:215], 0, s[18:19]
	s_mov_b32 m0, s78
	s_addc_u32 s47, s49, 0
	global_load_lds_dwordx4 v[212:213], off
	s_mov_b32 m0, s79
	v_lshl_add_u64 v[212:213], s[46:47], 0, v[130:131]
	global_load_lds_dwordx4 v[212:213], off
	s_mov_b32 m0, s80
	v_lshl_add_u64 v[212:213], s[46:47], 0, v[134:135]
	global_load_lds_dwordx4 v[212:213], off
	s_mov_b32 m0, s57
	v_lshl_add_u64 v[212:213], v[216:217], 0, s[18:19]
	global_load_lds_dwordx4 v[212:213], off
	s_mov_b32 m0, s58
	v_lshl_add_u64 v[212:213], v[218:219], 0, s[18:19]
	global_load_lds_dwordx4 v[212:213], off
	s_waitcnt vmcnt(8)
	s_waitcnt lgkmcnt(0)
	s_barrier
	s_waitcnt lgkmcnt(0)
	v_mfma_f32_16x16x32_bf16 v[0:3], v[24:27], v[204:207], v[0:3]
	v_mfma_f32_16x16x32_bf16 v[4:7], v[112:115], v[204:207], v[4:7]
	v_mfma_f32_16x16x32_bf16 v[146:149], v[24:27], v[178:181], v[146:149]
	v_mfma_f32_16x16x32_bf16 v[150:153], v[112:115], v[178:181], v[150:153]
	v_mfma_f32_16x16x32_bf16 v[154:157], v[24:27], v[186:189], v[154:157]
	v_mfma_f32_16x16x32_bf16 v[158:161], v[112:115], v[186:189], v[158:161]
	v_mfma_f32_16x16x32_bf16 v[162:165], v[24:27], v[194:197], v[162:165]
	v_mfma_f32_16x16x32_bf16 v[166:169], v[112:115], v[194:197], v[166:169]
	v_mfma_f32_16x16x32_bf16 v[0:3], v[28:31], v[208:211], v[0:3]
	v_mfma_f32_16x16x32_bf16 v[4:7], v[116:119], v[208:211], v[4:7]
	v_mfma_f32_16x16x32_bf16 v[146:149], v[28:31], v[182:185], v[146:149]
	v_mfma_f32_16x16x32_bf16 v[150:153], v[116:119], v[182:185], v[150:153]
	v_mfma_f32_16x16x32_bf16 v[154:157], v[28:31], v[190:193], v[154:157]
	v_mfma_f32_16x16x32_bf16 v[158:161], v[116:119], v[190:193], v[158:161]
	v_mfma_f32_16x16x32_bf16 v[162:165], v[28:31], v[198:201], v[162:165]
	v_mfma_f32_16x16x32_bf16 v[166:169], v[116:119], v[198:201], v[166:169]
	v_mfma_f32_16x16x32_bf16 v[8:11], v[120:123], v[178:181], v[8:11]
	v_mfma_f32_16x16x32_bf16 v[12:15], v[170:173], v[178:181], v[12:15]
	v_mfma_f32_16x16x32_bf16 v[24:27], v[120:123], v[186:189], v[60:63]
	v_mfma_f32_16x16x32_bf16 v[28:31], v[170:173], v[186:189], v[100:103]
	v_mfma_f32_16x16x32_bf16 v[60:63], v[120:123], v[194:197], v[104:107]
	v_mfma_f32_16x16x32_bf16 v[100:103], v[170:173], v[194:197], v[108:111]
	v_mfma_f32_16x16x32_bf16 v[16:19], v[120:123], v[204:207], v[16:19]
	v_mfma_f32_16x16x32_bf16 v[20:23], v[170:173], v[204:207], v[20:23]
	v_mfma_f32_16x16x32_bf16 v[8:11], v[124:127], v[182:185], v[8:11]
	v_mfma_f32_16x16x32_bf16 v[12:15], v[174:177], v[182:185], v[12:15]
	v_mfma_f32_16x16x32_bf16 v[24:27], v[124:127], v[190:193], v[24:27]
	v_mfma_f32_16x16x32_bf16 v[28:31], v[174:177], v[190:193], v[28:31]
	v_mfma_f32_16x16x32_bf16 v[60:63], v[124:127], v[198:201], v[60:63]
	v_mfma_f32_16x16x32_bf16 v[100:103], v[174:177], v[198:201], v[100:103]
	v_mfma_f32_16x16x32_bf16 v[16:19], v[124:127], v[208:211], v[16:19]
	v_mfma_f32_16x16x32_bf16 v[20:23], v[174:177], v[208:211], v[20:23]
	s_barrier
	ds_read_b128 v[104:107], v140
	ds_read_b128 v[108:111], v140 offset:1024
	ds_read_b128 v[112:115], v140 offset:2048
	ds_read_b128 v[116:119], v140 offset:3072
	ds_read_b128 v[120:123], v141
	ds_read_b128 v[124:127], v141 offset:1024
	ds_read_b128 v[170:173], v141 offset:2048
	ds_read_b128 v[174:177], v141 offset:3072
	s_add_u32 s42, s42, 0x10180
	s_addc_u32 s43, s43, 0
	s_mov_b32 m0, s59
	v_lshl_add_u64 v[212:213], s[42:43], 0, v[128:129]
	ds_read_b128 v[178:181], v142
	ds_read_b128 v[182:185], v142 offset:1024
	ds_read_b128 v[186:189], v142 offset:2048
	ds_read_b128 v[190:193], v142 offset:3072
	ds_read_b128 v[194:197], v142 offset:4096
	ds_read_b128 v[198:201], v142 offset:5120
	ds_read_b128 v[204:207], v142 offset:6144
	ds_read_b128 v[208:211], v142 offset:7168
	global_load_lds_dwordx4 v[212:213], off
	s_mov_b32 m0, s60
	v_lshl_add_u64 v[212:213], s[42:43], 0, v[132:133]
	global_load_lds_dwordx4 v[212:213], off
	s_waitcnt vmcnt(8)
	s_waitcnt lgkmcnt(0)
	s_barrier
	s_waitcnt lgkmcnt(0)
	v_mfma_f32_16x16x32_bf16 v[64:67], v[104:107], v[178:181], v[64:67]
	v_mfma_f32_16x16x32_bf16 v[68:71], v[112:115], v[178:181], v[68:71]
	v_mfma_f32_16x16x32_bf16 v[72:75], v[104:107], v[186:189], v[72:75]
	v_mfma_f32_16x16x32_bf16 v[76:79], v[112:115], v[186:189], v[76:79]
	v_mfma_f32_16x16x32_bf16 v[80:83], v[104:107], v[194:197], v[80:83]
	v_mfma_f32_16x16x32_bf16 v[84:87], v[112:115], v[194:197], v[84:87]
	v_mfma_f32_16x16x32_bf16 v[88:91], v[104:107], v[204:207], v[88:91]
	v_mfma_f32_16x16x32_bf16 v[92:95], v[112:115], v[204:207], v[92:95]
	v_mfma_f32_16x16x32_bf16 v[64:67], v[108:111], v[182:185], v[64:67]
	v_mfma_f32_16x16x32_bf16 v[68:71], v[116:119], v[182:185], v[68:71]
	v_mfma_f32_16x16x32_bf16 v[72:75], v[108:111], v[190:193], v[72:75]
	v_mfma_f32_16x16x32_bf16 v[76:79], v[116:119], v[190:193], v[76:79]
	v_mfma_f32_16x16x32_bf16 v[80:83], v[108:111], v[198:201], v[80:83]
	v_mfma_f32_16x16x32_bf16 v[84:87], v[116:119], v[198:201], v[84:87]
	v_mfma_f32_16x16x32_bf16 v[88:91], v[108:111], v[208:211], v[88:91]
	v_mfma_f32_16x16x32_bf16 v[92:95], v[116:119], v[208:211], v[92:95]
	v_mfma_f32_16x16x32_bf16 v[32:35], v[170:173], v[178:181], v[32:35]
	v_mfma_f32_16x16x32_bf16 v[36:39], v[120:123], v[186:189], v[36:39]
	v_mfma_f32_16x16x32_bf16 v[40:43], v[170:173], v[186:189], v[40:43]
	v_mfma_f32_16x16x32_bf16 v[44:47], v[120:123], v[194:197], v[44:47]
	v_mfma_f32_16x16x32_bf16 v[48:51], v[170:173], v[194:197], v[48:51]
	v_mfma_f32_16x16x32_bf16 v[52:55], v[120:123], v[204:207], v[52:55]
	v_mfma_f32_16x16x32_bf16 v[56:59], v[170:173], v[204:207], v[56:59]
	v_mfma_f32_16x16x32_bf16 v[96:99], v[120:123], v[178:181], v[96:99]
	v_mfma_f32_16x16x32_bf16 v[32:35], v[174:177], v[182:185], v[32:35]
	v_mfma_f32_16x16x32_bf16 v[36:39], v[124:127], v[190:193], v[36:39]
	v_mfma_f32_16x16x32_bf16 v[40:43], v[174:177], v[190:193], v[40:43]
	v_mfma_f32_16x16x32_bf16 v[44:47], v[124:127], v[198:201], v[44:47]
	v_mfma_f32_16x16x32_bf16 v[48:51], v[174:177], v[198:201], v[48:51]
	v_mfma_f32_16x16x32_bf16 v[52:55], v[124:127], v[208:211], v[52:55]
	v_mfma_f32_16x16x32_bf16 v[56:59], v[174:177], v[208:211], v[56:59]
	v_mfma_f32_16x16x32_bf16 v[212:215], v[124:127], v[182:185], v[96:99]
	s_barrier
; #define PG8_STAGE(bufoff, gbase, voff) do { _Pragma("unroll") for (int _i = 0; _i < 2; ++_i) \
;         __builtin_amdgcn_global_load_lds((const unsigned*)((const char*)(gbase) + (voff)[_i]), (LAS unsigned*)(lds + (bufoff) + ldsw + _i * 8192), 16, 0, 0); } while (0)
; #define PG8_LDA(dst, b, h) do { _Pragma("unroll") for (int m = 0; m < 4; ++m) _Pragma("unroll") for (int k = 0; k < 2; ++k) dst[m][k] = *(const LAS bf16x8*)(lds + PG8_SA(b, h) + aoff + m * 2048 + k * 1024); } while (0)
; #define PG8_LDB(dst, b, h) do { _Pragma("unroll") for (int n = 0; n < 2; ++n) _Pragma("unroll") for (int k = 0; k < 2; ++k) dst[n][k] = *(const LAS bf16x8*)(lds + PG8_SB(b, h) + boff + n * 2048 + k * 1024); } while (0)
; #define PG8_MMA(ai, bj, At, Bt) do { __builtin_amdgcn_s_setprio(1); _Pragma("unroll") for (int m = 0; m < 4; ++m) _Pragma("unroll") for (int n = 0; n < 2; ++n) _Pragma("unroll") for (int k = 0; k < 2; ++k) \
;         acc[ai][bj][m][n] = __builtin_amdgcn_mfma_f32_16x16x32_bf16(Bt[n][k], At[m][k], acc[ai][bj][m][n], 0, 0, 0); __builtin_amdgcn_s_setprio(0); } while (0)
; #define PG8_WAIT_V(n) asm volatile("s_waitcnt vmcnt(" #n ")" ::: "memory")
; #define PG8_WAIT_L(n) asm volatile("s_waitcnt lgkmcnt(" #n ")" ::: "memory")
; #define PG8_BAR __builtin_amdgcn_s_barrier()
; #define PG8_SCHED __builtin_amdgcn_sched_barrier(0)
; template <class Epi, class Sched, bool ALIGN_EPI = true>
; __device__ __forceinline__ void gemm_phase(LAS unsigned char* lds, const Gemm g, const Sched& S, const Epi& E) {
;     ...
;             PG8_LDB(B0, 0, 0); PG8_LDB(B1, 0, 1); PG8_SCHED; PG8_LDA(At, 0, 0); PG8_STAGE(PG8_SA(1, 1), a1 + hstep, voffA);
;             PG8_WAIT_V(8); PG8_WAIT_L(0); PG8_BAR; PG8_MMA(0, 0, At, B0); PG8_MMA(0, 1, At, B1); PG8_BAR; PG8_SCHED;
;             PG8_LDA(At, 0, 1); PG8_STAGE(PG8_SB(0, 0), b2, voffB); PG8_STAGE(PG8_SB(0, 1), b2 + hstep, voffB); PG8_STAGE(PG8_SA(0, 0), a2, voffA);
;             PG8_WAIT_V(8); PG8_WAIT_L(0); PG8_BAR; PG8_MMA(1, 0, At, B0); PG8_MMA(1, 1, At, B1); PG8_BAR; PG8_SCHED;
;             PG8_LDB(B0, 1, 0); PG8_LDB(B1, 1, 1); PG8_SCHED; PG8_LDA(At, 1, 0); PG8_STAGE(PG8_SA(0, 1), a2 + hstep, voffA);
;             PG8_WAIT_V(8); PG8_WAIT_L(0); PG8_BAR; PG8_MMA(0, 0, At, B0); PG8_MMA(0, 1, At, B1); PG8_BAR; PG8_SCHED;
	s_mov_b32 m0, s61
	v_lshl_add_u64 v[248:249], s[40:41], 0, v[130:131]
	s_add_u32 s42, s40, 0x10000
	ds_read_b128 v[96:99], v142 offset:16384
	ds_read_b128 v[178:181], v142 offset:17408
	ds_read_b128 v[182:185], v142 offset:18432
	ds_read_b128 v[186:189], v142 offset:19456
	ds_read_b128 v[190:193], v142 offset:20480
	ds_read_b128 v[194:197], v142 offset:21504
	ds_read_b128 v[198:201], v142 offset:22528
	ds_read_b128 v[204:207], v142 offset:23552
	global_load_lds_dwordx4 v[248:249], off
	v_lshl_add_u64 v[250:251], s[40:41], 0, v[134:135]
	s_mov_b32 m0, s62
	s_addc_u32 s43, s41, 0
	global_load_lds_dwordx4 v[250:251], off
	v_lshl_add_u64 v[208:209], s[42:43], 0, v[130:131]
	s_mov_b32 m0, s63
	v_lshl_add_u64 v[252:253], s[44:45], 0, v[128:129]
	global_load_lds_dwordx4 v[208:209], off
	v_lshl_add_u64 v[208:209], s[42:43], 0, v[134:135]
	s_mov_b32 m0, s76
	v_lshl_add_u64 v[202:203], s[44:45], 0, v[132:133]
	global_load_lds_dwordx4 v[208:209], off
	s_mov_b32 m0, s23
	s_nop 0
	global_load_lds_dwordx4 v[252:253], off
	s_mov_b32 m0, s53
	s_nop 0
	global_load_lds_dwordx4 v[202:203], off
	s_waitcnt vmcnt(8)
	s_waitcnt lgkmcnt(0)
	s_barrier
	s_waitcnt lgkmcnt(0)
	v_mfma_f32_16x16x32_bf16 v[0:3], v[104:107], v[198:201], v[0:3]
	v_mfma_f32_16x16x32_bf16 v[4:7], v[112:115], v[198:201], v[4:7]
	v_mfma_f32_16x16x32_bf16 v[146:149], v[104:107], v[96:99], v[146:149]
	v_mfma_f32_16x16x32_bf16 v[150:153], v[112:115], v[96:99], v[150:153]
	v_mfma_f32_16x16x32_bf16 v[154:157], v[104:107], v[182:185], v[154:157]
	v_mfma_f32_16x16x32_bf16 v[158:161], v[112:115], v[182:185], v[158:161]
	v_mfma_f32_16x16x32_bf16 v[162:165], v[104:107], v[190:193], v[162:165]
	v_mfma_f32_16x16x32_bf16 v[166:169], v[112:115], v[190:193], v[166:169]
	v_mfma_f32_16x16x32_bf16 v[0:3], v[108:111], v[204:207], v[0:3]
	v_mfma_f32_16x16x32_bf16 v[4:7], v[116:119], v[204:207], v[4:7]
	v_mfma_f32_16x16x32_bf16 v[146:149], v[108:111], v[178:181], v[146:149]
	v_mfma_f32_16x16x32_bf16 v[150:153], v[116:119], v[178:181], v[150:153]
	v_mfma_f32_16x16x32_bf16 v[154:157], v[108:111], v[186:189], v[154:157]
	v_mfma_f32_16x16x32_bf16 v[158:161], v[116:119], v[186:189], v[158:161]
	v_mfma_f32_16x16x32_bf16 v[162:165], v[108:111], v[194:197], v[162:165]
	v_mfma_f32_16x16x32_bf16 v[166:169], v[116:119], v[194:197], v[166:169]
	v_mfma_f32_16x16x32_bf16 v[8:11], v[120:123], v[96:99], v[8:11]
	v_mfma_f32_16x16x32_bf16 v[12:15], v[170:173], v[96:99], v[12:15]
	v_mfma_f32_16x16x32_bf16 v[24:27], v[120:123], v[182:185], v[24:27]
	v_mfma_f32_16x16x32_bf16 v[8:11], v[124:127], v[178:181], v[8:11]
	v_mfma_f32_16x16x32_bf16 v[12:15], v[174:177], v[178:181], v[12:15]
	v_mfma_f32_16x16x32_bf16 v[178:181], v[124:127], v[186:189], v[24:27]
	v_mfma_f32_16x16x32_bf16 v[24:27], v[170:173], v[182:185], v[28:31]
	v_mfma_f32_16x16x32_bf16 v[182:185], v[174:177], v[186:189], v[24:27]
	v_mfma_f32_16x16x32_bf16 v[24:27], v[120:123], v[190:193], v[60:63]
	v_mfma_f32_16x16x32_bf16 v[186:189], v[124:127], v[194:197], v[24:27]
	v_mfma_f32_16x16x32_bf16 v[24:27], v[170:173], v[190:193], v[100:103]
	v_mfma_f32_16x16x32_bf16 v[16:19], v[120:123], v[198:201], v[16:19]
	v_mfma_f32_16x16x32_bf16 v[190:193], v[174:177], v[194:197], v[24:27]
	v_mfma_f32_16x16x32_bf16 v[194:197], v[124:127], v[204:207], v[16:19]
	v_mfma_f32_16x16x32_bf16 v[16:19], v[170:173], v[198:201], v[20:23]
	v_mfma_f32_16x16x32_bf16 v[170:173], v[174:177], v[204:207], v[16:19]
	s_barrier
	ds_read_b128 v[60:63], v143
	ds_read_b128 v[174:177], v143 offset:1024
	ds_read_b128 v[198:201], v143 offset:2048
	ds_read_b128 v[204:207], v143 offset:3072
	ds_read_b128 v[208:211], v144
	ds_read_b128 v[216:219], v144 offset:1024
	ds_read_b128 v[220:223], v144 offset:2048
	ds_read_b128 v[224:227], v144 offset:3072
	s_add_u32 s42, s44, 0x10000
	s_addc_u32 s43, s45, 0
	s_mov_b32 m0, s54
	v_lshl_add_u64 v[24:25], s[42:43], 0, v[128:129]
	ds_read_b128 v[16:19], v142 offset:32768
	ds_read_b128 v[20:23], v142 offset:33792
	ds_read_b128 v[108:111], v142 offset:34816
	ds_read_b128 v[228:231], v142 offset:35840
	ds_read_b128 v[232:235], v142 offset:36864
	ds_read_b128 v[236:239], v142 offset:37888
	ds_read_b128 v[240:243], v142 offset:38912
	ds_read_b128 v[244:247], v142 offset:39936
	global_load_lds_dwordx4 v[24:25], off
	s_mov_b32 m0, s55
	v_lshl_add_u64 v[24:25], s[42:43], 0, v[132:133]
	global_load_lds_dwordx4 v[24:25], off
	s_waitcnt vmcnt(8)
	s_waitcnt lgkmcnt(0)
	s_barrier
; #define PG8_STAGE(bufoff, gbase, voff) do { _Pragma("unroll") for (int _i = 0; _i < 2; ++_i) \
;         __builtin_amdgcn_global_load_lds((const unsigned*)((const char*)(gbase) + (voff)[_i]), (LAS unsigned*)(lds + (bufoff) + ldsw + _i * 8192), 16, 0, 0); } while (0)
; #define PG8_LDA(dst, b, h) do { _Pragma("unroll") for (int m = 0; m < 4; ++m) _Pragma("unroll") for (int k = 0; k < 2; ++k) dst[m][k] = *(const LAS bf16x8*)(lds + PG8_SA(b, h) + aoff + m * 2048 + k * 1024); } while (0)
; #define PG8_MMA(ai, bj, At, Bt) do { __builtin_amdgcn_s_setprio(1); _Pragma("unroll") for (int m = 0; m < 4; ++m) _Pragma("unroll") for (int n = 0; n < 2; ++n) _Pragma("unroll") for (int k = 0; k < 2; ++k) \
;         acc[ai][bj][m][n] = __builtin_amdgcn_mfma_f32_16x16x32_bf16(Bt[n][k], At[m][k], acc[ai][bj][m][n], 0, 0, 0); __builtin_amdgcn_s_setprio(0); } while (0)
; #define PG8_WAIT_V(n) asm volatile("s_waitcnt vmcnt(" #n ")" ::: "memory")
; #define PG8_WAIT_L(n) asm volatile("s_waitcnt lgkmcnt(" #n ")" ::: "memory")
; #define PG8_BAR __builtin_amdgcn_s_barrier()
; #define PG8_SCHED __builtin_amdgcn_sched_barrier(0)
; template <class Epi, class Sched, bool ALIGN_EPI = true>
; __device__ __forceinline__ void gemm_phase(LAS unsigned char* lds, const Gemm g, const Sched& S, const Epi& E) {
;     ...
;             PG8_WAIT_V(8); PG8_WAIT_L(0); PG8_BAR; PG8_MMA(0, 0, At, B0); PG8_MMA(0, 1, At, B1); PG8_BAR; PG8_SCHED;
;             PG8_LDA(At, 1, 1); PG8_STAGE(PG8_SB(1, 0), b3, voffB); PG8_STAGE(PG8_SB(1, 1), b3 + hstep, voffB); PG8_STAGE(PG8_SA(1, 0), a3, voffA);
;             PG8_WAIT_V(8); PG8_WAIT_L(0); PG8_BAR; PG8_MMA(1, 0, At, B0); PG8_MMA(1, 1, At, B1); PG8_BAR; PG8_SCHED;
;         }
;         if constexpr (ALIGN_EPI) { if (wr == 0) PG8_BAR; }
	s_waitcnt lgkmcnt(0)
	v_mfma_f32_16x16x32_bf16 v[24:27], v[60:63], v[16:19], v[64:67]
	v_mfma_f32_16x16x32_bf16 v[112:115], v[174:177], v[20:23], v[24:27]
	v_mfma_f32_16x16x32_bf16 v[24:27], v[198:201], v[16:19], v[68:71]
	v_mfma_f32_16x16x32_bf16 v[116:119], v[204:207], v[20:23], v[24:27]
	v_mfma_f32_16x16x32_bf16 v[24:27], v[60:63], v[108:111], v[72:75]
	v_mfma_f32_16x16x32_bf16 v[96:99], v[174:177], v[228:231], v[24:27]
	v_mfma_f32_16x16x32_bf16 v[24:27], v[198:201], v[108:111], v[76:79]
	v_mfma_f32_16x16x32_bf16 v[100:103], v[204:207], v[228:231], v[24:27]
	v_mfma_f32_16x16x32_bf16 v[24:27], v[60:63], v[232:235], v[80:83]
	v_mfma_f32_16x16x32_bf16 v[64:67], v[174:177], v[236:239], v[24:27]
	v_mfma_f32_16x16x32_bf16 v[24:27], v[198:201], v[232:235], v[84:87]
	v_mfma_f32_16x16x32_bf16 v[68:71], v[204:207], v[236:239], v[24:27]
	v_mfma_f32_16x16x32_bf16 v[24:27], v[60:63], v[240:243], v[88:91]
	v_mfma_f32_16x16x32_bf16 v[28:31], v[198:201], v[240:243], v[92:95]
	v_mfma_f32_16x16x32_bf16 v[24:27], v[174:177], v[244:247], v[24:27]
	v_mfma_f32_16x16x32_bf16 v[28:31], v[204:207], v[244:247], v[28:31]
	v_mfma_f32_16x16x32_bf16 v[72:75], v[208:211], v[16:19], v[212:215]
	v_mfma_f32_16x16x32_bf16 v[16:19], v[220:223], v[16:19], v[32:35]
	v_mfma_f32_16x16x32_bf16 v[124:127], v[224:227], v[20:23], v[16:19]
	v_mfma_f32_16x16x32_bf16 v[16:19], v[208:211], v[108:111], v[36:39]
	v_mfma_f32_16x16x32_bf16 v[104:107], v[216:219], v[228:231], v[16:19]
	v_mfma_f32_16x16x32_bf16 v[16:19], v[220:223], v[108:111], v[40:43]
	v_mfma_f32_16x16x32_bf16 v[108:111], v[224:227], v[228:231], v[16:19]
	v_mfma_f32_16x16x32_bf16 v[16:19], v[208:211], v[232:235], v[44:47]
	v_mfma_f32_16x16x32_bf16 v[120:123], v[216:219], v[20:23], v[72:75]
	v_mfma_f32_16x16x32_bf16 v[72:75], v[216:219], v[236:239], v[16:19]
	v_mfma_f32_16x16x32_bf16 v[16:19], v[220:223], v[232:235], v[48:51]
	v_mfma_f32_16x16x32_bf16 v[76:79], v[224:227], v[236:239], v[16:19]
	v_mfma_f32_16x16x32_bf16 v[16:19], v[208:211], v[240:243], v[52:55]
	v_mfma_f32_16x16x32_bf16 v[40:43], v[216:219], v[244:247], v[16:19]
	v_mfma_f32_16x16x32_bf16 v[16:19], v[220:223], v[240:243], v[56:59]
	v_mfma_f32_16x16x32_bf16 v[44:47], v[224:227], v[244:247], v[16:19]
	s_barrier
	s_mov_b32 m0, s77
	s_nop 3
	v_lshl_add_u64 v[16:17], v[248:249], 0, s[12:13]
	s_add_u32 s40, s40, 0x10080
	ds_read_b128 v[32:35], v142 offset:49152
	ds_read_b128 v[36:39], v142 offset:50176
	ds_read_b128 v[212:215], v142 offset:51200
	ds_read_b128 v[228:231], v142 offset:52224
	ds_read_b128 v[232:235], v142 offset:53248
	ds_read_b128 v[236:239], v142 offset:54272
	ds_read_b128 v[240:243], v142 offset:55296
	ds_read_b128 v[244:247], v142 offset:56320
	global_load_lds_dwordx4 v[16:17], off
	v_lshl_add_u64 v[16:17], v[250:251], 0, s[12:13]
	s_mov_b32 m0, s78
	s_addc_u32 s41, s41, 0
	global_load_lds_dwordx4 v[16:17], off
	s_mov_b32 m0, s79
	v_lshl_add_u64 v[16:17], s[40:41], 0, v[130:131]
	global_load_lds_dwordx4 v[16:17], off
	s_mov_b32 m0, s80
	v_lshl_add_u64 v[16:17], s[40:41], 0, v[134:135]
	global_load_lds_dwordx4 v[16:17], off
	s_mov_b32 m0, s57
	v_lshl_add_u64 v[16:17], v[252:253], 0, s[12:13]
	global_load_lds_dwordx4 v[16:17], off
	s_mov_b32 m0, s58
	v_lshl_add_u64 v[16:17], v[202:203], 0, s[12:13]
	global_load_lds_dwordx4 v[16:17], off
	s_waitcnt vmcnt(8)
	s_waitcnt lgkmcnt(0)
	s_barrier
	s_waitcnt lgkmcnt(0)
	v_mfma_f32_16x16x32_bf16 v[16:19], v[60:63], v[32:35], v[146:149]
	v_mfma_f32_16x16x32_bf16 v[80:83], v[174:177], v[36:39], v[16:19]
	v_mfma_f32_16x16x32_bf16 v[16:19], v[198:201], v[32:35], v[150:153]
	v_mfma_f32_16x16x32_bf16 v[84:87], v[204:207], v[36:39], v[16:19]
	v_mfma_f32_16x16x32_bf16 v[16:19], v[60:63], v[212:215], v[154:157]
	v_mfma_f32_16x16x32_bf16 v[48:51], v[174:177], v[228:231], v[16:19]
	v_mfma_f32_16x16x32_bf16 v[16:19], v[198:201], v[212:215], v[158:161]
	v_mfma_f32_16x16x32_bf16 v[52:55], v[204:207], v[228:231], v[16:19]
	v_mfma_f32_16x16x32_bf16 v[16:19], v[60:63], v[232:235], v[162:165]
	v_mfma_f32_16x16x32_bf16 v[20:23], v[198:201], v[232:235], v[166:169]
	v_mfma_f32_16x16x32_bf16 v[0:3], v[60:63], v[240:243], v[0:3]
	v_mfma_f32_16x16x32_bf16 v[4:7], v[198:201], v[240:243], v[4:7]
	v_mfma_f32_16x16x32_bf16 v[16:19], v[174:177], v[236:239], v[16:19]
	v_mfma_f32_16x16x32_bf16 v[20:23], v[204:207], v[236:239], v[20:23]
	v_mfma_f32_16x16x32_bf16 v[0:3], v[174:177], v[244:247], v[0:3]
	v_mfma_f32_16x16x32_bf16 v[4:7], v[204:207], v[244:247], v[4:7]
	v_mfma_f32_16x16x32_bf16 v[8:11], v[208:211], v[32:35], v[8:11]
	v_mfma_f32_16x16x32_bf16 v[88:91], v[216:219], v[36:39], v[8:11]
	v_mfma_f32_16x16x32_bf16 v[8:11], v[220:223], v[32:35], v[12:15]
	v_mfma_f32_16x16x32_bf16 v[92:95], v[224:227], v[36:39], v[8:11]
	v_mfma_f32_16x16x32_bf16 v[8:11], v[208:211], v[212:215], v[178:181]
	v_mfma_f32_16x16x32_bf16 v[56:59], v[216:219], v[228:231], v[8:11]
	v_mfma_f32_16x16x32_bf16 v[8:11], v[220:223], v[212:215], v[182:185]
	v_mfma_f32_16x16x32_bf16 v[60:63], v[224:227], v[228:231], v[8:11]
	v_mfma_f32_16x16x32_bf16 v[8:11], v[208:211], v[232:235], v[186:189]
	v_mfma_f32_16x16x32_bf16 v[32:35], v[216:219], v[236:239], v[8:11]
	v_mfma_f32_16x16x32_bf16 v[8:11], v[220:223], v[232:235], v[190:193]
	v_mfma_f32_16x16x32_bf16 v[36:39], v[224:227], v[236:239], v[8:11]
	v_mfma_f32_16x16x32_bf16 v[8:11], v[208:211], v[240:243], v[194:197]
	v_mfma_f32_16x16x32_bf16 v[12:15], v[220:223], v[240:243], v[170:173]
	v_mfma_f32_16x16x32_bf16 v[8:11], v[216:219], v[244:247], v[8:11]
	v_mfma_f32_16x16x32_bf16 v[12:15], v[224:227], v[244:247], v[12:15]
	s_barrier
	s_and_b64 vcc, exec, s[4:5]
	s_cbranch_vccnz .LBB0_669
	s_barrier

; #define PG8_STAGE(bufoff, gbase, voff) do { _Pragma("unroll") for (int _i = 0; _i < 2; ++_i) \
;         __builtin_amdgcn_global_load_lds((const unsigned*)((const char*)(gbase) + (voff)[_i]), (LAS unsigned*)(lds + (bufoff) + ldsw + _i * 8192), 16, 0, 0); } while (0)
; #define PG8_LDA(dst, b, h) do { _Pragma("unroll") for (int m = 0; m < 4; ++m) _Pragma("unroll") for (int k = 0; k < 2; ++k) dst[m][k] = *(const LAS bf16x8*)(lds + PG8_SA(b, h) + aoff + m * 2048 + k * 1024); } while (0)
; #define PG8_LDB(dst, b, h) do { _Pragma("unroll") for (int n = 0; n < 2; ++n) _Pragma("unroll") for (int k = 0; k < 2; ++k) dst[n][k] = *(const LAS bf16x8*)(lds + PG8_SB(b, h) + boff + n * 2048 + k * 1024); } while (0)
; #define PG8_MMA(ai, bj, At, Bt) do { __builtin_amdgcn_s_setprio(1); _Pragma("unroll") for (int m = 0; m < 4; ++m) _Pragma("unroll") for (int n = 0; n < 2; ++n) _Pragma("unroll") for (int k = 0; k < 2; ++k) \
;         acc[ai][bj][m][n] = __builtin_amdgcn_mfma_f32_16x16x32_bf16(Bt[n][k], At[m][k], acc[ai][bj][m][n], 0, 0, 0); __builtin_amdgcn_s_setprio(0); } while (0)
; #define PG8_WAIT_V(n) asm volatile("s_waitcnt vmcnt(" #n ")" ::: "memory")
; #define PG8_WAIT_L(n) asm volatile("s_waitcnt lgkmcnt(" #n ")" ::: "memory")
; #define PG8_BAR __builtin_amdgcn_s_barrier()
; #define PG8_SCHED __builtin_amdgcn_sched_barrier(0)
; template <class Epi, class Sched, bool ALIGN_EPI = true>
; __device__ __forceinline__ void gemm_phase(LAS unsigned char* lds, const Gemm g, const Sched& S, const Epi& E) {
;     ...
;         for (int t = 0; t < nt; t += 2) {
;             const bool last = (t == nt - 2);
;             const char* a1 = cA + (size_t)(t + 1) * kstep;
;             const char* a2 = last ? nA : cA + (size_t)(t + 2) * kstep; const char* b2 = last ? nB : cB + (size_t)(t + 2) * kstep;
;             const char* a3 = a2 + kstep; const char* b3 = b2 + kstep;
;             PG8_LDB(B0, 0, 0); PG8_LDB(B1, 0, 1); PG8_SCHED; PG8_LDA(At, 0, 0); PG8_STAGE(PG8_SA(1, 1), a1 + hstep, voffA);
;             PG8_WAIT_V(8); PG8_WAIT_L(0); PG8_BAR; PG8_MMA(0, 0, At, B0); PG8_MMA(0, 1, At, B1); PG8_BAR; PG8_SCHED;
;             PG8_LDA(At, 0, 1); PG8_STAGE(PG8_SB(0, 0), b2, voffB); PG8_STAGE(PG8_SB(0, 1), b2 + hstep, voffB); PG8_STAGE(PG8_SA(0, 0), a2, voffA);
;             PG8_WAIT_V(8); PG8_WAIT_L(0); PG8_BAR; PG8_MMA(1, 0, At, B0); PG8_MMA(1, 1, At, B1); PG8_BAR; PG8_SCHED;
.LBB0_746:
	ds_read_b128 v[128:131], v187
	ds_read_b128 v[132:135], v187 offset:1024
	ds_read_b128 v[136:139], v187 offset:2048
	ds_read_b128 v[140:143], v187 offset:3072
	ds_read_b128 v[144:147], v188
	ds_read_b128 v[148:151], v188 offset:1024
	ds_read_b128 v[164:167], v188 offset:2048
	ds_read_b128 v[168:171], v188 offset:3072
	s_add_u32 s24, s22, 0x100
	s_addc_u32 s25, s23, 0
	s_cmpk_eq_i32 s56, 0x54
	s_cselect_b32 s29, s19, s25
	s_cselect_b32 s28, s18, s24
	s_cselect_b32 s27, s21, s55
	s_cselect_b32 s26, s20, s54
	s_mov_b32 m0, s43
	v_lshl_add_u64 v[180:181], s[22:23], 0, v[160:161]
	ds_read_b128 v[172:175], v189
	ds_read_b128 v[176:179], v189 offset:1024
	ds_read_b128 v[192:195], v189 offset:2048
	ds_read_b128 v[196:199], v189 offset:3072
	ds_read_b128 v[204:207], v189 offset:4096
	ds_read_b128 v[208:211], v189 offset:5120
	ds_read_b128 v[212:215], v189 offset:6144
	ds_read_b128 v[216:219], v189 offset:7168
	global_load_lds_dwordx4 v[180:181], off
	s_mov_b32 m0, s44
	v_lshl_add_u64 v[180:181], s[22:23], 0, v[162:163]
	global_load_lds_dwordx4 v[180:181], off
	s_waitcnt vmcnt(8)
	s_waitcnt lgkmcnt(0)
	s_barrier
	s_waitcnt lgkmcnt(0)
	v_mfma_f32_16x16x32_bf16 v[124:127], v[128:131], v[172:175], v[124:127]
	v_mfma_f32_16x16x32_bf16 v[120:123], v[136:139], v[172:175], v[120:123]
	v_mfma_f32_16x16x32_bf16 v[108:111], v[128:131], v[192:195], v[108:111]
	v_mfma_f32_16x16x32_bf16 v[104:107], v[136:139], v[192:195], v[104:107]
	v_mfma_f32_16x16x32_bf16 v[92:95], v[128:131], v[204:207], v[92:95]
	v_mfma_f32_16x16x32_bf16 v[88:91], v[136:139], v[204:207], v[88:91]
	v_mfma_f32_16x16x32_bf16 v[76:79], v[128:131], v[212:215], v[76:79]
	v_mfma_f32_16x16x32_bf16 v[72:75], v[136:139], v[212:215], v[72:75]
	v_mfma_f32_16x16x32_bf16 v[124:127], v[132:135], v[176:179], v[124:127]
	v_mfma_f32_16x16x32_bf16 v[120:123], v[140:143], v[176:179], v[120:123]
	v_mfma_f32_16x16x32_bf16 v[108:111], v[132:135], v[196:199], v[108:111]
	v_mfma_f32_16x16x32_bf16 v[104:107], v[140:143], v[196:199], v[104:107]
	v_mfma_f32_16x16x32_bf16 v[92:95], v[132:135], v[208:211], v[92:95]
	v_mfma_f32_16x16x32_bf16 v[88:91], v[140:143], v[208:211], v[88:91]
	v_mfma_f32_16x16x32_bf16 v[76:79], v[132:135], v[216:219], v[76:79]
	v_mfma_f32_16x16x32_bf16 v[72:75], v[140:143], v[216:219], v[72:75]
	v_mfma_f32_16x16x32_bf16 v[116:119], v[144:147], v[172:175], v[116:119]
	v_mfma_f32_16x16x32_bf16 v[112:115], v[164:167], v[172:175], v[112:115]
	v_mfma_f32_16x16x32_bf16 v[100:103], v[144:147], v[192:195], v[100:103]
	v_mfma_f32_16x16x32_bf16 v[96:99], v[164:167], v[192:195], v[96:99]
	v_mfma_f32_16x16x32_bf16 v[84:87], v[144:147], v[204:207], v[84:87]
	v_mfma_f32_16x16x32_bf16 v[80:83], v[164:167], v[204:207], v[80:83]
	v_mfma_f32_16x16x32_bf16 v[68:71], v[144:147], v[212:215], v[68:71]
	v_mfma_f32_16x16x32_bf16 v[64:67], v[164:167], v[212:215], v[64:67]
	v_mfma_f32_16x16x32_bf16 v[116:119], v[148:151], v[176:179], v[116:119]
	v_mfma_f32_16x16x32_bf16 v[112:115], v[168:171], v[176:179], v[112:115]
	v_mfma_f32_16x16x32_bf16 v[100:103], v[148:151], v[196:199], v[100:103]
	v_mfma_f32_16x16x32_bf16 v[96:99], v[168:171], v[196:199], v[96:99]
	v_mfma_f32_16x16x32_bf16 v[84:87], v[148:151], v[208:211], v[84:87]
	v_mfma_f32_16x16x32_bf16 v[80:83], v[168:171], v[208:211], v[80:83]
	v_mfma_f32_16x16x32_bf16 v[68:71], v[148:151], v[216:219], v[68:71]
	v_mfma_f32_16x16x32_bf16 v[64:67], v[168:171], v[216:219], v[64:67]
	s_barrier
	s_mov_b32 m0, s45
	v_lshl_add_u64 v[180:181], s[26:27], 0, v[154:155]
	s_add_u32 s22, s26, 0x160000
	ds_read_b128 v[172:175], v189 offset:16384
	ds_read_b128 v[176:179], v189 offset:17408
	ds_read_b128 v[192:195], v189 offset:18432
	ds_read_b128 v[196:199], v189 offset:19456
	ds_read_b128 v[204:207], v189 offset:20480
	ds_read_b128 v[208:211], v189 offset:21504
	ds_read_b128 v[212:215], v189 offset:22528
	ds_read_b128 v[216:219], v189 offset:23552
	global_load_lds_dwordx4 v[180:181], off
	v_lshl_add_u64 v[200:201], s[26:27], 0, v[158:159]
	s_mov_b32 m0, s48
	s_addc_u32 s23, s27, 0
	global_load_lds_dwordx4 v[200:201], off
	v_lshl_add_u64 v[202:203], s[22:23], 0, v[154:155]
	s_mov_b32 m0, s49
	v_lshl_add_u64 v[220:221], s[28:29], 0, v[156:157]
	global_load_lds_dwordx4 v[202:203], off
	s_add_i32 m0, s49, 0x2000
	v_lshl_add_u64 v[202:203], s[22:23], 0, v[158:159]
	global_load_lds_dwordx4 v[202:203], off
	s_mov_b32 m0, s36
	v_lshl_add_u64 v[202:203], s[28:29], 0, v[152:153]
	global_load_lds_dwordx4 v[202:203], off
	s_mov_b32 m0, s37
	s_nop 0
	global_load_lds_dwordx4 v[220:221], off
	s_waitcnt vmcnt(8)
	s_waitcnt lgkmcnt(0)
	s_barrier
; #define PG8_STAGE(bufoff, gbase, voff) do { _Pragma("unroll") for (int _i = 0; _i < 2; ++_i) \
;         __builtin_amdgcn_global_load_lds((const unsigned*)((const char*)(gbase) + (voff)[_i]), (LAS unsigned*)(lds + (bufoff) + ldsw + _i * 8192), 16, 0, 0); } while (0)
; #define PG8_LDA(dst, b, h) do { _Pragma("unroll") for (int m = 0; m < 4; ++m) _Pragma("unroll") for (int k = 0; k < 2; ++k) dst[m][k] = *(const LAS bf16x8*)(lds + PG8_SA(b, h) + aoff + m * 2048 + k * 1024); } while (0)
; #define PG8_LDB(dst, b, h) do { _Pragma("unroll") for (int n = 0; n < 2; ++n) _Pragma("unroll") for (int k = 0; k < 2; ++k) dst[n][k] = *(const LAS bf16x8*)(lds + PG8_SB(b, h) + boff + n * 2048 + k * 1024); } while (0)
; #define PG8_MMA(ai, bj, At, Bt) do { __builtin_amdgcn_s_setprio(1); _Pragma("unroll") for (int m = 0; m < 4; ++m) _Pragma("unroll") for (int n = 0; n < 2; ++n) _Pragma("unroll") for (int k = 0; k < 2; ++k) \
;         acc[ai][bj][m][n] = __builtin_amdgcn_mfma_f32_16x16x32_bf16(Bt[n][k], At[m][k], acc[ai][bj][m][n], 0, 0, 0); __builtin_amdgcn_s_setprio(0); } while (0)
; #define PG8_WAIT_V(n) asm volatile("s_waitcnt vmcnt(" #n ")" ::: "memory")
; #define PG8_WAIT_L(n) asm volatile("s_waitcnt lgkmcnt(" #n ")" ::: "memory")
; #define PG8_BAR __builtin_amdgcn_s_barrier()
; #define PG8_SCHED __builtin_amdgcn_sched_barrier(0)
; template <class Epi, class Sched, bool ALIGN_EPI = true>
; __device__ __forceinline__ void gemm_phase(LAS unsigned char* lds, const Gemm g, const Sched& S, const Epi& E) {
;     ...
;             PG8_WAIT_V(8); PG8_WAIT_L(0); PG8_BAR; PG8_MMA(1, 0, At, B0); PG8_MMA(1, 1, At, B1); PG8_BAR; PG8_SCHED;
;             PG8_LDB(B0, 1, 0); PG8_LDB(B1, 1, 1); PG8_SCHED; PG8_LDA(At, 1, 0); PG8_STAGE(PG8_SA(0, 1), a2 + hstep, voffA);
;             PG8_WAIT_V(8); PG8_WAIT_L(0); PG8_BAR; PG8_MMA(0, 0, At, B0); PG8_MMA(0, 1, At, B1); PG8_BAR; PG8_SCHED;
	s_waitcnt lgkmcnt(0)
	v_mfma_f32_16x16x32_bf16 v[60:63], v[128:131], v[172:175], v[60:63]
	v_mfma_f32_16x16x32_bf16 v[56:59], v[136:139], v[172:175], v[56:59]
	v_mfma_f32_16x16x32_bf16 v[44:47], v[128:131], v[192:195], v[44:47]
	v_mfma_f32_16x16x32_bf16 v[40:43], v[136:139], v[192:195], v[40:43]
	v_mfma_f32_16x16x32_bf16 v[28:31], v[128:131], v[204:207], v[28:31]
	v_mfma_f32_16x16x32_bf16 v[24:27], v[136:139], v[204:207], v[24:27]
	v_mfma_f32_16x16x32_bf16 v[12:15], v[128:131], v[212:215], v[12:15]
	v_mfma_f32_16x16x32_bf16 v[8:11], v[136:139], v[212:215], v[8:11]
	v_mfma_f32_16x16x32_bf16 v[60:63], v[132:135], v[176:179], v[60:63]
	v_mfma_f32_16x16x32_bf16 v[56:59], v[140:143], v[176:179], v[56:59]
	v_mfma_f32_16x16x32_bf16 v[44:47], v[132:135], v[196:199], v[44:47]
	v_mfma_f32_16x16x32_bf16 v[40:43], v[140:143], v[196:199], v[40:43]
	v_mfma_f32_16x16x32_bf16 v[28:31], v[132:135], v[208:211], v[28:31]
	v_mfma_f32_16x16x32_bf16 v[24:27], v[140:143], v[208:211], v[24:27]
	v_mfma_f32_16x16x32_bf16 v[12:15], v[132:135], v[216:219], v[12:15]
	v_mfma_f32_16x16x32_bf16 v[8:11], v[140:143], v[216:219], v[8:11]
	v_mfma_f32_16x16x32_bf16 v[52:55], v[144:147], v[172:175], v[52:55]
	v_mfma_f32_16x16x32_bf16 v[48:51], v[164:167], v[172:175], v[48:51]
	v_mfma_f32_16x16x32_bf16 v[36:39], v[144:147], v[192:195], v[36:39]
	v_mfma_f32_16x16x32_bf16 v[32:35], v[164:167], v[192:195], v[32:35]
	v_mfma_f32_16x16x32_bf16 v[20:23], v[144:147], v[204:207], v[20:23]
	v_mfma_f32_16x16x32_bf16 v[16:19], v[164:167], v[204:207], v[16:19]
	v_mfma_f32_16x16x32_bf16 v[4:7], v[144:147], v[212:215], v[4:7]
	v_mfma_f32_16x16x32_bf16 v[0:3], v[164:167], v[212:215], v[0:3]
	v_mfma_f32_16x16x32_bf16 v[52:55], v[148:151], v[176:179], v[52:55]
	v_mfma_f32_16x16x32_bf16 v[48:51], v[168:171], v[176:179], v[48:51]
	v_mfma_f32_16x16x32_bf16 v[36:39], v[148:151], v[196:199], v[36:39]
	v_mfma_f32_16x16x32_bf16 v[32:35], v[168:171], v[196:199], v[32:35]
	v_mfma_f32_16x16x32_bf16 v[20:23], v[148:151], v[208:211], v[20:23]
	v_mfma_f32_16x16x32_bf16 v[16:19], v[168:171], v[208:211], v[16:19]
	v_mfma_f32_16x16x32_bf16 v[4:7], v[148:151], v[216:219], v[4:7]
	v_mfma_f32_16x16x32_bf16 v[0:3], v[168:171], v[216:219], v[0:3]
	s_barrier
	s_add_i32 s46, 0, 0x18000
	s_add_i32 s47, 0, 0x1c000
	v_add_u32_e32 v140, s46, v185
	v_add_u32_e32 v168, s47, v185
	ds_read_b128 v[128:131], v140
	ds_read_b128 v[132:135], v140 offset:1024
	ds_read_b128 v[136:139], v140 offset:2048
	ds_read_b128 v[140:143], v140 offset:3072
	ds_read_b128 v[144:147], v168
	ds_read_b128 v[148:151], v168 offset:1024
	ds_read_b128 v[164:167], v168 offset:2048
	ds_read_b128 v[168:171], v168 offset:3072
	s_add_u32 s22, s28, 0x160000
	s_addc_u32 s23, s29, 0
	s_mov_b32 m0, s38
	v_lshl_add_u64 v[222:223], s[22:23], 0, v[152:153]
	ds_read_b128 v[172:175], v189 offset:32768
	ds_read_b128 v[176:179], v189 offset:33792
	ds_read_b128 v[192:195], v189 offset:34816
	ds_read_b128 v[196:199], v189 offset:35840
	ds_read_b128 v[204:207], v189 offset:36864
	ds_read_b128 v[208:211], v189 offset:37888
	ds_read_b128 v[212:215], v189 offset:38912
	ds_read_b128 v[216:219], v189 offset:39936
	global_load_lds_dwordx4 v[222:223], off
	s_mov_b32 m0, s39
	v_lshl_add_u64 v[222:223], s[22:23], 0, v[156:157]
	global_load_lds_dwordx4 v[222:223], off
	s_waitcnt vmcnt(8)
	s_waitcnt lgkmcnt(0)
	s_barrier
	s_waitcnt lgkmcnt(0)
	v_mfma_f32_16x16x32_bf16 v[124:127], v[128:131], v[172:175], v[124:127]
	v_mfma_f32_16x16x32_bf16 v[120:123], v[136:139], v[172:175], v[120:123]
	v_mfma_f32_16x16x32_bf16 v[108:111], v[128:131], v[192:195], v[108:111]
	v_mfma_f32_16x16x32_bf16 v[104:107], v[136:139], v[192:195], v[104:107]
	v_mfma_f32_16x16x32_bf16 v[92:95], v[128:131], v[204:207], v[92:95]
	v_mfma_f32_16x16x32_bf16 v[88:91], v[136:139], v[204:207], v[88:91]
	v_mfma_f32_16x16x32_bf16 v[76:79], v[128:131], v[212:215], v[76:79]
	v_mfma_f32_16x16x32_bf16 v[72:75], v[136:139], v[212:215], v[72:75]
	v_mfma_f32_16x16x32_bf16 v[124:127], v[132:135], v[176:179], v[124:127]
	v_mfma_f32_16x16x32_bf16 v[120:123], v[140:143], v[176:179], v[120:123]
	v_mfma_f32_16x16x32_bf16 v[108:111], v[132:135], v[196:199], v[108:111]
	v_mfma_f32_16x16x32_bf16 v[104:107], v[140:143], v[196:199], v[104:107]
	v_mfma_f32_16x16x32_bf16 v[92:95], v[132:135], v[208:211], v[92:95]
	v_mfma_f32_16x16x32_bf16 v[88:91], v[140:143], v[208:211], v[88:91]
	v_mfma_f32_16x16x32_bf16 v[76:79], v[132:135], v[216:219], v[76:79]
	v_mfma_f32_16x16x32_bf16 v[72:75], v[140:143], v[216:219], v[72:75]
	v_mfma_f32_16x16x32_bf16 v[116:119], v[144:147], v[172:175], v[116:119]
	v_mfma_f32_16x16x32_bf16 v[112:115], v[164:167], v[172:175], v[112:115]
	v_mfma_f32_16x16x32_bf16 v[100:103], v[144:147], v[192:195], v[100:103]
	v_mfma_f32_16x16x32_bf16 v[96:99], v[164:167], v[192:195], v[96:99]
	v_mfma_f32_16x16x32_bf16 v[84:87], v[144:147], v[204:207], v[84:87]
	v_mfma_f32_16x16x32_bf16 v[80:83], v[164:167], v[204:207], v[80:83]
	v_mfma_f32_16x16x32_bf16 v[68:71], v[144:147], v[212:215], v[68:71]
	v_mfma_f32_16x16x32_bf16 v[64:67], v[164:167], v[212:215], v[64:67]
	v_mfma_f32_16x16x32_bf16 v[116:119], v[148:151], v[176:179], v[116:119]
	v_mfma_f32_16x16x32_bf16 v[112:115], v[168:171], v[176:179], v[112:115]
	v_mfma_f32_16x16x32_bf16 v[100:103], v[148:151], v[196:199], v[100:103]
	v_mfma_f32_16x16x32_bf16 v[96:99], v[168:171], v[196:199], v[96:99]
	v_mfma_f32_16x16x32_bf16 v[84:87], v[148:151], v[208:211], v[84:87]
	v_mfma_f32_16x16x32_bf16 v[80:83], v[168:171], v[208:211], v[80:83]
	v_mfma_f32_16x16x32_bf16 v[68:71], v[148:151], v[216:219], v[68:71]
	v_mfma_f32_16x16x32_bf16 v[64:67], v[168:171], v[216:219], v[64:67]
	s_barrier
; #define PG8_STAGE(bufoff, gbase, voff) do { _Pragma("unroll") for (int _i = 0; _i < 2; ++_i) \
;         __builtin_amdgcn_global_load_lds((const unsigned*)((const char*)(gbase) + (voff)[_i]), (LAS unsigned*)(lds + (bufoff) + ldsw + _i * 8192), 16, 0, 0); } while (0)
; #define PG8_LDA(dst, b, h) do { _Pragma("unroll") for (int m = 0; m < 4; ++m) _Pragma("unroll") for (int k = 0; k < 2; ++k) dst[m][k] = *(const LAS bf16x8*)(lds + PG8_SA(b, h) + aoff + m * 2048 + k * 1024); } while (0)
; #define PG8_MMA(ai, bj, At, Bt) do { __builtin_amdgcn_s_setprio(1); _Pragma("unroll") for (int m = 0; m < 4; ++m) _Pragma("unroll") for (int n = 0; n < 2; ++n) _Pragma("unroll") for (int k = 0; k < 2; ++k) \
;         acc[ai][bj][m][n] = __builtin_amdgcn_mfma_f32_16x16x32_bf16(Bt[n][k], At[m][k], acc[ai][bj][m][n], 0, 0, 0); __builtin_amdgcn_s_setprio(0); } while (0)
; #define PG8_WAIT_V(n) asm volatile("s_waitcnt vmcnt(" #n ")" ::: "memory")
; #define PG8_WAIT_L(n) asm volatile("s_waitcnt lgkmcnt(" #n ")" ::: "memory")
; #define PG8_BAR __builtin_amdgcn_s_barrier()
; #define PG8_SCHED __builtin_amdgcn_sched_barrier(0)
; template <class Epi, class Sched, bool ALIGN_EPI = true>
; __device__ __forceinline__ void gemm_phase(LAS unsigned char* lds, const Gemm g, const Sched& S, const Epi& E) {
;     ...
;             PG8_LDA(At, 1, 1); PG8_STAGE(PG8_SB(1, 0), b3, voffB); PG8_STAGE(PG8_SB(1, 1), b3 + hstep, voffB); PG8_STAGE(PG8_SA(1, 0), a3, voffA);
;             PG8_WAIT_V(8); PG8_WAIT_L(0); PG8_BAR; PG8_MMA(1, 0, At, B0); PG8_MMA(1, 1, At, B1); PG8_BAR; PG8_SCHED;
;         }
;         if constexpr (ALIGN_EPI) { if (wr == 0) PG8_BAR; }
	s_add_i32 s22, s46, s35
	v_lshl_add_u64 v[180:181], v[180:181], 0, s[14:15]
	s_mov_b32 m0, s22
	ds_read_b128 v[172:175], v189 offset:49152
	ds_read_b128 v[176:179], v189 offset:50176
	ds_read_b128 v[192:195], v189 offset:51200
	ds_read_b128 v[196:199], v189 offset:52224
	ds_read_b128 v[204:207], v189 offset:53248
	ds_read_b128 v[208:211], v189 offset:54272
	ds_read_b128 v[212:215], v189 offset:55296
	ds_read_b128 v[216:219], v189 offset:56320
	global_load_lds_dwordx4 v[180:181], off
	s_add_i32 m0, s22, 0x2000
	s_add_u32 s22, s26, 0x160080
	v_lshl_add_u64 v[180:181], v[200:201], 0, s[14:15]
	s_addc_u32 s23, s27, 0
	s_add_i32 s26, s47, s35
	global_load_lds_dwordx4 v[180:181], off
	s_mov_b32 m0, s26
	v_lshl_add_u64 v[180:181], s[22:23], 0, v[154:155]
	global_load_lds_dwordx4 v[180:181], off
	s_add_i32 m0, s26, 0x2000
	v_lshl_add_u64 v[180:181], s[22:23], 0, v[158:159]
	global_load_lds_dwordx4 v[180:181], off
	s_mov_b32 m0, s40
	v_lshl_add_u64 v[180:181], v[202:203], 0, s[14:15]
	global_load_lds_dwordx4 v[180:181], off
	s_mov_b32 m0, s41
	v_lshl_add_u64 v[180:181], v[220:221], 0, s[14:15]
	global_load_lds_dwordx4 v[180:181], off
	s_waitcnt vmcnt(8)
	s_waitcnt lgkmcnt(0)
	s_barrier
	s_waitcnt lgkmcnt(0)
	v_mfma_f32_16x16x32_bf16 v[60:63], v[128:131], v[172:175], v[60:63]
	v_mfma_f32_16x16x32_bf16 v[56:59], v[136:139], v[172:175], v[56:59]
	v_mfma_f32_16x16x32_bf16 v[44:47], v[128:131], v[192:195], v[44:47]
	v_mfma_f32_16x16x32_bf16 v[40:43], v[136:139], v[192:195], v[40:43]
	v_mfma_f32_16x16x32_bf16 v[28:31], v[128:131], v[204:207], v[28:31]
	v_mfma_f32_16x16x32_bf16 v[24:27], v[136:139], v[204:207], v[24:27]
	v_mfma_f32_16x16x32_bf16 v[12:15], v[128:131], v[212:215], v[12:15]
	v_mfma_f32_16x16x32_bf16 v[8:11], v[136:139], v[212:215], v[8:11]
	v_mfma_f32_16x16x32_bf16 v[60:63], v[132:135], v[176:179], v[60:63]
	v_mfma_f32_16x16x32_bf16 v[56:59], v[140:143], v[176:179], v[56:59]
	v_mfma_f32_16x16x32_bf16 v[44:47], v[132:135], v[196:199], v[44:47]
	v_mfma_f32_16x16x32_bf16 v[40:43], v[140:143], v[196:199], v[40:43]
	v_mfma_f32_16x16x32_bf16 v[28:31], v[132:135], v[208:211], v[28:31]
	v_mfma_f32_16x16x32_bf16 v[24:27], v[140:143], v[208:211], v[24:27]
	v_mfma_f32_16x16x32_bf16 v[12:15], v[132:135], v[216:219], v[12:15]
	v_mfma_f32_16x16x32_bf16 v[8:11], v[140:143], v[216:219], v[8:11]
	v_mfma_f32_16x16x32_bf16 v[52:55], v[144:147], v[172:175], v[52:55]
	v_mfma_f32_16x16x32_bf16 v[48:51], v[164:167], v[172:175], v[48:51]
	v_mfma_f32_16x16x32_bf16 v[36:39], v[144:147], v[192:195], v[36:39]
	v_mfma_f32_16x16x32_bf16 v[32:35], v[164:167], v[192:195], v[32:35]
	v_mfma_f32_16x16x32_bf16 v[20:23], v[144:147], v[204:207], v[20:23]
	v_mfma_f32_16x16x32_bf16 v[16:19], v[164:167], v[204:207], v[16:19]
	v_mfma_f32_16x16x32_bf16 v[4:7], v[144:147], v[212:215], v[4:7]
	v_mfma_f32_16x16x32_bf16 v[0:3], v[164:167], v[212:215], v[0:3]
	v_mfma_f32_16x16x32_bf16 v[52:55], v[148:151], v[176:179], v[52:55]
	v_mfma_f32_16x16x32_bf16 v[48:51], v[168:171], v[176:179], v[48:51]
	v_mfma_f32_16x16x32_bf16 v[36:39], v[148:151], v[196:199], v[36:39]
	v_mfma_f32_16x16x32_bf16 v[32:35], v[168:171], v[196:199], v[32:35]
	v_mfma_f32_16x16x32_bf16 v[20:23], v[148:151], v[208:211], v[20:23]
	v_mfma_f32_16x16x32_bf16 v[16:19], v[168:171], v[208:211], v[16:19]
	v_mfma_f32_16x16x32_bf16 v[4:7], v[148:151], v[216:219], v[4:7]
	v_mfma_f32_16x16x32_bf16 v[0:3], v[168:171], v[216:219], v[0:3]
	s_barrier
	s_add_i32 s56, s56, 2
	s_add_u32 s54, s54, 0x100
	s_addc_u32 s55, s55, 0
	s_cmpk_gt_u32 s56, 0x55
	s_mov_b64 s[22:23], s[24:25]
	s_cbranch_scc0 .LBB0_746
	s_and_b64 vcc, exec, s[16:17]
	s_cbranch_vccz .LBB0_749
	s_barrier

; #define PG8_STAGE(bufoff, gbase, voff) do { _Pragma("unroll") for (int _i = 0; _i < 2; ++_i) \
;         __builtin_amdgcn_global_load_lds((const unsigned*)((const char*)(gbase) + (voff)[_i]), (LAS unsigned*)(lds + (bufoff) + ldsw + _i * 8192), 16, 0, 0); } while (0)
; #define PG8_LDA(dst, b, h) do { _Pragma("unroll") for (int m = 0; m < 4; ++m) _Pragma("unroll") for (int k = 0; k < 2; ++k) dst[m][k] = *(const LAS bf16x8*)(lds + PG8_SA(b, h) + aoff + m * 2048 + k * 1024); } while (0)
; #define PG8_LDB(dst, b, h) do { _Pragma("unroll") for (int n = 0; n < 2; ++n) _Pragma("unroll") for (int k = 0; k < 2; ++k) dst[n][k] = *(const LAS bf16x8*)(lds + PG8_SB(b, h) + boff + n * 2048 + k * 1024); } while (0)
; #define PG8_MMA(ai, bj, At, Bt) do { __builtin_amdgcn_s_setprio(1); _Pragma("unroll") for (int m = 0; m < 4; ++m) _Pragma("unroll") for (int n = 0; n < 2; ++n) _Pragma("unroll") for (int k = 0; k < 2; ++k) \
;         acc[ai][bj][m][n] = __builtin_amdgcn_mfma_f32_16x16x32_bf16(Bt[n][k], At[m][k], acc[ai][bj][m][n], 0, 0, 0); __builtin_amdgcn_s_setprio(0); } while (0)
; #define PG8_WAIT_V(n) asm volatile("s_waitcnt vmcnt(" #n ")" ::: "memory")
; #define PG8_WAIT_L(n) asm volatile("s_waitcnt lgkmcnt(" #n ")" ::: "memory")
; #define PG8_BAR __builtin_amdgcn_s_barrier()
; #define PG8_SCHED __builtin_amdgcn_sched_barrier(0)
; template <class Epi, class Sched, bool ALIGN_EPI = true>
; __device__ __forceinline__ void gemm_phase(LAS unsigned char* lds, const Gemm g, const Sched& S, const Epi& E) {
;     ...
;         for (int t = 0; t < nt; t += 2) {
;             const bool last = (t == nt - 2);
;             const char* a1 = cA + (size_t)(t + 1) * kstep;
;             const char* a2 = last ? nA : cA + (size_t)(t + 2) * kstep; const char* b2 = last ? nB : cB + (size_t)(t + 2) * kstep;
;             const char* a3 = a2 + kstep; const char* b3 = b2 + kstep;
;             PG8_LDB(B0, 0, 0); PG8_LDB(B1, 0, 1); PG8_SCHED; PG8_LDA(At, 0, 0); PG8_STAGE(PG8_SA(1, 1), a1 + hstep, voffA);
;             PG8_WAIT_V(8); PG8_WAIT_L(0); PG8_BAR; PG8_MMA(0, 0, At, B0); PG8_MMA(0, 1, At, B1); PG8_BAR; PG8_SCHED;
;             PG8_LDA(At, 0, 1); PG8_STAGE(PG8_SB(0, 0), b2, voffB); PG8_STAGE(PG8_SB(0, 1), b2 + hstep, voffB); PG8_STAGE(PG8_SA(0, 0), a2, voffA);
;             PG8_WAIT_V(8); PG8_WAIT_L(0); PG8_BAR; PG8_MMA(1, 0, At, B0); PG8_MMA(1, 1, At, B1); PG8_BAR; PG8_SCHED;
.LBB0_837:
	ds_read_b128 v[120:123], v208
	ds_read_b128 v[124:127], v208 offset:1024
	ds_read_b128 v[132:135], v208 offset:2048
	ds_read_b128 v[136:139], v208 offset:3072
	ds_read_b128 v[144:147], v209
	ds_read_b128 v[148:151], v209 offset:1024
	ds_read_b128 v[152:155], v209 offset:2048
	ds_read_b128 v[156:159], v209 offset:3072
	s_add_u32 s36, s34, 0xfff80080
	s_addc_u32 s37, s35, -1
	s_cmp_eq_u32 s60, 28
	s_cselect_b32 s39, s55, s37
	s_cselect_b32 s38, s56, s36
	s_cselect_b32 s37, s11, s59
	s_cselect_b32 s36, s57, s58
	v_lshl_add_u64 v[200:201], s[34:35], 0, v[184:185]
	s_add_i32 m0, s42, 0xc000
	ds_read_b128 v[160:163], v210
	ds_read_b128 v[164:167], v210 offset:1024
	ds_read_b128 v[168:171], v210 offset:2048
	ds_read_b128 v[172:175], v210 offset:3072
	ds_read_b128 v[188:191], v210 offset:4096
	ds_read_b128 v[192:195], v210 offset:5120
	ds_read_b128 v[196:199], v210 offset:6144
	ds_read_b128 v[214:217], v210 offset:7168
	global_load_lds_dwordx4 v[200:201], off
	s_add_i32 m0, s42, 0xe000
	v_lshl_add_u64 v[200:201], s[34:35], 0, v[186:187]
	global_load_lds_dwordx4 v[200:201], off
	s_waitcnt vmcnt(8)
	s_waitcnt lgkmcnt(0)
	s_barrier
	s_waitcnt lgkmcnt(0)
	v_mfma_f32_16x16x32_bf16 v[140:143], v[120:123], v[160:163], v[140:143]
	v_mfma_f32_16x16x32_bf16 v[128:131], v[132:135], v[160:163], v[128:131]
	v_mfma_f32_16x16x32_bf16 v[108:111], v[120:123], v[168:171], v[108:111]
	v_mfma_f32_16x16x32_bf16 v[104:107], v[132:135], v[168:171], v[104:107]
	v_mfma_f32_16x16x32_bf16 v[92:95], v[120:123], v[188:191], v[92:95]
	v_mfma_f32_16x16x32_bf16 v[88:91], v[132:135], v[188:191], v[88:91]
	v_mfma_f32_16x16x32_bf16 v[76:79], v[120:123], v[196:199], v[76:79]
	v_mfma_f32_16x16x32_bf16 v[72:75], v[132:135], v[196:199], v[72:75]
	v_mfma_f32_16x16x32_bf16 v[140:143], v[124:127], v[164:167], v[140:143]
	v_mfma_f32_16x16x32_bf16 v[128:131], v[136:139], v[164:167], v[128:131]
	v_mfma_f32_16x16x32_bf16 v[108:111], v[124:127], v[172:175], v[108:111]
	v_mfma_f32_16x16x32_bf16 v[104:107], v[136:139], v[172:175], v[104:107]
	v_mfma_f32_16x16x32_bf16 v[92:95], v[124:127], v[192:195], v[92:95]
	v_mfma_f32_16x16x32_bf16 v[88:91], v[136:139], v[192:195], v[88:91]
	v_mfma_f32_16x16x32_bf16 v[76:79], v[124:127], v[214:217], v[76:79]
	v_mfma_f32_16x16x32_bf16 v[72:75], v[136:139], v[214:217], v[72:75]
	v_mfma_f32_16x16x32_bf16 v[116:119], v[144:147], v[160:163], v[116:119]
	v_mfma_f32_16x16x32_bf16 v[112:115], v[152:155], v[160:163], v[112:115]
	v_mfma_f32_16x16x32_bf16 v[100:103], v[144:147], v[168:171], v[100:103]
	v_mfma_f32_16x16x32_bf16 v[96:99], v[152:155], v[168:171], v[96:99]
	v_mfma_f32_16x16x32_bf16 v[84:87], v[144:147], v[188:191], v[84:87]
	v_mfma_f32_16x16x32_bf16 v[80:83], v[152:155], v[188:191], v[80:83]
	v_mfma_f32_16x16x32_bf16 v[68:71], v[144:147], v[196:199], v[68:71]
	v_mfma_f32_16x16x32_bf16 v[64:67], v[152:155], v[196:199], v[64:67]
	v_mfma_f32_16x16x32_bf16 v[116:119], v[148:151], v[164:167], v[116:119]
	v_mfma_f32_16x16x32_bf16 v[112:115], v[156:159], v[164:167], v[112:115]
	v_mfma_f32_16x16x32_bf16 v[100:103], v[148:151], v[172:175], v[100:103]
	v_mfma_f32_16x16x32_bf16 v[96:99], v[156:159], v[172:175], v[96:99]
	v_mfma_f32_16x16x32_bf16 v[84:87], v[148:151], v[192:195], v[84:87]
	v_mfma_f32_16x16x32_bf16 v[80:83], v[156:159], v[192:195], v[80:83]
	v_mfma_f32_16x16x32_bf16 v[68:71], v[148:151], v[214:217], v[68:71]
	v_mfma_f32_16x16x32_bf16 v[64:67], v[156:159], v[214:217], v[64:67]
	s_barrier
	s_add_i32 s46, s50, s41
	v_lshl_add_u64 v[200:201], s[36:37], 0, v[178:179]
	s_mov_b32 m0, s46
	ds_read_b128 v[160:163], v210 offset:16384
	ds_read_b128 v[164:167], v210 offset:17408
	ds_read_b128 v[168:171], v210 offset:18432
	ds_read_b128 v[172:175], v210 offset:19456
	ds_read_b128 v[188:191], v210 offset:20480
	ds_read_b128 v[192:195], v210 offset:21504
	ds_read_b128 v[196:199], v210 offset:22528
	ds_read_b128 v[214:217], v210 offset:23552
	global_load_lds_dwordx4 v[200:201], off
	s_add_i32 m0, s46, 0x2000
	s_add_u32 s46, s36, 0x80000
	v_lshl_add_u64 v[218:219], s[36:37], 0, v[182:183]
	s_addc_u32 s47, s37, 0
	s_add_i32 s61, s51, s41
	global_load_lds_dwordx4 v[218:219], off
	v_lshl_add_u64 v[220:221], s[46:47], 0, v[178:179]
	s_mov_b32 m0, s61
	v_lshl_add_u64 v[222:223], s[38:39], 0, v[180:181]
	global_load_lds_dwordx4 v[220:221], off
	s_add_i32 m0, s61, 0x2000
	v_lshl_add_u64 v[220:221], s[46:47], 0, v[182:183]
	global_load_lds_dwordx4 v[220:221], off
	s_mov_b32 m0, s42
	v_lshl_add_u64 v[220:221], s[38:39], 0, v[176:177]
	global_load_lds_dwordx4 v[220:221], off
	s_mov_b32 m0, s43
	s_nop 0
	global_load_lds_dwordx4 v[222:223], off
	s_waitcnt vmcnt(8)
	s_waitcnt lgkmcnt(0)
	s_barrier
; #define PG8_STAGE(bufoff, gbase, voff) do { _Pragma("unroll") for (int _i = 0; _i < 2; ++_i) \
;         __builtin_amdgcn_global_load_lds((const unsigned*)((const char*)(gbase) + (voff)[_i]), (LAS unsigned*)(lds + (bufoff) + ldsw + _i * 8192), 16, 0, 0); } while (0)
; #define PG8_LDA(dst, b, h) do { _Pragma("unroll") for (int m = 0; m < 4; ++m) _Pragma("unroll") for (int k = 0; k < 2; ++k) dst[m][k] = *(const LAS bf16x8*)(lds + PG8_SA(b, h) + aoff + m * 2048 + k * 1024); } while (0)
; #define PG8_LDB(dst, b, h) do { _Pragma("unroll") for (int n = 0; n < 2; ++n) _Pragma("unroll") for (int k = 0; k < 2; ++k) dst[n][k] = *(const LAS bf16x8*)(lds + PG8_SB(b, h) + boff + n * 2048 + k * 1024); } while (0)
; #define PG8_MMA(ai, bj, At, Bt) do { __builtin_amdgcn_s_setprio(1); _Pragma("unroll") for (int m = 0; m < 4; ++m) _Pragma("unroll") for (int n = 0; n < 2; ++n) _Pragma("unroll") for (int k = 0; k < 2; ++k) \
;         acc[ai][bj][m][n] = __builtin_amdgcn_mfma_f32_16x16x32_bf16(Bt[n][k], At[m][k], acc[ai][bj][m][n], 0, 0, 0); __builtin_amdgcn_s_setprio(0); } while (0)
; #define PG8_WAIT_V(n) asm volatile("s_waitcnt vmcnt(" #n ")" ::: "memory")
; #define PG8_WAIT_L(n) asm volatile("s_waitcnt lgkmcnt(" #n ")" ::: "memory")
; #define PG8_BAR __builtin_amdgcn_s_barrier()
; #define PG8_SCHED __builtin_amdgcn_sched_barrier(0)
; template <class Epi, class Sched, bool ALIGN_EPI = true>
; __device__ __forceinline__ void gemm_phase(LAS unsigned char* lds, const Gemm g, const Sched& S, const Epi& E) {
;     ...
;             PG8_WAIT_V(8); PG8_WAIT_L(0); PG8_BAR; PG8_MMA(1, 0, At, B0); PG8_MMA(1, 1, At, B1); PG8_BAR; PG8_SCHED;
;             PG8_LDB(B0, 1, 0); PG8_LDB(B1, 1, 1); PG8_SCHED; PG8_LDA(At, 1, 0); PG8_STAGE(PG8_SA(0, 1), a2 + hstep, voffA);
;             PG8_WAIT_V(8); PG8_WAIT_L(0); PG8_BAR; PG8_MMA(0, 0, At, B0); PG8_MMA(0, 1, At, B1); PG8_BAR; PG8_SCHED;
	s_waitcnt lgkmcnt(0)
	v_mfma_f32_16x16x32_bf16 v[60:63], v[120:123], v[160:163], v[60:63]
	v_mfma_f32_16x16x32_bf16 v[56:59], v[132:135], v[160:163], v[56:59]
	v_mfma_f32_16x16x32_bf16 v[44:47], v[120:123], v[168:171], v[44:47]
	v_mfma_f32_16x16x32_bf16 v[40:43], v[132:135], v[168:171], v[40:43]
	v_mfma_f32_16x16x32_bf16 v[28:31], v[120:123], v[188:191], v[28:31]
	v_mfma_f32_16x16x32_bf16 v[24:27], v[132:135], v[188:191], v[24:27]
	v_mfma_f32_16x16x32_bf16 v[12:15], v[120:123], v[196:199], v[12:15]
	v_mfma_f32_16x16x32_bf16 v[8:11], v[132:135], v[196:199], v[8:11]
	v_mfma_f32_16x16x32_bf16 v[60:63], v[124:127], v[164:167], v[60:63]
	v_mfma_f32_16x16x32_bf16 v[56:59], v[136:139], v[164:167], v[56:59]
	v_mfma_f32_16x16x32_bf16 v[44:47], v[124:127], v[172:175], v[44:47]
	v_mfma_f32_16x16x32_bf16 v[40:43], v[136:139], v[172:175], v[40:43]
	v_mfma_f32_16x16x32_bf16 v[28:31], v[124:127], v[192:195], v[28:31]
	v_mfma_f32_16x16x32_bf16 v[24:27], v[136:139], v[192:195], v[24:27]
	v_mfma_f32_16x16x32_bf16 v[12:15], v[124:127], v[214:217], v[12:15]
	v_mfma_f32_16x16x32_bf16 v[8:11], v[136:139], v[214:217], v[8:11]
	v_mfma_f32_16x16x32_bf16 v[52:55], v[144:147], v[160:163], v[52:55]
	v_mfma_f32_16x16x32_bf16 v[48:51], v[152:155], v[160:163], v[48:51]
	v_mfma_f32_16x16x32_bf16 v[36:39], v[144:147], v[168:171], v[36:39]
	v_mfma_f32_16x16x32_bf16 v[32:35], v[152:155], v[168:171], v[32:35]
	v_mfma_f32_16x16x32_bf16 v[20:23], v[144:147], v[188:191], v[20:23]
	v_mfma_f32_16x16x32_bf16 v[16:19], v[152:155], v[188:191], v[16:19]
	v_mfma_f32_16x16x32_bf16 v[4:7], v[144:147], v[196:199], v[4:7]
	v_mfma_f32_16x16x32_bf16 v[0:3], v[152:155], v[196:199], v[0:3]
	v_mfma_f32_16x16x32_bf16 v[52:55], v[148:151], v[164:167], v[52:55]
	v_mfma_f32_16x16x32_bf16 v[48:51], v[156:159], v[164:167], v[48:51]
	v_mfma_f32_16x16x32_bf16 v[36:39], v[148:151], v[172:175], v[36:39]
	v_mfma_f32_16x16x32_bf16 v[32:35], v[156:159], v[172:175], v[32:35]
	v_mfma_f32_16x16x32_bf16 v[20:23], v[148:151], v[192:195], v[20:23]
	v_mfma_f32_16x16x32_bf16 v[16:19], v[156:159], v[192:195], v[16:19]
	v_mfma_f32_16x16x32_bf16 v[4:7], v[148:151], v[214:217], v[4:7]
	v_mfma_f32_16x16x32_bf16 v[0:3], v[156:159], v[214:217], v[0:3]
	s_barrier
	s_add_i32 s46, 0, 0x18000
	s_add_i32 s47, 0, 0x1c000
	v_add_u32_e32 v136, s46, v206
	v_add_u32_e32 v156, s47, v206
	ds_read_b128 v[120:123], v136
	ds_read_b128 v[124:127], v136 offset:1024
	ds_read_b128 v[132:135], v136 offset:2048
	ds_read_b128 v[136:139], v136 offset:3072
	ds_read_b128 v[144:147], v156
	ds_read_b128 v[148:151], v156 offset:1024
	ds_read_b128 v[152:155], v156 offset:2048
	ds_read_b128 v[156:159], v156 offset:3072
	s_add_u32 s38, s38, 0x80000
	s_addc_u32 s39, s39, 0
	s_mov_b32 m0, s44
	v_lshl_add_u64 v[224:225], s[38:39], 0, v[176:177]
	ds_read_b128 v[160:163], v210 offset:32768
	ds_read_b128 v[164:167], v210 offset:33792
	ds_read_b128 v[168:171], v210 offset:34816
	ds_read_b128 v[172:175], v210 offset:35840
	ds_read_b128 v[188:191], v210 offset:36864
	ds_read_b128 v[192:195], v210 offset:37888
	ds_read_b128 v[196:199], v210 offset:38912
	ds_read_b128 v[214:217], v210 offset:39936
	global_load_lds_dwordx4 v[224:225], off
	s_mov_b32 m0, s45
	v_lshl_add_u64 v[224:225], s[38:39], 0, v[180:181]
	global_load_lds_dwordx4 v[224:225], off
	s_waitcnt vmcnt(8)
	s_waitcnt lgkmcnt(0)
	s_barrier
	s_waitcnt lgkmcnt(0)
	v_mfma_f32_16x16x32_bf16 v[140:143], v[120:123], v[160:163], v[140:143]
	v_mfma_f32_16x16x32_bf16 v[128:131], v[132:135], v[160:163], v[128:131]
	v_mfma_f32_16x16x32_bf16 v[108:111], v[120:123], v[168:171], v[108:111]
	v_mfma_f32_16x16x32_bf16 v[104:107], v[132:135], v[168:171], v[104:107]
	v_mfma_f32_16x16x32_bf16 v[92:95], v[120:123], v[188:191], v[92:95]
	v_mfma_f32_16x16x32_bf16 v[88:91], v[132:135], v[188:191], v[88:91]
	v_mfma_f32_16x16x32_bf16 v[76:79], v[120:123], v[196:199], v[76:79]
	v_mfma_f32_16x16x32_bf16 v[72:75], v[132:135], v[196:199], v[72:75]
	v_mfma_f32_16x16x32_bf16 v[140:143], v[124:127], v[164:167], v[140:143]
	v_mfma_f32_16x16x32_bf16 v[128:131], v[136:139], v[164:167], v[128:131]
	v_mfma_f32_16x16x32_bf16 v[108:111], v[124:127], v[172:175], v[108:111]
	v_mfma_f32_16x16x32_bf16 v[104:107], v[136:139], v[172:175], v[104:107]
	v_mfma_f32_16x16x32_bf16 v[92:95], v[124:127], v[192:195], v[92:95]
	v_mfma_f32_16x16x32_bf16 v[88:91], v[136:139], v[192:195], v[88:91]
	v_mfma_f32_16x16x32_bf16 v[76:79], v[124:127], v[214:217], v[76:79]
	v_mfma_f32_16x16x32_bf16 v[72:75], v[136:139], v[214:217], v[72:75]
	v_mfma_f32_16x16x32_bf16 v[116:119], v[144:147], v[160:163], v[116:119]
	v_mfma_f32_16x16x32_bf16 v[112:115], v[152:155], v[160:163], v[112:115]
	v_mfma_f32_16x16x32_bf16 v[100:103], v[144:147], v[168:171], v[100:103]
	v_mfma_f32_16x16x32_bf16 v[96:99], v[152:155], v[168:171], v[96:99]
	v_mfma_f32_16x16x32_bf16 v[84:87], v[144:147], v[188:191], v[84:87]
	v_mfma_f32_16x16x32_bf16 v[80:83], v[152:155], v[188:191], v[80:83]
	v_mfma_f32_16x16x32_bf16 v[68:71], v[144:147], v[196:199], v[68:71]
	v_mfma_f32_16x16x32_bf16 v[64:67], v[152:155], v[196:199], v[64:67]
	v_mfma_f32_16x16x32_bf16 v[116:119], v[148:151], v[164:167], v[116:119]
	v_mfma_f32_16x16x32_bf16 v[112:115], v[156:159], v[164:167], v[112:115]
	v_mfma_f32_16x16x32_bf16 v[100:103], v[148:151], v[172:175], v[100:103]
	v_mfma_f32_16x16x32_bf16 v[96:99], v[156:159], v[172:175], v[96:99]
	v_mfma_f32_16x16x32_bf16 v[84:87], v[148:151], v[192:195], v[84:87]
	v_mfma_f32_16x16x32_bf16 v[80:83], v[156:159], v[192:195], v[80:83]
	v_mfma_f32_16x16x32_bf16 v[68:71], v[148:151], v[214:217], v[68:71]
	v_mfma_f32_16x16x32_bf16 v[64:67], v[156:159], v[214:217], v[64:67]
	s_barrier
; #define PG8_STAGE(bufoff, gbase, voff) do { _Pragma("unroll") for (int _i = 0; _i < 2; ++_i) \
;         __builtin_amdgcn_global_load_lds((const unsigned*)((const char*)(gbase) + (voff)[_i]), (LAS unsigned*)(lds + (bufoff) + ldsw + _i * 8192), 16, 0, 0); } while (0)
; #define PG8_LDA(dst, b, h) do { _Pragma("unroll") for (int m = 0; m < 4; ++m) _Pragma("unroll") for (int k = 0; k < 2; ++k) dst[m][k] = *(const LAS bf16x8*)(lds + PG8_SA(b, h) + aoff + m * 2048 + k * 1024); } while (0)
; #define PG8_MMA(ai, bj, At, Bt) do { __builtin_amdgcn_s_setprio(1); _Pragma("unroll") for (int m = 0; m < 4; ++m) _Pragma("unroll") for (int n = 0; n < 2; ++n) _Pragma("unroll") for (int k = 0; k < 2; ++k) \
;         acc[ai][bj][m][n] = __builtin_amdgcn_mfma_f32_16x16x32_bf16(Bt[n][k], At[m][k], acc[ai][bj][m][n], 0, 0, 0); __builtin_amdgcn_s_setprio(0); } while (0)
; #define PG8_WAIT_V(n) asm volatile("s_waitcnt vmcnt(" #n ")" ::: "memory")
; #define PG8_WAIT_L(n) asm volatile("s_waitcnt lgkmcnt(" #n ")" ::: "memory")
; #define PG8_BAR __builtin_amdgcn_s_barrier()
; #define PG8_SCHED __builtin_amdgcn_sched_barrier(0)
; template <class Epi, class Sched, bool ALIGN_EPI = true>
; __device__ __forceinline__ void gemm_phase(LAS unsigned char* lds, const Gemm g, const Sched& S, const Epi& E) {
;     ...
;             PG8_LDA(At, 1, 1); PG8_STAGE(PG8_SB(1, 0), b3, voffB); PG8_STAGE(PG8_SB(1, 1), b3 + hstep, voffB); PG8_STAGE(PG8_SA(1, 0), a3, voffA);
;             PG8_WAIT_V(8); PG8_WAIT_L(0); PG8_BAR; PG8_MMA(1, 0, At, B0); PG8_MMA(1, 1, At, B1); PG8_BAR; PG8_SCHED;
;         }
	s_add_i32 s38, s46, s41
	v_lshl_add_u64 v[200:201], v[200:201], 0, s[26:27]
	s_mov_b32 m0, s38
	ds_read_b128 v[160:163], v210 offset:49152
	ds_read_b128 v[164:167], v210 offset:50176
	ds_read_b128 v[168:171], v210 offset:51200
	ds_read_b128 v[172:175], v210 offset:52224
	ds_read_b128 v[188:191], v210 offset:53248
	ds_read_b128 v[192:195], v210 offset:54272
	ds_read_b128 v[196:199], v210 offset:55296
	ds_read_b128 v[214:217], v210 offset:56320
	global_load_lds_dwordx4 v[200:201], off
	s_add_i32 m0, s38, 0x2000
	s_add_u32 s36, s36, 0x80080
	v_lshl_add_u64 v[200:201], v[218:219], 0, s[26:27]
	s_addc_u32 s37, s37, 0
	s_add_i32 s38, s47, s41
	global_load_lds_dwordx4 v[200:201], off
	s_mov_b32 m0, s38
	v_lshl_add_u64 v[200:201], s[36:37], 0, v[178:179]
	global_load_lds_dwordx4 v[200:201], off
	s_add_i32 m0, s38, 0x2000
	v_lshl_add_u64 v[200:201], s[36:37], 0, v[182:183]
	global_load_lds_dwordx4 v[200:201], off
	s_mov_b32 m0, s48
	v_lshl_add_u64 v[200:201], v[220:221], 0, s[26:27]
	global_load_lds_dwordx4 v[200:201], off
	s_mov_b32 m0, s49
	v_lshl_add_u64 v[200:201], v[222:223], 0, s[26:27]
	global_load_lds_dwordx4 v[200:201], off
	s_waitcnt vmcnt(8)
	s_waitcnt lgkmcnt(0)
	s_barrier
	s_waitcnt lgkmcnt(0)
	v_mfma_f32_16x16x32_bf16 v[60:63], v[120:123], v[160:163], v[60:63]
	v_mfma_f32_16x16x32_bf16 v[56:59], v[132:135], v[160:163], v[56:59]
	v_mfma_f32_16x16x32_bf16 v[44:47], v[120:123], v[168:171], v[44:47]
	v_mfma_f32_16x16x32_bf16 v[40:43], v[132:135], v[168:171], v[40:43]
	v_mfma_f32_16x16x32_bf16 v[28:31], v[120:123], v[188:191], v[28:31]
	v_mfma_f32_16x16x32_bf16 v[24:27], v[132:135], v[188:191], v[24:27]
	v_mfma_f32_16x16x32_bf16 v[12:15], v[120:123], v[196:199], v[12:15]
	v_mfma_f32_16x16x32_bf16 v[8:11], v[132:135], v[196:199], v[8:11]
	v_mfma_f32_16x16x32_bf16 v[60:63], v[124:127], v[164:167], v[60:63]
	v_mfma_f32_16x16x32_bf16 v[56:59], v[136:139], v[164:167], v[56:59]
	v_mfma_f32_16x16x32_bf16 v[44:47], v[124:127], v[172:175], v[44:47]
	v_mfma_f32_16x16x32_bf16 v[40:43], v[136:139], v[172:175], v[40:43]
	v_mfma_f32_16x16x32_bf16 v[28:31], v[124:127], v[192:195], v[28:31]
	v_mfma_f32_16x16x32_bf16 v[24:27], v[136:139], v[192:195], v[24:27]
	v_mfma_f32_16x16x32_bf16 v[12:15], v[124:127], v[214:217], v[12:15]
	v_mfma_f32_16x16x32_bf16 v[8:11], v[136:139], v[214:217], v[8:11]
	v_mfma_f32_16x16x32_bf16 v[52:55], v[144:147], v[160:163], v[52:55]
	v_mfma_f32_16x16x32_bf16 v[48:51], v[152:155], v[160:163], v[48:51]
	v_mfma_f32_16x16x32_bf16 v[36:39], v[144:147], v[168:171], v[36:39]
	v_mfma_f32_16x16x32_bf16 v[32:35], v[152:155], v[168:171], v[32:35]
	v_mfma_f32_16x16x32_bf16 v[20:23], v[144:147], v[188:191], v[20:23]
	v_mfma_f32_16x16x32_bf16 v[16:19], v[152:155], v[188:191], v[16:19]
	v_mfma_f32_16x16x32_bf16 v[4:7], v[144:147], v[196:199], v[4:7]
	v_mfma_f32_16x16x32_bf16 v[0:3], v[152:155], v[196:199], v[0:3]
	v_mfma_f32_16x16x32_bf16 v[52:55], v[148:151], v[164:167], v[52:55]
	v_mfma_f32_16x16x32_bf16 v[48:51], v[156:159], v[164:167], v[48:51]
	v_mfma_f32_16x16x32_bf16 v[36:39], v[148:151], v[172:175], v[36:39]
	v_mfma_f32_16x16x32_bf16 v[32:35], v[156:159], v[172:175], v[32:35]
	v_mfma_f32_16x16x32_bf16 v[20:23], v[148:151], v[192:195], v[20:23]
	v_mfma_f32_16x16x32_bf16 v[16:19], v[156:159], v[192:195], v[16:19]
	v_mfma_f32_16x16x32_bf16 v[4:7], v[148:151], v[214:217], v[4:7]
	v_mfma_f32_16x16x32_bf16 v[0:3], v[156:159], v[214:217], v[0:3]
	s_barrier
	s_add_i32 s60, s60, 2
	s_add_u32 s34, s34, 0x100
	s_addc_u32 s35, s35, 0
	s_add_u32 s58, s58, 0x100
	s_addc_u32 s59, s59, 0
	s_cmp_gt_u32 s60, 29
	s_cbranch_scc0 .LBB0_837
	s_and_b64 vcc, exec, s[28:29]
	s_cbranch_vccz .LBB0_840
	s_barrier
